# GEMM K-loops: loop-back SALU rotated into the last MFMA block; in each load segment the ds_reads are issued first, address/m0 prep after
# speedup vs baseline: 1.0063x; 1.0014x over previous
; #define PG8_STAGE(bufoff, gbase, voff) do { _Pragma("unroll") for (int _i = 0; _i < 2; ++_i) \
;         __builtin_amdgcn_global_load_lds((const unsigned*)((const char*)(gbase) + (voff)[_i]), (PG8_LAS unsigned*)(lds + (bufoff) + ldsw + _i * 8192), 16, 0, 0); } while (0)
; #define PG8_LDA(dst, b, h) do { _Pragma("unroll") for (int m = 0; m < 4; ++m) _Pragma("unroll") for (int k = 0; k < 2; ++k) dst[m][k] = *(const PG8_LAS bf16x8*)(lds + PG8_SA(b, h) + aoff + m * 2048 + k * 1024); } while (0)
; #define PG8_LDB(dst, b, h) do { _Pragma("unroll") for (int n = 0; n < 2; ++n) _Pragma("unroll") for (int k = 0; k < 2; ++k) dst[n][k] = *(const PG8_LAS bf16x8*)(lds + PG8_SB(b, h) + boff + n * 2048 + k * 1024); } while (0)
; #define PG8_MMA(ai, bj, At, Bt) do { __builtin_amdgcn_s_setprio(1); _Pragma("unroll") for (int m = 0; m < 4; ++m) _Pragma("unroll") for (int n = 0; n < 2; ++n) _Pragma("unroll") for (int k = 0; k < 2; ++k) \
;         acc[ai][bj][m][n] = __builtin_amdgcn_mfma_f32_16x16x32_bf16(Bt[n][k], At[m][k], acc[ai][bj][m][n], 0, 0, 0); __builtin_amdgcn_s_setprio(0); } while (0)
; #define PG8_WAIT_V(n) asm volatile("s_waitcnt vmcnt(" #n ")" ::: "memory")
; #define PG8_WAIT_L(n) asm volatile("s_waitcnt lgkmcnt(" #n ")" ::: "memory")
; #define PG8_BAR __builtin_amdgcn_s_barrier()
; #define PG8_SCHED __builtin_amdgcn_sched_barrier(0)
; template <class Epi, class Sched, bool ALIGN_EPI = false, bool SP2 = false>
; __device__ __forceinline__ void gemm_phase(PG8_LAS unsigned char* lds, const Gemm g, const Sched& S, const Epi& E, const int wid) {
;     ...
;             PG8_LDB(B0, 0, 0); PG8_LDB(B1, 0, 1); PG8_SCHED; PG8_LDA(At, 0, 0); PG8_STAGE(PG8_SA(1, 1), a1 + hstep, voffA);
;             PG8_WAIT_V(8); PG8_WAIT_L(0); PG8_BAR; PG8_MMA(0, 0, At, B0); PG8_MMA(0, 1, At, B1); PG8_BAR; PG8_SCHED;
;             PG8_LDA(At, 0, 1); PG8_STAGE(PG8_SB(0, 0), b2, voffB); PG8_STAGE(PG8_SB(0, 1), b2 + hstep, voffB); PG8_STAGE(PG8_SA(0, 0), a2, voffA);
;             PG8_WAIT_V(8); PG8_WAIT_L(0); PG8_BAR; PG8_MMA(1, 0, At, B0); PG8_MMA(1, 1, At, B1); PG8_BAR; PG8_SCHED;
.LBB0_277:
	ds_read_b128 v[128:131], v163
	ds_read_b128 v[132:135], v163 offset:1024
	ds_read_b128 v[136:139], v163 offset:2048
	ds_read_b128 v[140:143], v163 offset:3072
	ds_read_b128 v[168:171], v165
	ds_read_b128 v[172:175], v165 offset:1024
	ds_read_b128 v[176:179], v165 offset:2048
	ds_read_b128 v[180:183], v165 offset:3072
	ds_read_b128 v[184:187], v167
	ds_read_b128 v[188:191], v167 offset:1024
	ds_read_b128 v[192:195], v167 offset:2048
	ds_read_b128 v[196:199], v167 offset:3072
	ds_read_b128 v[200:203], v167 offset:4096
	ds_read_b128 v[204:207], v167 offset:5120
	ds_read_b128 v[208:211], v167 offset:6144
	ds_read_b128 v[212:215], v167 offset:7168
	s_nop 0
	s_add_u32 s62, s60, 0xfff00080
	s_addc_u32 s63, s61, -1
	s_cmp_eq_u32 s70, 60
	s_cselect_b32 s67, s53, s63
	s_cselect_b32 s66, s59, s62
	s_cselect_b32 s63, s51, s69
	s_cselect_b32 s62, s65, s68
	v_lshl_add_u64 v[216:217], s[60:61], 0, v[152:153]
	s_add_i32 m0, s76, 0xc000
	s_nop 0
	global_load_lds_dwordx4 v[216:217], off
	v_lshl_add_u64 v[216:217], s[60:61], 0, v[154:155]
	s_add_i32 m0, s76, 0xe000
	s_nop 0
	global_load_lds_dwordx4 v[216:217], off
	s_waitcnt vmcnt(8)
	s_waitcnt lgkmcnt(0)
	s_barrier
	s_setprio 1
	s_waitcnt lgkmcnt(0)
	v_mfma_f32_16x16x32_bf16 v[124:127], v[128:131], v[184:187], v[124:127]
	v_mfma_f32_16x16x32_bf16 v[120:123], v[136:139], v[184:187], v[120:123]
	v_mfma_f32_16x16x32_bf16 v[108:111], v[128:131], v[192:195], v[108:111]
	v_mfma_f32_16x16x32_bf16 v[104:107], v[136:139], v[192:195], v[104:107]
	v_mfma_f32_16x16x32_bf16 v[92:95], v[128:131], v[200:203], v[92:95]
	v_mfma_f32_16x16x32_bf16 v[88:91], v[136:139], v[200:203], v[88:91]
	v_mfma_f32_16x16x32_bf16 v[76:79], v[128:131], v[208:211], v[76:79]
	v_mfma_f32_16x16x32_bf16 v[72:75], v[136:139], v[208:211], v[72:75]
	v_mfma_f32_16x16x32_bf16 v[124:127], v[132:135], v[188:191], v[124:127]
	v_mfma_f32_16x16x32_bf16 v[120:123], v[140:143], v[188:191], v[120:123]
	v_mfma_f32_16x16x32_bf16 v[108:111], v[132:135], v[196:199], v[108:111]
	v_mfma_f32_16x16x32_bf16 v[104:107], v[140:143], v[196:199], v[104:107]
	v_mfma_f32_16x16x32_bf16 v[92:95], v[132:135], v[204:207], v[92:95]
	v_mfma_f32_16x16x32_bf16 v[88:91], v[140:143], v[204:207], v[88:91]
	v_mfma_f32_16x16x32_bf16 v[76:79], v[132:135], v[212:215], v[76:79]
	v_mfma_f32_16x16x32_bf16 v[72:75], v[140:143], v[212:215], v[72:75]
	s_setprio 0
	s_setprio 1
	v_mfma_f32_16x16x32_bf16 v[116:119], v[168:171], v[184:187], v[116:119]
	v_mfma_f32_16x16x32_bf16 v[112:115], v[176:179], v[184:187], v[112:115]
	v_mfma_f32_16x16x32_bf16 v[100:103], v[168:171], v[192:195], v[100:103]
	v_mfma_f32_16x16x32_bf16 v[96:99], v[176:179], v[192:195], v[96:99]
	v_mfma_f32_16x16x32_bf16 v[84:87], v[168:171], v[200:203], v[84:87]
	v_mfma_f32_16x16x32_bf16 v[80:83], v[176:179], v[200:203], v[80:83]
	v_mfma_f32_16x16x32_bf16 v[68:71], v[168:171], v[208:211], v[68:71]
	v_mfma_f32_16x16x32_bf16 v[64:67], v[176:179], v[208:211], v[64:67]
	v_mfma_f32_16x16x32_bf16 v[116:119], v[172:175], v[188:191], v[116:119]
	v_mfma_f32_16x16x32_bf16 v[112:115], v[180:183], v[188:191], v[112:115]
	v_mfma_f32_16x16x32_bf16 v[100:103], v[172:175], v[196:199], v[100:103]
	v_mfma_f32_16x16x32_bf16 v[96:99], v[180:183], v[196:199], v[96:99]
	v_mfma_f32_16x16x32_bf16 v[84:87], v[172:175], v[204:207], v[84:87]
	v_mfma_f32_16x16x32_bf16 v[80:83], v[180:183], v[204:207], v[80:83]
	v_mfma_f32_16x16x32_bf16 v[68:71], v[172:175], v[212:215], v[68:71]
	v_mfma_f32_16x16x32_bf16 v[64:67], v[180:183], v[212:215], v[64:67]
	s_setprio 0
	s_barrier
	ds_read_b128 v[184:187], v167 offset:16384
	ds_read_b128 v[188:191], v167 offset:17408
	ds_read_b128 v[192:195], v167 offset:18432
	ds_read_b128 v[196:199], v167 offset:19456
	ds_read_b128 v[200:203], v167 offset:20480
	ds_read_b128 v[204:207], v167 offset:21504
	ds_read_b128 v[208:211], v167 offset:22528
	ds_read_b128 v[212:215], v167 offset:23552
	s_add_i32 s71, s89, s75
	v_lshl_add_u64 v[216:217], s[62:63], 0, v[146:147]
	s_mov_b32 m0, s71
	s_nop 0
	global_load_lds_dwordx4 v[216:217], off
	s_add_i32 m0, s71, 0x2000
	s_add_u32 s72, s62, 0x100000
	v_lshl_add_u64 v[218:219], s[62:63], 0, v[150:151]
	s_addc_u32 s73, s63, 0
	s_add_i32 s71, s90, s75
	global_load_lds_dwordx4 v[218:219], off
	v_lshl_add_u64 v[220:221], s[72:73], 0, v[146:147]
	s_mov_b32 m0, s71
	v_lshl_add_u64 v[222:223], s[66:67], 0, v[148:149]
	global_load_lds_dwordx4 v[220:221], off
	v_lshl_add_u64 v[220:221], s[72:73], 0, v[150:151]
	s_add_i32 m0, s71, 0x2000
	s_nop 0
	global_load_lds_dwordx4 v[220:221], off
	v_lshl_add_u64 v[220:221], s[66:67], 0, v[144:145]
	s_mov_b32 m0, s76
	s_nop 0
	global_load_lds_dwordx4 v[220:221], off
	s_mov_b32 m0, s77
	s_nop 0
	global_load_lds_dwordx4 v[222:223], off
	s_waitcnt vmcnt(8)
	s_waitcnt lgkmcnt(0)
	s_barrier
; #define PG8_STAGE(bufoff, gbase, voff) do { _Pragma("unroll") for (int _i = 0; _i < 2; ++_i) \
;         __builtin_amdgcn_global_load_lds((const unsigned*)((const char*)(gbase) + (voff)[_i]), (PG8_LAS unsigned*)(lds + (bufoff) + ldsw + _i * 8192), 16, 0, 0); } while (0)
; #define PG8_LDA(dst, b, h) do { _Pragma("unroll") for (int m = 0; m < 4; ++m) _Pragma("unroll") for (int k = 0; k < 2; ++k) dst[m][k] = *(const PG8_LAS bf16x8*)(lds + PG8_SA(b, h) + aoff + m * 2048 + k * 1024); } while (0)
; #define PG8_LDB(dst, b, h) do { _Pragma("unroll") for (int n = 0; n < 2; ++n) _Pragma("unroll") for (int k = 0; k < 2; ++k) dst[n][k] = *(const PG8_LAS bf16x8*)(lds + PG8_SB(b, h) + boff + n * 2048 + k * 1024); } while (0)
; #define PG8_MMA(ai, bj, At, Bt) do { __builtin_amdgcn_s_setprio(1); _Pragma("unroll") for (int m = 0; m < 4; ++m) _Pragma("unroll") for (int n = 0; n < 2; ++n) _Pragma("unroll") for (int k = 0; k < 2; ++k) \
;         acc[ai][bj][m][n] = __builtin_amdgcn_mfma_f32_16x16x32_bf16(Bt[n][k], At[m][k], acc[ai][bj][m][n], 0, 0, 0); __builtin_amdgcn_s_setprio(0); } while (0)
; #define PG8_WAIT_V(n) asm volatile("s_waitcnt vmcnt(" #n ")" ::: "memory")
; #define PG8_WAIT_L(n) asm volatile("s_waitcnt lgkmcnt(" #n ")" ::: "memory")
; #define PG8_BAR __builtin_amdgcn_s_barrier()
; #define PG8_SCHED __builtin_amdgcn_sched_barrier(0)
; template <class Epi, class Sched, bool ALIGN_EPI = false, bool SP2 = false>
; __device__ __forceinline__ void gemm_phase(PG8_LAS unsigned char* lds, const Gemm g, const Sched& S, const Epi& E, const int wid) {
;     ...
;             PG8_WAIT_V(8); PG8_WAIT_L(0); PG8_BAR; PG8_MMA(1, 0, At, B0); PG8_MMA(1, 1, At, B1); PG8_BAR; PG8_SCHED;
;             PG8_LDB(B0, 1, 0); PG8_LDB(B1, 1, 1); PG8_SCHED; PG8_LDA(At, 1, 0); PG8_STAGE(PG8_SA(0, 1), a2 + hstep, voffA);
;             PG8_WAIT_V(8); PG8_WAIT_L(0); PG8_BAR; PG8_MMA(0, 0, At, B0); PG8_MMA(0, 1, At, B1); PG8_BAR; PG8_SCHED;
	s_setprio 1
	s_waitcnt lgkmcnt(0)
	v_mfma_f32_16x16x32_bf16 v[60:63], v[128:131], v[184:187], v[60:63]
	v_mfma_f32_16x16x32_bf16 v[56:59], v[136:139], v[184:187], v[56:59]
	v_mfma_f32_16x16x32_bf16 v[44:47], v[128:131], v[192:195], v[44:47]
	v_mfma_f32_16x16x32_bf16 v[40:43], v[136:139], v[192:195], v[40:43]
	v_mfma_f32_16x16x32_bf16 v[28:31], v[128:131], v[200:203], v[28:31]
	v_mfma_f32_16x16x32_bf16 v[24:27], v[136:139], v[200:203], v[24:27]
	v_mfma_f32_16x16x32_bf16 v[12:15], v[128:131], v[208:211], v[12:15]
	v_mfma_f32_16x16x32_bf16 v[8:11], v[136:139], v[208:211], v[8:11]
	v_mfma_f32_16x16x32_bf16 v[60:63], v[132:135], v[188:191], v[60:63]
	v_mfma_f32_16x16x32_bf16 v[56:59], v[140:143], v[188:191], v[56:59]
	v_mfma_f32_16x16x32_bf16 v[44:47], v[132:135], v[196:199], v[44:47]
	v_mfma_f32_16x16x32_bf16 v[40:43], v[140:143], v[196:199], v[40:43]
	v_mfma_f32_16x16x32_bf16 v[28:31], v[132:135], v[204:207], v[28:31]
	v_mfma_f32_16x16x32_bf16 v[24:27], v[140:143], v[204:207], v[24:27]
	v_mfma_f32_16x16x32_bf16 v[12:15], v[132:135], v[212:215], v[12:15]
	v_mfma_f32_16x16x32_bf16 v[8:11], v[140:143], v[212:215], v[8:11]
	s_setprio 0
	s_setprio 1
	v_mfma_f32_16x16x32_bf16 v[52:55], v[168:171], v[184:187], v[52:55]
	v_mfma_f32_16x16x32_bf16 v[48:51], v[176:179], v[184:187], v[48:51]
	v_mfma_f32_16x16x32_bf16 v[36:39], v[168:171], v[192:195], v[36:39]
	v_mfma_f32_16x16x32_bf16 v[32:35], v[176:179], v[192:195], v[32:35]
	v_mfma_f32_16x16x32_bf16 v[20:23], v[168:171], v[200:203], v[20:23]
	v_mfma_f32_16x16x32_bf16 v[16:19], v[176:179], v[200:203], v[16:19]
	v_mfma_f32_16x16x32_bf16 v[4:7], v[168:171], v[208:211], v[4:7]
	v_mfma_f32_16x16x32_bf16 v[0:3], v[176:179], v[208:211], v[0:3]
	v_mfma_f32_16x16x32_bf16 v[52:55], v[172:175], v[188:191], v[52:55]
	v_mfma_f32_16x16x32_bf16 v[48:51], v[180:183], v[188:191], v[48:51]
	v_mfma_f32_16x16x32_bf16 v[36:39], v[172:175], v[196:199], v[36:39]
	v_mfma_f32_16x16x32_bf16 v[32:35], v[180:183], v[196:199], v[32:35]
	v_mfma_f32_16x16x32_bf16 v[20:23], v[172:175], v[204:207], v[20:23]
	v_mfma_f32_16x16x32_bf16 v[16:19], v[180:183], v[204:207], v[16:19]
	v_mfma_f32_16x16x32_bf16 v[4:7], v[172:175], v[212:215], v[4:7]
	v_mfma_f32_16x16x32_bf16 v[0:3], v[180:183], v[212:215], v[0:3]
	s_setprio 0
	s_barrier
	ds_read_b128 v[184:187], v167 offset:32768
	ds_read_b128 v[188:191], v167 offset:33792
	ds_read_b128 v[192:195], v167 offset:34816
	ds_read_b128 v[196:199], v167 offset:35840
	ds_read_b128 v[200:203], v167 offset:36864
	ds_read_b128 v[204:207], v167 offset:37888
	ds_read_b128 v[208:211], v167 offset:38912
	ds_read_b128 v[212:215], v167 offset:39936
	s_add_i32 s71, 0, 0x18000
	s_add_i32 s72, 0, 0x1c000
	v_add_u32_e32 v140, s71, v161
	v_add_u32_e32 v160, s72, v161
	ds_read_b128 v[128:131], v140
	ds_read_b128 v[132:135], v140 offset:1024
	ds_read_b128 v[136:139], v140 offset:2048
	ds_read_b128 v[140:143], v140 offset:3072
	ds_read_b128 v[168:171], v160
	ds_read_b128 v[172:175], v160 offset:1024
	ds_read_b128 v[176:179], v160 offset:2048
	ds_read_b128 v[180:183], v160 offset:3072
	s_add_u32 s66, s66, 0x100000
	s_addc_u32 s67, s67, 0
	s_mov_b32 m0, s78
	v_lshl_add_u64 v[224:225], s[66:67], 0, v[144:145]
	global_load_lds_dwordx4 v[224:225], off
	v_lshl_add_u64 v[224:225], s[66:67], 0, v[148:149]
	s_mov_b32 m0, s79
	s_nop 0
	global_load_lds_dwordx4 v[224:225], off
	s_waitcnt vmcnt(8)
	s_waitcnt lgkmcnt(0)
	s_barrier
	s_setprio 1
	s_waitcnt lgkmcnt(0)
	v_mfma_f32_16x16x32_bf16 v[124:127], v[128:131], v[184:187], v[124:127]
	v_mfma_f32_16x16x32_bf16 v[120:123], v[136:139], v[184:187], v[120:123]
	v_mfma_f32_16x16x32_bf16 v[108:111], v[128:131], v[192:195], v[108:111]
	v_mfma_f32_16x16x32_bf16 v[104:107], v[136:139], v[192:195], v[104:107]
	v_mfma_f32_16x16x32_bf16 v[92:95], v[128:131], v[200:203], v[92:95]
	v_mfma_f32_16x16x32_bf16 v[88:91], v[136:139], v[200:203], v[88:91]
	v_mfma_f32_16x16x32_bf16 v[76:79], v[128:131], v[208:211], v[76:79]
	v_mfma_f32_16x16x32_bf16 v[72:75], v[136:139], v[208:211], v[72:75]
	v_mfma_f32_16x16x32_bf16 v[124:127], v[132:135], v[188:191], v[124:127]
	v_mfma_f32_16x16x32_bf16 v[120:123], v[140:143], v[188:191], v[120:123]
	v_mfma_f32_16x16x32_bf16 v[108:111], v[132:135], v[196:199], v[108:111]
	v_mfma_f32_16x16x32_bf16 v[104:107], v[140:143], v[196:199], v[104:107]
	v_mfma_f32_16x16x32_bf16 v[92:95], v[132:135], v[204:207], v[92:95]
	v_mfma_f32_16x16x32_bf16 v[88:91], v[140:143], v[204:207], v[88:91]
	v_mfma_f32_16x16x32_bf16 v[76:79], v[132:135], v[212:215], v[76:79]
	v_mfma_f32_16x16x32_bf16 v[72:75], v[140:143], v[212:215], v[72:75]
	s_setprio 0
	s_setprio 1
	v_mfma_f32_16x16x32_bf16 v[116:119], v[168:171], v[184:187], v[116:119]
	v_mfma_f32_16x16x32_bf16 v[112:115], v[176:179], v[184:187], v[112:115]
	v_mfma_f32_16x16x32_bf16 v[100:103], v[168:171], v[192:195], v[100:103]
	v_mfma_f32_16x16x32_bf16 v[96:99], v[176:179], v[192:195], v[96:99]
	v_mfma_f32_16x16x32_bf16 v[84:87], v[168:171], v[200:203], v[84:87]
	v_mfma_f32_16x16x32_bf16 v[80:83], v[176:179], v[200:203], v[80:83]
	v_mfma_f32_16x16x32_bf16 v[68:71], v[168:171], v[208:211], v[68:71]
	v_mfma_f32_16x16x32_bf16 v[64:67], v[176:179], v[208:211], v[64:67]
	v_mfma_f32_16x16x32_bf16 v[116:119], v[172:175], v[188:191], v[116:119]
	v_mfma_f32_16x16x32_bf16 v[112:115], v[180:183], v[188:191], v[112:115]
	v_mfma_f32_16x16x32_bf16 v[100:103], v[172:175], v[196:199], v[100:103]
	v_mfma_f32_16x16x32_bf16 v[96:99], v[180:183], v[196:199], v[96:99]
	v_mfma_f32_16x16x32_bf16 v[84:87], v[172:175], v[204:207], v[84:87]
	v_mfma_f32_16x16x32_bf16 v[80:83], v[180:183], v[204:207], v[80:83]
	v_mfma_f32_16x16x32_bf16 v[68:71], v[172:175], v[212:215], v[68:71]
	v_mfma_f32_16x16x32_bf16 v[64:67], v[180:183], v[212:215], v[64:67]
	s_setprio 0
	s_barrier
; #define PG8_STAGE(bufoff, gbase, voff) do { _Pragma("unroll") for (int _i = 0; _i < 2; ++_i) \
;         __builtin_amdgcn_global_load_lds((const unsigned*)((const char*)(gbase) + (voff)[_i]), (PG8_LAS unsigned*)(lds + (bufoff) + ldsw + _i * 8192), 16, 0, 0); } while (0)
; #define PG8_LDA(dst, b, h) do { _Pragma("unroll") for (int m = 0; m < 4; ++m) _Pragma("unroll") for (int k = 0; k < 2; ++k) dst[m][k] = *(const PG8_LAS bf16x8*)(lds + PG8_SA(b, h) + aoff + m * 2048 + k * 1024); } while (0)
; #define PG8_MMA(ai, bj, At, Bt) do { __builtin_amdgcn_s_setprio(1); _Pragma("unroll") for (int m = 0; m < 4; ++m) _Pragma("unroll") for (int n = 0; n < 2; ++n) _Pragma("unroll") for (int k = 0; k < 2; ++k) \
;         acc[ai][bj][m][n] = __builtin_amdgcn_mfma_f32_16x16x32_bf16(Bt[n][k], At[m][k], acc[ai][bj][m][n], 0, 0, 0); __builtin_amdgcn_s_setprio(0); } while (0)
; #define PG8_WAIT_V(n) asm volatile("s_waitcnt vmcnt(" #n ")" ::: "memory")
; #define PG8_WAIT_L(n) asm volatile("s_waitcnt lgkmcnt(" #n ")" ::: "memory")
; #define PG8_BAR __builtin_amdgcn_s_barrier()
; #define PG8_SCHED __builtin_amdgcn_sched_barrier(0)
; template <class Epi, class Sched, bool ALIGN_EPI = false, bool SP2 = false>
; __device__ __forceinline__ void gemm_phase(PG8_LAS unsigned char* lds, const Gemm g, const Sched& S, const Epi& E, const int wid) {
;     ...
;         for (int t = 0; t < nt; t += 2) {
;             const bool last = (t == nt - 2);
;     ...
;             PG8_LDA(At, 1, 1); PG8_STAGE(PG8_SB(1, 0), b3, voffB); PG8_STAGE(PG8_SB(1, 1), b3 + hstep, voffB); PG8_STAGE(PG8_SA(1, 0), a3, voffA);
;             PG8_WAIT_V(8); PG8_WAIT_L(0); PG8_BAR; PG8_MMA(1, 0, At, B0); PG8_MMA(1, 1, At, B1); PG8_BAR; PG8_SCHED;
	ds_read_b128 v[184:187], v167 offset:49152
	ds_read_b128 v[188:191], v167 offset:50176
	ds_read_b128 v[192:195], v167 offset:51200
	ds_read_b128 v[196:199], v167 offset:52224
	ds_read_b128 v[200:203], v167 offset:53248
	ds_read_b128 v[204:207], v167 offset:54272
	ds_read_b128 v[208:211], v167 offset:55296
	ds_read_b128 v[212:215], v167 offset:56320
	s_add_i32 s66, s71, s75
	v_lshl_add_u64 v[216:217], v[216:217], 0, s[40:41]
	s_mov_b32 m0, s66
	s_nop 0
	global_load_lds_dwordx4 v[216:217], off
	s_add_i32 m0, s66, 0x2000
	s_add_u32 s62, s62, 0x100080
	v_lshl_add_u64 v[216:217], v[218:219], 0, s[40:41]
	s_addc_u32 s63, s63, 0
	s_add_i32 s66, s72, s75
	global_load_lds_dwordx4 v[216:217], off
	v_lshl_add_u64 v[216:217], s[62:63], 0, v[146:147]
	s_mov_b32 m0, s66
	s_nop 0
	global_load_lds_dwordx4 v[216:217], off
	v_lshl_add_u64 v[216:217], s[62:63], 0, v[150:151]
	s_add_i32 m0, s66, 0x2000
	s_nop 0
	global_load_lds_dwordx4 v[216:217], off
	v_lshl_add_u64 v[216:217], v[220:221], 0, s[40:41]
	s_mov_b32 m0, s83
	s_nop 0
	global_load_lds_dwordx4 v[216:217], off
	v_lshl_add_u64 v[216:217], v[222:223], 0, s[40:41]
	s_mov_b32 m0, s84
	s_nop 0
	global_load_lds_dwordx4 v[216:217], off
	s_waitcnt vmcnt(8)
	s_waitcnt lgkmcnt(0)
	s_barrier
	s_setprio 1
	s_waitcnt lgkmcnt(0)
	v_mfma_f32_16x16x32_bf16 v[60:63], v[128:131], v[184:187], v[60:63]
	v_mfma_f32_16x16x32_bf16 v[56:59], v[136:139], v[184:187], v[56:59]
	v_mfma_f32_16x16x32_bf16 v[44:47], v[128:131], v[192:195], v[44:47]
	v_mfma_f32_16x16x32_bf16 v[40:43], v[136:139], v[192:195], v[40:43]
	v_mfma_f32_16x16x32_bf16 v[28:31], v[128:131], v[200:203], v[28:31]
	v_mfma_f32_16x16x32_bf16 v[24:27], v[136:139], v[200:203], v[24:27]
	v_mfma_f32_16x16x32_bf16 v[12:15], v[128:131], v[208:211], v[12:15]
	v_mfma_f32_16x16x32_bf16 v[8:11], v[136:139], v[208:211], v[8:11]
	v_mfma_f32_16x16x32_bf16 v[60:63], v[132:135], v[188:191], v[60:63]
	v_mfma_f32_16x16x32_bf16 v[56:59], v[140:143], v[188:191], v[56:59]
	v_mfma_f32_16x16x32_bf16 v[44:47], v[132:135], v[196:199], v[44:47]
	v_mfma_f32_16x16x32_bf16 v[40:43], v[140:143], v[196:199], v[40:43]
	v_mfma_f32_16x16x32_bf16 v[28:31], v[132:135], v[204:207], v[28:31]
	v_mfma_f32_16x16x32_bf16 v[24:27], v[140:143], v[204:207], v[24:27]
	v_mfma_f32_16x16x32_bf16 v[12:15], v[132:135], v[212:215], v[12:15]
	v_mfma_f32_16x16x32_bf16 v[8:11], v[140:143], v[212:215], v[8:11]
	s_setprio 0
	s_setprio 1
	v_mfma_f32_16x16x32_bf16 v[52:55], v[168:171], v[184:187], v[52:55]
	v_mfma_f32_16x16x32_bf16 v[48:51], v[176:179], v[184:187], v[48:51]
	v_mfma_f32_16x16x32_bf16 v[36:39], v[168:171], v[192:195], v[36:39]
	v_mfma_f32_16x16x32_bf16 v[32:35], v[176:179], v[192:195], v[32:35]
	s_add_i32 s70, s70, 2
	s_add_u32 s60, s60, 0x100
	s_addc_u32 s61, s61, 0
	s_add_u32 s68, s68, 0x100
	s_addc_u32 s69, s69, 0
	s_cmp_gt_u32 s70, 61
	v_mfma_f32_16x16x32_bf16 v[20:23], v[168:171], v[200:203], v[20:23]
	v_mfma_f32_16x16x32_bf16 v[16:19], v[176:179], v[200:203], v[16:19]
	v_mfma_f32_16x16x32_bf16 v[4:7], v[168:171], v[208:211], v[4:7]
	v_mfma_f32_16x16x32_bf16 v[0:3], v[176:179], v[208:211], v[0:3]
	v_mfma_f32_16x16x32_bf16 v[52:55], v[172:175], v[188:191], v[52:55]
	v_mfma_f32_16x16x32_bf16 v[48:51], v[180:183], v[188:191], v[48:51]
	v_mfma_f32_16x16x32_bf16 v[36:39], v[172:175], v[196:199], v[36:39]
	v_mfma_f32_16x16x32_bf16 v[32:35], v[180:183], v[196:199], v[32:35]
	v_mfma_f32_16x16x32_bf16 v[20:23], v[172:175], v[204:207], v[20:23]
	v_mfma_f32_16x16x32_bf16 v[16:19], v[180:183], v[204:207], v[16:19]
	v_mfma_f32_16x16x32_bf16 v[4:7], v[172:175], v[212:215], v[4:7]
	v_mfma_f32_16x16x32_bf16 v[0:3], v[180:183], v[212:215], v[0:3]
	s_setprio 0
	s_barrier
	s_cbranch_scc0 .LBB0_277
	s_and_b64 vcc, exec, s[42:43]
	s_cbranch_vccz .LBB0_280
	s_barrier

; #define PG8_STAGE(bufoff, gbase, voff) do { _Pragma("unroll") for (int _i = 0; _i < 2; ++_i) \
;         __builtin_amdgcn_global_load_lds((const unsigned*)((const char*)(gbase) + (voff)[_i]), (PG8_LAS unsigned*)(lds + (bufoff) + ldsw + _i * 8192), 16, 0, 0); } while (0)
; #define PG8_LDA(dst, b, h) do { _Pragma("unroll") for (int m = 0; m < 4; ++m) _Pragma("unroll") for (int k = 0; k < 2; ++k) dst[m][k] = *(const PG8_LAS bf16x8*)(lds + PG8_SA(b, h) + aoff + m * 2048 + k * 1024); } while (0)
; #define PG8_LDB(dst, b, h) do { _Pragma("unroll") for (int n = 0; n < 2; ++n) _Pragma("unroll") for (int k = 0; k < 2; ++k) dst[n][k] = *(const PG8_LAS bf16x8*)(lds + PG8_SB(b, h) + boff + n * 2048 + k * 1024); } while (0)
; #define PG8_MMA(ai, bj, At, Bt) do { __builtin_amdgcn_s_setprio(1); _Pragma("unroll") for (int m = 0; m < 4; ++m) _Pragma("unroll") for (int n = 0; n < 2; ++n) _Pragma("unroll") for (int k = 0; k < 2; ++k) \
;         acc[ai][bj][m][n] = __builtin_amdgcn_mfma_f32_16x16x32_bf16(Bt[n][k], At[m][k], acc[ai][bj][m][n], 0, 0, 0); __builtin_amdgcn_s_setprio(0); } while (0)
; #define PG8_WAIT_V(n) asm volatile("s_waitcnt vmcnt(" #n ")" ::: "memory")
; #define PG8_WAIT_L(n) asm volatile("s_waitcnt lgkmcnt(" #n ")" ::: "memory")
; template <class Epi, class Sched, bool ALIGN_EPI = false, bool SP2 = false>
; __device__ __forceinline__ void gemm_phase(PG8_LAS unsigned char* lds, const Gemm g, const Sched& S, const Epi& E, const int wid) {
;     ...
;             const bool last = (t == nt - 2);
;             const char* a1 = cA + (size_t)(t + 1) * kstep;
;             const char* a2 = last ? nA : cA + (size_t)(t + 2) * kstep; const char* b2 = last ? nB : cB + (size_t)(t + 2) * kstep;
;             const char* a3 = a2 + kstep; const char* b3 = b2 + kstep;
;             if (last && has_next) S.a_ready(nxt);
;             if constexpr (SP2) {
;             PG8_LDB(B0, 0, 0); PG8_LDB(B1, 0, 1); PG8_SCHED; PG8_LDA(At, 0, 0); PG8_STAGE(PG8_SA(1, 1), a1 + hstep, voffA);
;             PG8_WAIT_V(8); PG8_WAIT_L(0); PG8_BAR; PG8_MMA(0, 0, At, B0); PG8_MMA(0, 1, At, B1); PG8_BAR; PG8_SCHED;
;             PG8_LDA(At, 0, 1); PG8_STAGE(PG8_SB(0, 0), b2, voffB); PG8_STAGE(PG8_SB(0, 1), b2 + hstep, voffB); PG8_STAGE(PG8_SA(0, 0), a2, voffA);
;             PG8_WAIT_V(8); PG8_WAIT_L(0); PG8_BAR; PG8_MMA(1, 0, At, B0); PG8_MMA(1, 1, At, B1); PG8_BAR; PG8_SCHED;
.LBB0_2061:
	ds_read_b128 v[128:131], v170
	ds_read_b128 v[132:135], v170 offset:1024
	ds_read_b128 v[150:153], v170 offset:2048
	ds_read_b128 v[154:157], v170 offset:3072
	ds_read_b128 v[158:161], v171
	ds_read_b128 v[162:165], v171 offset:1024
	ds_read_b128 v[166:169], v171 offset:2048
	ds_read_b128 v[176:179], v171 offset:3072
	ds_read_b128 v[180:183], v172
	ds_read_b128 v[184:187], v172 offset:1024
	ds_read_b128 v[188:191], v172 offset:2048
	ds_read_b128 v[192:195], v172 offset:3072
	ds_read_b128 v[196:199], v172 offset:4096
	ds_read_b128 v[200:203], v172 offset:5120
	ds_read_b128 v[204:207], v172 offset:6144
	ds_read_b128 v[208:211], v172 offset:7168
	s_add_i32 s12, s2, 2
	s_add_u32 s13, s0, 0x80
	s_addc_u32 s3, s1, 0
	s_cmp_eq_u32 s56, s2
	s_cselect_b32 s2, s38, s13
	s_cselect_b32 s3, s39, s3
	s_cselect_b32 s69, s41, s9
	s_cselect_b32 s68, s40, s8
	s_mov_b32 m0, s57
	v_lshl_add_u64 v[212:213], s[0:1], 0, v[146:147]
	global_load_lds_dwordx4 v[212:213], off
	v_lshl_add_u64 v[212:213], s[0:1], 0, v[148:149]
	s_mov_b32 m0, s58
	s_nop 0
	global_load_lds_dwordx4 v[212:213], off
	s_waitcnt vmcnt(8)
	s_waitcnt lgkmcnt(0)
	s_barrier
	s_setprio 1
	s_waitcnt lgkmcnt(0)
	v_mfma_f32_16x16x32_bf16 v[124:127], v[128:131], v[180:183], v[124:127]
	v_mfma_f32_16x16x32_bf16 v[120:123], v[150:153], v[180:183], v[120:123]
	v_mfma_f32_16x16x32_bf16 v[116:119], v[128:131], v[188:191], v[116:119]
	v_mfma_f32_16x16x32_bf16 v[112:115], v[150:153], v[188:191], v[112:115]
	v_mfma_f32_16x16x32_bf16 v[108:111], v[128:131], v[196:199], v[108:111]
	v_mfma_f32_16x16x32_bf16 v[104:107], v[150:153], v[196:199], v[104:107]
	v_mfma_f32_16x16x32_bf16 v[100:103], v[128:131], v[204:207], v[100:103]
	v_mfma_f32_16x16x32_bf16 v[96:99], v[150:153], v[204:207], v[96:99]
	v_mfma_f32_16x16x32_bf16 v[124:127], v[132:135], v[184:187], v[124:127]
	v_mfma_f32_16x16x32_bf16 v[120:123], v[154:157], v[184:187], v[120:123]
	v_mfma_f32_16x16x32_bf16 v[116:119], v[132:135], v[192:195], v[116:119]
	v_mfma_f32_16x16x32_bf16 v[112:115], v[154:157], v[192:195], v[112:115]
	v_mfma_f32_16x16x32_bf16 v[108:111], v[132:135], v[200:203], v[108:111]
	v_mfma_f32_16x16x32_bf16 v[104:107], v[154:157], v[200:203], v[104:107]
	v_mfma_f32_16x16x32_bf16 v[100:103], v[132:135], v[208:211], v[100:103]
	v_mfma_f32_16x16x32_bf16 v[96:99], v[154:157], v[208:211], v[96:99]
	s_setprio 0
	s_setprio 1
	v_mfma_f32_16x16x32_bf16 v[60:63], v[158:161], v[180:183], v[60:63]
	v_mfma_f32_16x16x32_bf16 v[56:59], v[166:169], v[180:183], v[56:59]
	v_mfma_f32_16x16x32_bf16 v[52:55], v[158:161], v[188:191], v[52:55]
	v_mfma_f32_16x16x32_bf16 v[48:51], v[166:169], v[188:191], v[48:51]
	v_mfma_f32_16x16x32_bf16 v[44:47], v[158:161], v[196:199], v[44:47]
	v_mfma_f32_16x16x32_bf16 v[40:43], v[166:169], v[196:199], v[40:43]
	v_mfma_f32_16x16x32_bf16 v[36:39], v[158:161], v[204:207], v[36:39]
	v_mfma_f32_16x16x32_bf16 v[32:35], v[166:169], v[204:207], v[32:35]
	v_mfma_f32_16x16x32_bf16 v[60:63], v[162:165], v[184:187], v[60:63]
	v_mfma_f32_16x16x32_bf16 v[56:59], v[176:179], v[184:187], v[56:59]
	v_mfma_f32_16x16x32_bf16 v[52:55], v[162:165], v[192:195], v[52:55]
	v_mfma_f32_16x16x32_bf16 v[48:51], v[176:179], v[192:195], v[48:51]
	v_mfma_f32_16x16x32_bf16 v[44:47], v[162:165], v[200:203], v[44:47]
	v_mfma_f32_16x16x32_bf16 v[40:43], v[176:179], v[200:203], v[40:43]
	v_mfma_f32_16x16x32_bf16 v[36:39], v[162:165], v[208:211], v[36:39]
	v_mfma_f32_16x16x32_bf16 v[32:35], v[176:179], v[208:211], v[32:35]
	s_setprio 0
	s_barrier
	ds_read_b128 v[180:183], v172 offset:16384
	ds_read_b128 v[184:187], v172 offset:17408
	ds_read_b128 v[188:191], v172 offset:18432
	ds_read_b128 v[192:195], v172 offset:19456
	ds_read_b128 v[196:199], v172 offset:20480
	ds_read_b128 v[200:203], v172 offset:21504
	ds_read_b128 v[204:207], v172 offset:22528
	ds_read_b128 v[208:211], v172 offset:23552
	s_mov_b32 m0, s59
	v_lshl_add_u64 v[212:213], s[68:69], 0, v[140:141]
	v_lshl_add_u64 v[214:215], s[68:69], 0, v[136:137]
	s_add_u32 s68, s68, s16
	global_load_lds_dwordx4 v[212:213], off
	s_mov_b32 m0, s60
	s_addc_u32 s69, s69, s17
	global_load_lds_dwordx4 v[214:215], off
	v_lshl_add_u64 v[216:217], s[68:69], 0, v[140:141]
	s_mov_b32 m0, s61
	v_lshl_add_u64 v[218:219], s[68:69], 0, v[136:137]
	global_load_lds_dwordx4 v[216:217], off
	s_mov_b32 m0, s62
	v_lshl_add_u64 v[220:221], s[2:3], 0, v[142:143]
	global_load_lds_dwordx4 v[218:219], off
	s_mov_b32 m0, s46
	v_lshl_add_u64 v[222:223], s[2:3], 0, v[138:139]
	global_load_lds_dwordx4 v[220:221], off
	s_mov_b32 m0, s47
	s_nop 0
	global_load_lds_dwordx4 v[222:223], off
	s_waitcnt vmcnt(8)
	s_waitcnt lgkmcnt(0)
	s_barrier
; #define PG8_STAGE(bufoff, gbase, voff) do { _Pragma("unroll") for (int _i = 0; _i < 2; ++_i) \
;         __builtin_amdgcn_global_load_lds((const unsigned*)((const char*)(gbase) + (voff)[_i]), (PG8_LAS unsigned*)(lds + (bufoff) + ldsw + _i * 8192), 16, 0, 0); } while (0)
; #define PG8_LDA(dst, b, h) do { _Pragma("unroll") for (int m = 0; m < 4; ++m) _Pragma("unroll") for (int k = 0; k < 2; ++k) dst[m][k] = *(const PG8_LAS bf16x8*)(lds + PG8_SA(b, h) + aoff + m * 2048 + k * 1024); } while (0)
; #define PG8_LDB(dst, b, h) do { _Pragma("unroll") for (int n = 0; n < 2; ++n) _Pragma("unroll") for (int k = 0; k < 2; ++k) dst[n][k] = *(const PG8_LAS bf16x8*)(lds + PG8_SB(b, h) + boff + n * 2048 + k * 1024); } while (0)
; #define PG8_MMA(ai, bj, At, Bt) do { __builtin_amdgcn_s_setprio(1); _Pragma("unroll") for (int m = 0; m < 4; ++m) _Pragma("unroll") for (int n = 0; n < 2; ++n) _Pragma("unroll") for (int k = 0; k < 2; ++k) \
;         acc[ai][bj][m][n] = __builtin_amdgcn_mfma_f32_16x16x32_bf16(Bt[n][k], At[m][k], acc[ai][bj][m][n], 0, 0, 0); __builtin_amdgcn_s_setprio(0); } while (0)
; #define PG8_WAIT_V(n) asm volatile("s_waitcnt vmcnt(" #n ")" ::: "memory")
; #define PG8_WAIT_L(n) asm volatile("s_waitcnt lgkmcnt(" #n ")" ::: "memory")
; #define PG8_BAR __builtin_amdgcn_s_barrier()
; #define PG8_SCHED __builtin_amdgcn_sched_barrier(0)
; template <class Epi, class Sched, bool ALIGN_EPI = false, bool SP2 = false>
; __device__ __forceinline__ void gemm_phase(PG8_LAS unsigned char* lds, const Gemm g, const Sched& S, const Epi& E, const int wid) {
;     ...
;             PG8_WAIT_V(8); PG8_WAIT_L(0); PG8_BAR; PG8_MMA(1, 0, At, B0); PG8_MMA(1, 1, At, B1); PG8_BAR; PG8_SCHED;
;             PG8_LDB(B0, 1, 0); PG8_LDB(B1, 1, 1); PG8_SCHED; PG8_LDA(At, 1, 0); PG8_STAGE(PG8_SA(0, 1), a2 + hstep, voffA);
;             PG8_WAIT_V(8); PG8_WAIT_L(0); PG8_BAR; PG8_MMA(0, 0, At, B0); PG8_MMA(0, 1, At, B1); PG8_BAR; PG8_SCHED;
	s_setprio 1
	s_waitcnt lgkmcnt(0)
	v_mfma_f32_16x16x32_bf16 v[92:95], v[128:131], v[180:183], v[92:95]
	v_mfma_f32_16x16x32_bf16 v[88:91], v[150:153], v[180:183], v[88:91]
	v_mfma_f32_16x16x32_bf16 v[84:87], v[128:131], v[188:191], v[84:87]
	v_mfma_f32_16x16x32_bf16 v[80:83], v[150:153], v[188:191], v[80:83]
	v_mfma_f32_16x16x32_bf16 v[76:79], v[128:131], v[196:199], v[76:79]
	v_mfma_f32_16x16x32_bf16 v[72:75], v[150:153], v[196:199], v[72:75]
	v_mfma_f32_16x16x32_bf16 v[68:71], v[128:131], v[204:207], v[68:71]
	v_mfma_f32_16x16x32_bf16 v[64:67], v[150:153], v[204:207], v[64:67]
	v_mfma_f32_16x16x32_bf16 v[92:95], v[132:135], v[184:187], v[92:95]
	v_mfma_f32_16x16x32_bf16 v[88:91], v[154:157], v[184:187], v[88:91]
	v_mfma_f32_16x16x32_bf16 v[84:87], v[132:135], v[192:195], v[84:87]
	v_mfma_f32_16x16x32_bf16 v[80:83], v[154:157], v[192:195], v[80:83]
	v_mfma_f32_16x16x32_bf16 v[76:79], v[132:135], v[200:203], v[76:79]
	v_mfma_f32_16x16x32_bf16 v[72:75], v[154:157], v[200:203], v[72:75]
	v_mfma_f32_16x16x32_bf16 v[68:71], v[132:135], v[208:211], v[68:71]
	v_mfma_f32_16x16x32_bf16 v[64:67], v[154:157], v[208:211], v[64:67]
	s_setprio 0
	s_setprio 1
	v_mfma_f32_16x16x32_bf16 v[28:31], v[158:161], v[180:183], v[28:31]
	v_mfma_f32_16x16x32_bf16 v[24:27], v[166:169], v[180:183], v[24:27]
	v_mfma_f32_16x16x32_bf16 v[20:23], v[158:161], v[188:191], v[20:23]
	v_mfma_f32_16x16x32_bf16 v[16:19], v[166:169], v[188:191], v[16:19]
	v_mfma_f32_16x16x32_bf16 v[12:15], v[158:161], v[196:199], v[12:15]
	v_mfma_f32_16x16x32_bf16 v[8:11], v[166:169], v[196:199], v[8:11]
	v_mfma_f32_16x16x32_bf16 v[4:7], v[158:161], v[204:207], v[4:7]
	v_mfma_f32_16x16x32_bf16 v[0:3], v[166:169], v[204:207], v[0:3]
	v_mfma_f32_16x16x32_bf16 v[28:31], v[162:165], v[184:187], v[28:31]
	v_mfma_f32_16x16x32_bf16 v[24:27], v[176:179], v[184:187], v[24:27]
	v_mfma_f32_16x16x32_bf16 v[20:23], v[162:165], v[192:195], v[20:23]
	v_mfma_f32_16x16x32_bf16 v[16:19], v[176:179], v[192:195], v[16:19]
	v_mfma_f32_16x16x32_bf16 v[12:15], v[162:165], v[200:203], v[12:15]
	v_mfma_f32_16x16x32_bf16 v[8:11], v[176:179], v[200:203], v[8:11]
	v_mfma_f32_16x16x32_bf16 v[4:7], v[162:165], v[208:211], v[4:7]
	v_mfma_f32_16x16x32_bf16 v[0:3], v[176:179], v[208:211], v[0:3]
	s_setprio 0
	s_barrier
	ds_read_b128 v[128:131], v173
	ds_read_b128 v[132:135], v173 offset:1024
	ds_read_b128 v[150:153], v173 offset:2048
	ds_read_b128 v[154:157], v173 offset:3072
	ds_read_b128 v[158:161], v174
	ds_read_b128 v[162:165], v174 offset:1024
	ds_read_b128 v[166:169], v174 offset:2048
	ds_read_b128 v[176:179], v174 offset:3072
	ds_read_b128 v[180:183], v172 offset:32768
	ds_read_b128 v[184:187], v172 offset:33792
	ds_read_b128 v[188:191], v172 offset:34816
	ds_read_b128 v[192:195], v172 offset:35840
	ds_read_b128 v[196:199], v172 offset:36864
	ds_read_b128 v[200:203], v172 offset:37888
	ds_read_b128 v[204:207], v172 offset:38912
	ds_read_b128 v[208:211], v172 offset:39936
	s_add_u32 s2, s2, s16
	s_addc_u32 s3, s3, s17
	s_mov_b32 m0, s48
	v_lshl_add_u64 v[224:225], s[2:3], 0, v[142:143]
	global_load_lds_dwordx4 v[224:225], off
	v_lshl_add_u64 v[224:225], s[2:3], 0, v[138:139]
	s_mov_b32 m0, s49
	s_nop 0
	global_load_lds_dwordx4 v[224:225], off
	s_waitcnt vmcnt(8)
	s_waitcnt lgkmcnt(0)
	s_barrier
	s_setprio 1
	s_waitcnt lgkmcnt(0)
	v_mfma_f32_16x16x32_bf16 v[124:127], v[128:131], v[180:183], v[124:127]
	v_mfma_f32_16x16x32_bf16 v[120:123], v[150:153], v[180:183], v[120:123]
	v_mfma_f32_16x16x32_bf16 v[116:119], v[128:131], v[188:191], v[116:119]
	v_mfma_f32_16x16x32_bf16 v[112:115], v[150:153], v[188:191], v[112:115]
	v_mfma_f32_16x16x32_bf16 v[108:111], v[128:131], v[196:199], v[108:111]
	v_mfma_f32_16x16x32_bf16 v[104:107], v[150:153], v[196:199], v[104:107]
	v_mfma_f32_16x16x32_bf16 v[100:103], v[128:131], v[204:207], v[100:103]
	v_mfma_f32_16x16x32_bf16 v[96:99], v[150:153], v[204:207], v[96:99]
	v_mfma_f32_16x16x32_bf16 v[124:127], v[132:135], v[184:187], v[124:127]
	v_mfma_f32_16x16x32_bf16 v[120:123], v[154:157], v[184:187], v[120:123]
	v_mfma_f32_16x16x32_bf16 v[116:119], v[132:135], v[192:195], v[116:119]
	v_mfma_f32_16x16x32_bf16 v[112:115], v[154:157], v[192:195], v[112:115]
	v_mfma_f32_16x16x32_bf16 v[108:111], v[132:135], v[200:203], v[108:111]
	v_mfma_f32_16x16x32_bf16 v[104:107], v[154:157], v[200:203], v[104:107]
	v_mfma_f32_16x16x32_bf16 v[100:103], v[132:135], v[208:211], v[100:103]
	v_mfma_f32_16x16x32_bf16 v[96:99], v[154:157], v[208:211], v[96:99]
	s_setprio 0
	s_setprio 1
	v_mfma_f32_16x16x32_bf16 v[60:63], v[158:161], v[180:183], v[60:63]
	v_mfma_f32_16x16x32_bf16 v[56:59], v[166:169], v[180:183], v[56:59]
	v_mfma_f32_16x16x32_bf16 v[52:55], v[158:161], v[188:191], v[52:55]
	v_mfma_f32_16x16x32_bf16 v[48:51], v[166:169], v[188:191], v[48:51]
	v_mfma_f32_16x16x32_bf16 v[44:47], v[158:161], v[196:199], v[44:47]
	v_mfma_f32_16x16x32_bf16 v[40:43], v[166:169], v[196:199], v[40:43]
	v_mfma_f32_16x16x32_bf16 v[36:39], v[158:161], v[204:207], v[36:39]
	v_mfma_f32_16x16x32_bf16 v[32:35], v[166:169], v[204:207], v[32:35]
	v_mfma_f32_16x16x32_bf16 v[60:63], v[162:165], v[184:187], v[60:63]
	v_mfma_f32_16x16x32_bf16 v[56:59], v[176:179], v[184:187], v[56:59]
	v_mfma_f32_16x16x32_bf16 v[52:55], v[162:165], v[192:195], v[52:55]
	v_mfma_f32_16x16x32_bf16 v[48:51], v[176:179], v[192:195], v[48:51]
	v_mfma_f32_16x16x32_bf16 v[44:47], v[162:165], v[200:203], v[44:47]
	v_mfma_f32_16x16x32_bf16 v[40:43], v[176:179], v[200:203], v[40:43]
	v_mfma_f32_16x16x32_bf16 v[36:39], v[162:165], v[208:211], v[36:39]
	v_mfma_f32_16x16x32_bf16 v[32:35], v[176:179], v[208:211], v[32:35]
	s_setprio 0
	s_barrier
; #define PG8_STAGE(bufoff, gbase, voff) do { _Pragma("unroll") for (int _i = 0; _i < 2; ++_i) \
;         __builtin_amdgcn_global_load_lds((const unsigned*)((const char*)(gbase) + (voff)[_i]), (PG8_LAS unsigned*)(lds + (bufoff) + ldsw + _i * 8192), 16, 0, 0); } while (0)
; #define PG8_LDA(dst, b, h) do { _Pragma("unroll") for (int m = 0; m < 4; ++m) _Pragma("unroll") for (int k = 0; k < 2; ++k) dst[m][k] = *(const PG8_LAS bf16x8*)(lds + PG8_SA(b, h) + aoff + m * 2048 + k * 1024); } while (0)
; #define PG8_MMA(ai, bj, At, Bt) do { __builtin_amdgcn_s_setprio(1); _Pragma("unroll") for (int m = 0; m < 4; ++m) _Pragma("unroll") for (int n = 0; n < 2; ++n) _Pragma("unroll") for (int k = 0; k < 2; ++k) \
;         acc[ai][bj][m][n] = __builtin_amdgcn_mfma_f32_16x16x32_bf16(Bt[n][k], At[m][k], acc[ai][bj][m][n], 0, 0, 0); __builtin_amdgcn_s_setprio(0); } while (0)
; #define PG8_WAIT_V(n) asm volatile("s_waitcnt vmcnt(" #n ")" ::: "memory")
; #define PG8_WAIT_L(n) asm volatile("s_waitcnt lgkmcnt(" #n ")" ::: "memory")
; #define PG8_BAR __builtin_amdgcn_s_barrier()
; #define PG8_SCHED __builtin_amdgcn_sched_barrier(0)
; template <class Epi, class Sched, bool ALIGN_EPI = false, bool SP2 = false>
; __device__ __forceinline__ void gemm_phase(PG8_LAS unsigned char* lds, const Gemm g, const Sched& S, const Epi& E, const int wid) {
;     ...
;         for (int t = 0; t < nt; t += 2) {
;             const bool last = (t == nt - 2);
;             const char* a1 = cA + (size_t)(t + 1) * kstep;
;             const char* a2 = last ? nA : cA + (size_t)(t + 2) * kstep; const char* b2 = last ? nB : cB + (size_t)(t + 2) * kstep;
;     ...
;             PG8_LDA(At, 1, 1); PG8_STAGE(PG8_SB(1, 0), b3, voffB); PG8_STAGE(PG8_SB(1, 1), b3 + hstep, voffB); PG8_STAGE(PG8_SA(1, 0), a3, voffA);
;             PG8_WAIT_V(8); PG8_WAIT_L(0); PG8_BAR; PG8_MMA(1, 0, At, B0); PG8_MMA(1, 1, At, B1); PG8_BAR; PG8_SCHED;
	ds_read_b128 v[180:183], v172 offset:49152
	ds_read_b128 v[184:187], v172 offset:50176
	ds_read_b128 v[188:191], v172 offset:51200
	ds_read_b128 v[192:195], v172 offset:52224
	ds_read_b128 v[196:199], v172 offset:53248
	ds_read_b128 v[200:203], v172 offset:54272
	ds_read_b128 v[204:207], v172 offset:55296
	ds_read_b128 v[208:211], v172 offset:56320
	s_add_i32 s2, s63, s45
	v_lshl_add_u64 v[212:213], v[212:213], 0, s[34:35]
	s_mov_b32 m0, s2
	s_nop 0
	global_load_lds_dwordx4 v[212:213], off
	v_lshl_add_u64 v[212:213], v[214:215], 0, s[34:35]
	s_add_i32 m0, s2, 0x2000
	s_add_i32 s2, s64, s45
	global_load_lds_dwordx4 v[212:213], off
	v_lshl_add_u64 v[212:213], v[216:217], 0, s[34:35]
	s_mov_b32 m0, s2
	s_nop 0
	global_load_lds_dwordx4 v[212:213], off
	v_lshl_add_u64 v[212:213], v[218:219], 0, s[34:35]
	s_add_i32 m0, s2, 0x2000
	s_nop 0
	global_load_lds_dwordx4 v[212:213], off
	v_lshl_add_u64 v[212:213], v[220:221], 0, s[34:35]
	s_mov_b32 m0, s51
	s_nop 0
	global_load_lds_dwordx4 v[212:213], off
	v_lshl_add_u64 v[212:213], v[222:223], 0, s[34:35]
	s_mov_b32 m0, s52
	s_nop 0
	global_load_lds_dwordx4 v[212:213], off
	s_waitcnt vmcnt(8)
	s_waitcnt lgkmcnt(0)
	s_barrier
	s_setprio 1
	s_waitcnt lgkmcnt(0)
	v_mfma_f32_16x16x32_bf16 v[92:95], v[128:131], v[180:183], v[92:95]
	v_mfma_f32_16x16x32_bf16 v[88:91], v[150:153], v[180:183], v[88:91]
	v_mfma_f32_16x16x32_bf16 v[84:87], v[128:131], v[188:191], v[84:87]
	v_mfma_f32_16x16x32_bf16 v[80:83], v[150:153], v[188:191], v[80:83]
	v_mfma_f32_16x16x32_bf16 v[76:79], v[128:131], v[196:199], v[76:79]
	v_mfma_f32_16x16x32_bf16 v[72:75], v[150:153], v[196:199], v[72:75]
	v_mfma_f32_16x16x32_bf16 v[68:71], v[128:131], v[204:207], v[68:71]
	v_mfma_f32_16x16x32_bf16 v[64:67], v[150:153], v[204:207], v[64:67]
	v_mfma_f32_16x16x32_bf16 v[92:95], v[132:135], v[184:187], v[92:95]
	v_mfma_f32_16x16x32_bf16 v[88:91], v[154:157], v[184:187], v[88:91]
	v_mfma_f32_16x16x32_bf16 v[84:87], v[132:135], v[192:195], v[84:87]
	v_mfma_f32_16x16x32_bf16 v[80:83], v[154:157], v[192:195], v[80:83]
	v_mfma_f32_16x16x32_bf16 v[76:79], v[132:135], v[200:203], v[76:79]
	v_mfma_f32_16x16x32_bf16 v[72:75], v[154:157], v[200:203], v[72:75]
	v_mfma_f32_16x16x32_bf16 v[68:71], v[132:135], v[208:211], v[68:71]
	v_mfma_f32_16x16x32_bf16 v[64:67], v[154:157], v[208:211], v[64:67]
	s_setprio 0
	s_setprio 1
	v_mfma_f32_16x16x32_bf16 v[28:31], v[158:161], v[180:183], v[28:31]
	v_mfma_f32_16x16x32_bf16 v[24:27], v[166:169], v[180:183], v[24:27]
	v_mfma_f32_16x16x32_bf16 v[20:23], v[158:161], v[188:191], v[20:23]
	v_mfma_f32_16x16x32_bf16 v[16:19], v[166:169], v[188:191], v[16:19]
	s_add_u32 s0, s0, 0x100
	s_addc_u32 s1, s1, 0
	s_add_u32 s8, s8, 0x100
	s_addc_u32 s9, s9, 0
	s_cmp_ge_i32 s12, s53
	s_mov_b32 s2, s12
	v_mfma_f32_16x16x32_bf16 v[12:15], v[158:161], v[196:199], v[12:15]
	v_mfma_f32_16x16x32_bf16 v[8:11], v[166:169], v[196:199], v[8:11]
	v_mfma_f32_16x16x32_bf16 v[4:7], v[158:161], v[204:207], v[4:7]
	v_mfma_f32_16x16x32_bf16 v[0:3], v[166:169], v[204:207], v[0:3]
	v_mfma_f32_16x16x32_bf16 v[28:31], v[162:165], v[184:187], v[28:31]
	v_mfma_f32_16x16x32_bf16 v[24:27], v[176:179], v[184:187], v[24:27]
	v_mfma_f32_16x16x32_bf16 v[20:23], v[162:165], v[192:195], v[20:23]
	v_mfma_f32_16x16x32_bf16 v[16:19], v[176:179], v[192:195], v[16:19]
	v_mfma_f32_16x16x32_bf16 v[12:15], v[162:165], v[200:203], v[12:15]
	v_mfma_f32_16x16x32_bf16 v[8:11], v[176:179], v[200:203], v[8:11]
	v_mfma_f32_16x16x32_bf16 v[4:7], v[162:165], v[208:211], v[4:7]
	v_mfma_f32_16x16x32_bf16 v[0:3], v[176:179], v[208:211], v[0:3]
	s_setprio 0
	s_barrier
	s_cbranch_scc0 .LBB0_2061

; #define PG8_STAGE(bufoff, gbase, voff) do { _Pragma("unroll") for (int _i = 0; _i < 2; ++_i) \
;         __builtin_amdgcn_global_load_lds((const unsigned*)((const char*)(gbase) + (voff)[_i]), (PG8_LAS unsigned*)(lds + (bufoff) + ldsw + _i * 8192), 16, 0, 0); } while (0)
; #define PG8_LDA(dst, b, h) do { _Pragma("unroll") for (int m = 0; m < 4; ++m) _Pragma("unroll") for (int k = 0; k < 2; ++k) dst[m][k] = *(const PG8_LAS bf16x8*)(lds + PG8_SA(b, h) + aoff + m * 2048 + k * 1024); } while (0)
; #define PG8_LDB(dst, b, h) do { _Pragma("unroll") for (int n = 0; n < 2; ++n) _Pragma("unroll") for (int k = 0; k < 2; ++k) dst[n][k] = *(const PG8_LAS bf16x8*)(lds + PG8_SB(b, h) + boff + n * 2048 + k * 1024); } while (0)
; #define PG8_MMA(ai, bj, At, Bt) do { __builtin_amdgcn_s_setprio(1); _Pragma("unroll") for (int m = 0; m < 4; ++m) _Pragma("unroll") for (int n = 0; n < 2; ++n) _Pragma("unroll") for (int k = 0; k < 2; ++k) \
;         acc[ai][bj][m][n] = __builtin_amdgcn_mfma_f32_16x16x32_bf16(Bt[n][k], At[m][k], acc[ai][bj][m][n], 0, 0, 0); __builtin_amdgcn_s_setprio(0); } while (0)
; #define PG8_WAIT_V(n) asm volatile("s_waitcnt vmcnt(" #n ")" ::: "memory")
; #define PG8_WAIT_L(n) asm volatile("s_waitcnt lgkmcnt(" #n ")" ::: "memory")
; #define PG8_BAR __builtin_amdgcn_s_barrier()
; #define PG8_SCHED __builtin_amdgcn_sched_barrier(0)
; template <class Epi, class Sched, bool ALIGN_EPI = false, bool SP2 = false>
; __device__ __forceinline__ void gemm_phase(PG8_LAS unsigned char* lds, const Gemm g, const Sched& S, const Epi& E, const int wid) {
;     ...
;             const bool last = (t == nt - 2);
;             const char* a1 = cA + (size_t)(t + 1) * kstep;
;             const char* a2 = last ? nA : cA + (size_t)(t + 2) * kstep; const char* b2 = last ? nB : cB + (size_t)(t + 2) * kstep;
;             const char* a3 = a2 + kstep; const char* b3 = b2 + kstep;
;             if (last && has_next) S.a_ready(nxt);
;             if constexpr (SP2) {
;             PG8_LDB(B0, 0, 0); PG8_LDB(B1, 0, 1); PG8_SCHED; PG8_LDA(At, 0, 0); PG8_STAGE(PG8_SA(1, 1), a1 + hstep, voffA);
;             PG8_WAIT_V(8); PG8_WAIT_L(0); PG8_BAR; PG8_MMA(0, 0, At, B0); PG8_MMA(0, 1, At, B1); PG8_BAR; PG8_SCHED;
;             PG8_LDA(At, 0, 1); PG8_STAGE(PG8_SB(0, 0), b2, voffB); PG8_STAGE(PG8_SB(0, 1), b2 + hstep, voffB); PG8_STAGE(PG8_SA(0, 0), a2, voffA);
.LBB0_2604:
	ds_read_b128 v[164:167], v195
	ds_read_b128 v[184:187], v195 offset:1024
	ds_read_b128 v[188:191], v195 offset:2048
	ds_read_b128 v[196:199], v195 offset:3072
	ds_read_b128 v[200:203], v195 offset:4096
	ds_read_b128 v[204:207], v195 offset:5120
	ds_read_b128 v[208:211], v195 offset:6144
	ds_read_b128 v[212:215], v195 offset:7168
	v_add_u32_e32 v0, s47, v194
	ds_read_b128 v[60:63], v0
	ds_read_b128 v[64:67], v0 offset:1024
	ds_read_b128 v[84:87], v0 offset:2048
	ds_read_b128 v[88:91], v0 offset:3072
	v_add_u32_e32 v0, s48, v194
	ds_read_b128 v[116:119], v0
	ds_read_b128 v[120:123], v0 offset:1024
	ds_read_b128 v[140:143], v0 offset:2048
	ds_read_b128 v[144:147], v0 offset:3072
	s_add_u32 s26, s24, 0xfff80080
	s_addc_u32 s27, s25, -1
	s_cmp_eq_u32 s52, 28
	s_cselect_b32 s29, s7, s27
	s_cselect_b32 s28, s19, s26
	s_cselect_b32 s27, s17, s51
	s_cselect_b32 s26, s49, s50
	v_lshl_add_u64 v[2:3], s[24:25], 0, v[176:177]
	s_add_i32 m0, s13, 0xc000
	s_nop 0
	global_load_lds_dwordx4 v[2:3], off
	v_lshl_add_u64 v[2:3], s[24:25], 0, v[178:179]
	s_add_i32 m0, s13, 0xe000
	s_nop 0
	global_load_lds_dwordx4 v[2:3], off
	s_waitcnt vmcnt(8)
	s_waitcnt lgkmcnt(0)
	s_barrier
	s_setprio 1
	s_waitcnt lgkmcnt(0)
	v_mfma_f32_16x16x32_bf16 v[80:83], v[60:63], v[164:167], v[80:83]
	v_mfma_f32_16x16x32_bf16 v[76:79], v[84:87], v[164:167], v[76:79]
	v_mfma_f32_16x16x32_bf16 v[104:107], v[60:63], v[188:191], v[104:107]
	v_mfma_f32_16x16x32_bf16 v[100:103], v[84:87], v[188:191], v[100:103]
	v_mfma_f32_16x16x32_bf16 v[136:139], v[60:63], v[200:203], v[136:139]
	v_mfma_f32_16x16x32_bf16 v[132:135], v[84:87], v[200:203], v[132:135]
	v_mfma_f32_16x16x32_bf16 v[112:115], v[60:63], v[208:211], v[112:115]
	v_mfma_f32_16x16x32_bf16 v[108:111], v[84:87], v[208:211], v[108:111]
	v_mfma_f32_16x16x32_bf16 v[80:83], v[64:67], v[184:187], v[80:83]
	v_mfma_f32_16x16x32_bf16 v[76:79], v[88:91], v[184:187], v[76:79]
	v_mfma_f32_16x16x32_bf16 v[104:107], v[64:67], v[196:199], v[104:107]
	v_mfma_f32_16x16x32_bf16 v[100:103], v[88:91], v[196:199], v[100:103]
	v_mfma_f32_16x16x32_bf16 v[136:139], v[64:67], v[204:207], v[136:139]
	v_mfma_f32_16x16x32_bf16 v[132:135], v[88:91], v[204:207], v[132:135]
	v_mfma_f32_16x16x32_bf16 v[112:115], v[64:67], v[212:215], v[112:115]
	v_mfma_f32_16x16x32_bf16 v[108:111], v[88:91], v[212:215], v[108:111]
	s_setprio 0
	s_setprio 1
	v_mfma_f32_16x16x32_bf16 v[160:163], v[116:119], v[164:167], v[160:163]
	v_mfma_f32_16x16x32_bf16 v[156:159], v[140:143], v[164:167], v[156:159]
	v_mfma_f32_16x16x32_bf16 v[152:155], v[116:119], v[188:191], v[152:155]
	v_mfma_f32_16x16x32_bf16 v[148:151], v[140:143], v[188:191], v[148:151]
	v_mfma_f32_16x16x32_bf16 v[128:131], v[116:119], v[200:203], v[128:131]
	v_mfma_f32_16x16x32_bf16 v[124:127], v[140:143], v[200:203], v[124:127]
	v_mfma_f32_16x16x32_bf16 v[96:99], v[116:119], v[208:211], v[96:99]
	v_mfma_f32_16x16x32_bf16 v[92:95], v[140:143], v[208:211], v[92:95]
	v_mfma_f32_16x16x32_bf16 v[160:163], v[120:123], v[184:187], v[160:163]
	v_mfma_f32_16x16x32_bf16 v[156:159], v[144:147], v[184:187], v[156:159]
	v_mfma_f32_16x16x32_bf16 v[152:155], v[120:123], v[196:199], v[152:155]
	v_mfma_f32_16x16x32_bf16 v[148:151], v[144:147], v[196:199], v[148:151]
	v_mfma_f32_16x16x32_bf16 v[128:131], v[120:123], v[204:207], v[128:131]
	v_mfma_f32_16x16x32_bf16 v[124:127], v[144:147], v[204:207], v[124:127]
	v_mfma_f32_16x16x32_bf16 v[96:99], v[120:123], v[212:215], v[96:99]
	v_mfma_f32_16x16x32_bf16 v[92:95], v[144:147], v[212:215], v[92:95]
	s_setprio 0
	s_barrier
	ds_read_b128 v[164:167], v195 offset:16384
	ds_read_b128 v[184:187], v195 offset:17408
	ds_read_b128 v[188:191], v195 offset:18432
	ds_read_b128 v[196:199], v195 offset:19456
	ds_read_b128 v[200:203], v195 offset:20480
	ds_read_b128 v[204:207], v195 offset:21504
	ds_read_b128 v[208:211], v195 offset:22528
	ds_read_b128 v[212:215], v195 offset:23552
	s_add_i32 s53, s47, s35
	v_lshl_add_u64 v[192:193], s[26:27], 0, v[170:171]
	s_mov_b32 m0, s53
	s_nop 0
	global_load_lds_dwordx4 v[192:193], off
	s_add_i32 m0, s53, 0x2000
	s_add_u32 s54, s26, 0x80000
	v_lshl_add_u64 v[216:217], s[26:27], 0, v[174:175]
	s_addc_u32 s55, s27, 0
	s_add_i32 s53, s48, s35
	global_load_lds_dwordx4 v[216:217], off
	v_lshl_add_u64 v[2:3], s[54:55], 0, v[170:171]
	s_mov_b32 m0, s53
	v_lshl_add_u64 v[218:219], s[28:29], 0, v[168:169]
	global_load_lds_dwordx4 v[2:3], off
	v_lshl_add_u64 v[2:3], s[54:55], 0, v[174:175]
	s_add_i32 m0, s53, 0x2000
	v_lshl_add_u64 v[220:221], s[28:29], 0, v[172:173]
	global_load_lds_dwordx4 v[2:3], off
	s_mov_b32 m0, s13
	s_nop 0
	global_load_lds_dwordx4 v[218:219], off
	s_mov_b32 m0, s36
	s_nop 0
	global_load_lds_dwordx4 v[220:221], off
	s_waitcnt vmcnt(8)
	s_waitcnt lgkmcnt(0)
	s_barrier
; #define PG8_STAGE(bufoff, gbase, voff) do { _Pragma("unroll") for (int _i = 0; _i < 2; ++_i) \
;         __builtin_amdgcn_global_load_lds((const unsigned*)((const char*)(gbase) + (voff)[_i]), (PG8_LAS unsigned*)(lds + (bufoff) + ldsw + _i * 8192), 16, 0, 0); } while (0)
; #define PG8_LDA(dst, b, h) do { _Pragma("unroll") for (int m = 0; m < 4; ++m) _Pragma("unroll") for (int k = 0; k < 2; ++k) dst[m][k] = *(const PG8_LAS bf16x8*)(lds + PG8_SA(b, h) + aoff + m * 2048 + k * 1024); } while (0)
; #define PG8_LDB(dst, b, h) do { _Pragma("unroll") for (int n = 0; n < 2; ++n) _Pragma("unroll") for (int k = 0; k < 2; ++k) dst[n][k] = *(const PG8_LAS bf16x8*)(lds + PG8_SB(b, h) + boff + n * 2048 + k * 1024); } while (0)
; #define PG8_MMA(ai, bj, At, Bt) do { __builtin_amdgcn_s_setprio(1); _Pragma("unroll") for (int m = 0; m < 4; ++m) _Pragma("unroll") for (int n = 0; n < 2; ++n) _Pragma("unroll") for (int k = 0; k < 2; ++k) \
;         acc[ai][bj][m][n] = __builtin_amdgcn_mfma_f32_16x16x32_bf16(Bt[n][k], At[m][k], acc[ai][bj][m][n], 0, 0, 0); __builtin_amdgcn_s_setprio(0); } while (0)
; #define PG8_WAIT_V(n) asm volatile("s_waitcnt vmcnt(" #n ")" ::: "memory")
; #define PG8_WAIT_L(n) asm volatile("s_waitcnt lgkmcnt(" #n ")" ::: "memory")
; #define PG8_BAR __builtin_amdgcn_s_barrier()
; #define PG8_SCHED __builtin_amdgcn_sched_barrier(0)
; template <class Epi, class Sched, bool ALIGN_EPI = false, bool SP2 = false>
; __device__ __forceinline__ void gemm_phase(PG8_LAS unsigned char* lds, const Gemm g, const Sched& S, const Epi& E, const int wid) {
;     ...
;             PG8_WAIT_V(8); PG8_WAIT_L(0); PG8_BAR; PG8_MMA(1, 0, At, B0); PG8_MMA(1, 1, At, B1); PG8_BAR; PG8_SCHED;
;             PG8_LDB(B0, 1, 0); PG8_LDB(B1, 1, 1); PG8_SCHED; PG8_LDA(At, 1, 0); PG8_STAGE(PG8_SA(0, 1), a2 + hstep, voffA);
;             PG8_WAIT_V(8); PG8_WAIT_L(0); PG8_BAR; PG8_MMA(0, 0, At, B0); PG8_MMA(0, 1, At, B1); PG8_BAR; PG8_SCHED;
	s_setprio 1
	s_waitcnt lgkmcnt(0)
	v_mfma_f32_16x16x32_bf16 v[72:75], v[60:63], v[164:167], v[72:75]
	v_mfma_f32_16x16x32_bf16 v[68:71], v[84:87], v[164:167], v[68:71]
	v_mfma_f32_16x16x32_bf16 v[48:51], v[60:63], v[188:191], v[48:51]
	v_mfma_f32_16x16x32_bf16 v[44:47], v[84:87], v[188:191], v[44:47]
	v_mfma_f32_16x16x32_bf16 v[32:35], v[60:63], v[200:203], v[32:35]
	v_mfma_f32_16x16x32_bf16 v[28:31], v[84:87], v[200:203], v[28:31]
	v_mfma_f32_16x16x32_bf16 v[16:19], v[60:63], v[208:211], v[16:19]
	v_mfma_f32_16x16x32_bf16 v[12:15], v[84:87], v[208:211], v[12:15]
	v_mfma_f32_16x16x32_bf16 v[72:75], v[64:67], v[184:187], v[72:75]
	v_mfma_f32_16x16x32_bf16 v[68:71], v[88:91], v[184:187], v[68:71]
	v_mfma_f32_16x16x32_bf16 v[48:51], v[64:67], v[196:199], v[48:51]
	v_mfma_f32_16x16x32_bf16 v[44:47], v[88:91], v[196:199], v[44:47]
	v_mfma_f32_16x16x32_bf16 v[32:35], v[64:67], v[204:207], v[32:35]
	v_mfma_f32_16x16x32_bf16 v[28:31], v[88:91], v[204:207], v[28:31]
	v_mfma_f32_16x16x32_bf16 v[16:19], v[64:67], v[212:215], v[16:19]
	v_mfma_f32_16x16x32_bf16 v[12:15], v[88:91], v[212:215], v[12:15]
	s_setprio 0
	s_setprio 1
	v_mfma_f32_16x16x32_bf16 v[56:59], v[116:119], v[164:167], v[56:59]
	v_mfma_f32_16x16x32_bf16 v[52:55], v[140:143], v[164:167], v[52:55]
	v_mfma_f32_16x16x32_bf16 v[40:43], v[116:119], v[188:191], v[40:43]
	v_mfma_f32_16x16x32_bf16 v[36:39], v[140:143], v[188:191], v[36:39]
	v_mfma_f32_16x16x32_bf16 v[24:27], v[116:119], v[200:203], v[24:27]
	v_mfma_f32_16x16x32_bf16 v[20:23], v[140:143], v[200:203], v[20:23]
	v_mfma_f32_16x16x32_bf16 v[8:11], v[116:119], v[208:211], v[8:11]
	v_mfma_f32_16x16x32_bf16 v[2:5], v[140:143], v[208:211], v[4:7]
	v_mfma_f32_16x16x32_bf16 v[56:59], v[120:123], v[184:187], v[56:59]
	v_mfma_f32_16x16x32_bf16 v[52:55], v[144:147], v[184:187], v[52:55]
	v_mfma_f32_16x16x32_bf16 v[40:43], v[120:123], v[196:199], v[40:43]
	v_mfma_f32_16x16x32_bf16 v[36:39], v[144:147], v[196:199], v[36:39]
	v_mfma_f32_16x16x32_bf16 v[24:27], v[120:123], v[204:207], v[24:27]
	v_mfma_f32_16x16x32_bf16 v[20:23], v[144:147], v[204:207], v[20:23]
	v_mfma_f32_16x16x32_bf16 v[8:11], v[120:123], v[212:215], v[8:11]
	v_mfma_f32_16x16x32_bf16 v[2:5], v[144:147], v[212:215], v[2:5]
	s_setprio 0
	s_barrier
	ds_read_b128 v[164:167], v195 offset:32768
	ds_read_b128 v[184:187], v195 offset:33792
	ds_read_b128 v[188:191], v195 offset:34816
	ds_read_b128 v[196:199], v195 offset:35840
	ds_read_b128 v[200:203], v195 offset:36864
	ds_read_b128 v[204:207], v195 offset:37888
	ds_read_b128 v[208:211], v195 offset:38912
	ds_read_b128 v[212:215], v195 offset:39936
	s_add_i32 s53, 0, 0x18000
	v_add_u32_e32 v0, s53, v194
	s_add_i32 s54, 0, 0x1c000
	ds_read_b128 v[60:63], v0
	ds_read_b128 v[64:67], v0 offset:1024
	ds_read_b128 v[84:87], v0 offset:2048
	ds_read_b128 v[88:91], v0 offset:3072
	v_add_u32_e32 v0, s54, v194
	ds_read_b128 v[116:119], v0
	ds_read_b128 v[120:123], v0 offset:1024
	ds_read_b128 v[140:143], v0 offset:2048
	ds_read_b128 v[144:147], v0 offset:3072
	s_add_u32 s28, s28, 0x80000
	s_addc_u32 s29, s29, 0
	s_mov_b32 m0, s37
	v_lshl_add_u64 v[6:7], s[28:29], 0, v[168:169]
	global_load_lds_dwordx4 v[6:7], off
	v_lshl_add_u64 v[6:7], s[28:29], 0, v[172:173]
	s_mov_b32 m0, s38
	s_nop 0
	global_load_lds_dwordx4 v[6:7], off
	s_waitcnt vmcnt(8)
	s_waitcnt lgkmcnt(0)
	s_barrier
	s_setprio 1
	s_waitcnt lgkmcnt(0)
	v_mfma_f32_16x16x32_bf16 v[80:83], v[60:63], v[164:167], v[80:83]
	v_mfma_f32_16x16x32_bf16 v[76:79], v[84:87], v[164:167], v[76:79]
	v_mfma_f32_16x16x32_bf16 v[104:107], v[60:63], v[188:191], v[104:107]
	v_mfma_f32_16x16x32_bf16 v[100:103], v[84:87], v[188:191], v[100:103]
	v_mfma_f32_16x16x32_bf16 v[136:139], v[60:63], v[200:203], v[136:139]
	v_mfma_f32_16x16x32_bf16 v[132:135], v[84:87], v[200:203], v[132:135]
	v_mfma_f32_16x16x32_bf16 v[112:115], v[60:63], v[208:211], v[112:115]
	v_mfma_f32_16x16x32_bf16 v[108:111], v[84:87], v[208:211], v[108:111]
	v_mfma_f32_16x16x32_bf16 v[80:83], v[64:67], v[184:187], v[80:83]
	v_mfma_f32_16x16x32_bf16 v[76:79], v[88:91], v[184:187], v[76:79]
	v_mfma_f32_16x16x32_bf16 v[104:107], v[64:67], v[196:199], v[104:107]
	v_mfma_f32_16x16x32_bf16 v[100:103], v[88:91], v[196:199], v[100:103]
	v_mfma_f32_16x16x32_bf16 v[136:139], v[64:67], v[204:207], v[136:139]
	v_mfma_f32_16x16x32_bf16 v[132:135], v[88:91], v[204:207], v[132:135]
	v_mfma_f32_16x16x32_bf16 v[112:115], v[64:67], v[212:215], v[112:115]
	v_mfma_f32_16x16x32_bf16 v[108:111], v[88:91], v[212:215], v[108:111]
	s_setprio 0
	s_setprio 1
	v_mfma_f32_16x16x32_bf16 v[160:163], v[116:119], v[164:167], v[160:163]
	v_mfma_f32_16x16x32_bf16 v[156:159], v[140:143], v[164:167], v[156:159]
	v_mfma_f32_16x16x32_bf16 v[152:155], v[116:119], v[188:191], v[152:155]
	v_mfma_f32_16x16x32_bf16 v[148:151], v[140:143], v[188:191], v[148:151]
	v_mfma_f32_16x16x32_bf16 v[128:131], v[116:119], v[200:203], v[128:131]
	v_mfma_f32_16x16x32_bf16 v[124:127], v[140:143], v[200:203], v[124:127]
	v_mfma_f32_16x16x32_bf16 v[96:99], v[116:119], v[208:211], v[96:99]
	v_mfma_f32_16x16x32_bf16 v[92:95], v[140:143], v[208:211], v[92:95]
	v_mfma_f32_16x16x32_bf16 v[160:163], v[120:123], v[184:187], v[160:163]
	v_mfma_f32_16x16x32_bf16 v[156:159], v[144:147], v[184:187], v[156:159]
	v_mfma_f32_16x16x32_bf16 v[152:155], v[120:123], v[196:199], v[152:155]
	v_mfma_f32_16x16x32_bf16 v[148:151], v[144:147], v[196:199], v[148:151]
	v_mfma_f32_16x16x32_bf16 v[128:131], v[120:123], v[204:207], v[128:131]
	v_mfma_f32_16x16x32_bf16 v[124:127], v[144:147], v[204:207], v[124:127]
	v_mfma_f32_16x16x32_bf16 v[96:99], v[120:123], v[212:215], v[96:99]
	v_mfma_f32_16x16x32_bf16 v[92:95], v[144:147], v[212:215], v[92:95]
	s_setprio 0
	s_barrier
; #define PG8_STAGE(bufoff, gbase, voff) do { _Pragma("unroll") for (int _i = 0; _i < 2; ++_i) \
;         __builtin_amdgcn_global_load_lds((const unsigned*)((const char*)(gbase) + (voff)[_i]), (PG8_LAS unsigned*)(lds + (bufoff) + ldsw + _i * 8192), 16, 0, 0); } while (0)
; #define PG8_LDA(dst, b, h) do { _Pragma("unroll") for (int m = 0; m < 4; ++m) _Pragma("unroll") for (int k = 0; k < 2; ++k) dst[m][k] = *(const PG8_LAS bf16x8*)(lds + PG8_SA(b, h) + aoff + m * 2048 + k * 1024); } while (0)
; #define PG8_MMA(ai, bj, At, Bt) do { __builtin_amdgcn_s_setprio(1); _Pragma("unroll") for (int m = 0; m < 4; ++m) _Pragma("unroll") for (int n = 0; n < 2; ++n) _Pragma("unroll") for (int k = 0; k < 2; ++k) \
;         acc[ai][bj][m][n] = __builtin_amdgcn_mfma_f32_16x16x32_bf16(Bt[n][k], At[m][k], acc[ai][bj][m][n], 0, 0, 0); __builtin_amdgcn_s_setprio(0); } while (0)
; #define PG8_WAIT_V(n) asm volatile("s_waitcnt vmcnt(" #n ")" ::: "memory")
; #define PG8_WAIT_L(n) asm volatile("s_waitcnt lgkmcnt(" #n ")" ::: "memory")
; #define PG8_BAR __builtin_amdgcn_s_barrier()
; #define PG8_SCHED __builtin_amdgcn_sched_barrier(0)
; template <class Epi, class Sched, bool ALIGN_EPI = false, bool SP2 = false>
; __device__ __forceinline__ void gemm_phase(PG8_LAS unsigned char* lds, const Gemm g, const Sched& S, const Epi& E, const int wid) {
;     ...
;         for (int t = 0; t < nt; t += 2) {
;             const bool last = (t == nt - 2);
;             const char* a1 = cA + (size_t)(t + 1) * kstep;
;             const char* a2 = last ? nA : cA + (size_t)(t + 2) * kstep; const char* b2 = last ? nB : cB + (size_t)(t + 2) * kstep;
;     ...
;             PG8_LDA(At, 1, 1); PG8_STAGE(PG8_SB(1, 0), b3, voffB); PG8_STAGE(PG8_SB(1, 1), b3 + hstep, voffB); PG8_STAGE(PG8_SA(1, 0), a3, voffA);
;             PG8_WAIT_V(8); PG8_WAIT_L(0); PG8_BAR; PG8_MMA(1, 0, At, B0); PG8_MMA(1, 1, At, B1); PG8_BAR; PG8_SCHED;
;     ...
;         if constexpr (ALIGN_EPI) { if (wr == 0) PG8_BAR; }
	ds_read_b128 v[164:167], v195 offset:49152
	ds_read_b128 v[184:187], v195 offset:50176
	ds_read_b128 v[188:191], v195 offset:51200
	ds_read_b128 v[196:199], v195 offset:52224
	ds_read_b128 v[200:203], v195 offset:53248
	ds_read_b128 v[204:207], v195 offset:54272
	ds_read_b128 v[208:211], v195 offset:55296
	ds_read_b128 v[212:215], v195 offset:56320
	s_add_i32 s28, s53, s35
	v_lshl_add_u64 v[6:7], v[192:193], 0, s[10:11]
	s_mov_b32 m0, s28
	s_nop 0
	global_load_lds_dwordx4 v[6:7], off
	s_add_i32 m0, s28, 0x2000
	s_add_u32 s26, s26, 0x80080
	v_lshl_add_u64 v[6:7], v[216:217], 0, s[10:11]
	s_addc_u32 s27, s27, 0
	s_add_i32 s28, s54, s35
	global_load_lds_dwordx4 v[6:7], off
	v_lshl_add_u64 v[6:7], s[26:27], 0, v[170:171]
	s_mov_b32 m0, s28
	s_nop 0
	global_load_lds_dwordx4 v[6:7], off
	v_lshl_add_u64 v[6:7], s[26:27], 0, v[174:175]
	s_add_i32 m0, s28, 0x2000
	s_nop 0
	global_load_lds_dwordx4 v[6:7], off
	v_lshl_add_u64 v[6:7], v[218:219], 0, s[10:11]
	s_mov_b32 m0, s43
	s_nop 0
	global_load_lds_dwordx4 v[6:7], off
	v_lshl_add_u64 v[6:7], v[220:221], 0, s[10:11]
	s_mov_b32 m0, s44
	s_nop 0
	global_load_lds_dwordx4 v[6:7], off
	s_waitcnt vmcnt(8)
	s_waitcnt lgkmcnt(0)
	s_barrier
	s_setprio 1
	s_waitcnt lgkmcnt(0)
	v_mfma_f32_16x16x32_bf16 v[72:75], v[60:63], v[164:167], v[72:75]
	v_mfma_f32_16x16x32_bf16 v[68:71], v[84:87], v[164:167], v[68:71]
	v_mfma_f32_16x16x32_bf16 v[48:51], v[60:63], v[188:191], v[48:51]
	v_mfma_f32_16x16x32_bf16 v[44:47], v[84:87], v[188:191], v[44:47]
	v_mfma_f32_16x16x32_bf16 v[32:35], v[60:63], v[200:203], v[32:35]
	v_mfma_f32_16x16x32_bf16 v[28:31], v[84:87], v[200:203], v[28:31]
	v_mfma_f32_16x16x32_bf16 v[16:19], v[60:63], v[208:211], v[16:19]
	v_mfma_f32_16x16x32_bf16 v[12:15], v[84:87], v[208:211], v[12:15]
	v_mfma_f32_16x16x32_bf16 v[72:75], v[64:67], v[184:187], v[72:75]
	v_mfma_f32_16x16x32_bf16 v[68:71], v[88:91], v[184:187], v[68:71]
	v_mfma_f32_16x16x32_bf16 v[48:51], v[64:67], v[196:199], v[48:51]
	v_mfma_f32_16x16x32_bf16 v[44:47], v[88:91], v[196:199], v[44:47]
	v_mfma_f32_16x16x32_bf16 v[32:35], v[64:67], v[204:207], v[32:35]
	v_mfma_f32_16x16x32_bf16 v[28:31], v[88:91], v[204:207], v[28:31]
	v_mfma_f32_16x16x32_bf16 v[16:19], v[64:67], v[212:215], v[16:19]
	v_mfma_f32_16x16x32_bf16 v[12:15], v[88:91], v[212:215], v[12:15]
	s_setprio 0
	s_setprio 1
	v_mfma_f32_16x16x32_bf16 v[56:59], v[116:119], v[164:167], v[56:59]
	v_mfma_f32_16x16x32_bf16 v[52:55], v[140:143], v[164:167], v[52:55]
	v_mfma_f32_16x16x32_bf16 v[40:43], v[116:119], v[188:191], v[40:43]
	v_mfma_f32_16x16x32_bf16 v[36:39], v[140:143], v[188:191], v[36:39]
	s_add_i32 s52, s52, 2
	s_add_u32 s24, s24, 0x100
	s_addc_u32 s25, s25, 0
	s_add_u32 s50, s50, 0x100
	s_addc_u32 s51, s51, 0
	s_cmp_gt_u32 s52, 29
	v_mfma_f32_16x16x32_bf16 v[24:27], v[116:119], v[200:203], v[24:27]
	v_mfma_f32_16x16x32_bf16 v[20:23], v[140:143], v[200:203], v[20:23]
	v_mfma_f32_16x16x32_bf16 v[6:9], v[116:119], v[208:211], v[8:11]
	v_mfma_f32_16x16x32_bf16 v[2:5], v[140:143], v[208:211], v[2:5]
	v_mfma_f32_16x16x32_bf16 v[56:59], v[120:123], v[184:187], v[56:59]
	v_mfma_f32_16x16x32_bf16 v[52:55], v[144:147], v[184:187], v[52:55]
	v_mfma_f32_16x16x32_bf16 v[40:43], v[120:123], v[196:199], v[40:43]
	v_mfma_f32_16x16x32_bf16 v[36:39], v[144:147], v[196:199], v[36:39]
	v_mfma_f32_16x16x32_bf16 v[24:27], v[120:123], v[204:207], v[24:27]
	v_mfma_f32_16x16x32_bf16 v[20:23], v[144:147], v[204:207], v[20:23]
	v_mfma_f32_16x16x32_bf16 v[8:11], v[120:123], v[212:215], v[6:9]
	v_mfma_f32_16x16x32_bf16 v[4:7], v[144:147], v[212:215], v[2:5]
	s_setprio 0
	s_barrier
	s_cbranch_scc0 .LBB0_2604
	s_and_b64 vcc, exec, s[14:15]
	s_cbranch_vccz .LBB0_2607
	s_barrier

; #define PG8_STAGE(bufoff, gbase, voff) do { _Pragma("unroll") for (int _i = 0; _i < 2; ++_i) \
;         __builtin_amdgcn_global_load_lds((const unsigned*)((const char*)(gbase) + (voff)[_i]), (PG8_LAS unsigned*)(lds + (bufoff) + ldsw + _i * 8192), 16, 0, 0); } while (0)
; #define PG8_LDA(dst, b, h) do { _Pragma("unroll") for (int m = 0; m < 4; ++m) _Pragma("unroll") for (int k = 0; k < 2; ++k) dst[m][k] = *(const PG8_LAS bf16x8*)(lds + PG8_SA(b, h) + aoff + m * 2048 + k * 1024); } while (0)
; #define PG8_LDB(dst, b, h) do { _Pragma("unroll") for (int n = 0; n < 2; ++n) _Pragma("unroll") for (int k = 0; k < 2; ++k) dst[n][k] = *(const PG8_LAS bf16x8*)(lds + PG8_SB(b, h) + boff + n * 2048 + k * 1024); } while (0)
; #define PG8_MMA(ai, bj, At, Bt) do { __builtin_amdgcn_s_setprio(1); _Pragma("unroll") for (int m = 0; m < 4; ++m) _Pragma("unroll") for (int n = 0; n < 2; ++n) _Pragma("unroll") for (int k = 0; k < 2; ++k) \
;         acc[ai][bj][m][n] = __builtin_amdgcn_mfma_f32_16x16x32_bf16(Bt[n][k], At[m][k], acc[ai][bj][m][n], 0, 0, 0); __builtin_amdgcn_s_setprio(0); } while (0)
; #define PG8_WAIT_V(n) asm volatile("s_waitcnt vmcnt(" #n ")" ::: "memory")
; #define PG8_WAIT_L(n) asm volatile("s_waitcnt lgkmcnt(" #n ")" ::: "memory")
; #define PG8_BAR __builtin_amdgcn_s_barrier()
; #define PG8_SCHED __builtin_amdgcn_sched_barrier(0)
; template <class Epi, class Sched, bool ALIGN_EPI = false, bool SP2 = false>
; __device__ __forceinline__ void gemm_phase(PG8_LAS unsigned char* lds, const Gemm g, const Sched& S, const Epi& E, const int wid) {
;     ...
;             const bool last = (t == nt - 2);
;             const char* a1 = cA + (size_t)(t + 1) * kstep;
;             const char* a2 = last ? nA : cA + (size_t)(t + 2) * kstep; const char* b2 = last ? nB : cB + (size_t)(t + 2) * kstep;
;             const char* a3 = a2 + kstep; const char* b3 = b2 + kstep;
;             if (last && has_next) S.a_ready(nxt);
;             if constexpr (SP2) {
;             PG8_LDB(B0, 0, 0); PG8_LDB(B1, 0, 1); PG8_SCHED; PG8_LDA(At, 0, 0); PG8_STAGE(PG8_SA(1, 1), a1 + hstep, voffA);
;             PG8_WAIT_V(8); PG8_WAIT_L(0); PG8_BAR; PG8_MMA(0, 0, At, B0); PG8_MMA(0, 1, At, B1); PG8_BAR; PG8_SCHED;
;             PG8_LDA(At, 0, 1); PG8_STAGE(PG8_SB(0, 0), b2, voffB); PG8_STAGE(PG8_SB(0, 1), b2 + hstep, voffB); PG8_STAGE(PG8_SA(0, 0), a2, voffA);
.LBB0_2717:
	ds_read_b128 v[128:131], v187
	ds_read_b128 v[132:135], v187 offset:1024
	ds_read_b128 v[136:139], v187 offset:2048
	ds_read_b128 v[140:143], v187 offset:3072
	ds_read_b128 v[144:147], v188
	ds_read_b128 v[148:151], v188 offset:1024
	ds_read_b128 v[168:171], v188 offset:2048
	ds_read_b128 v[172:175], v188 offset:3072
	ds_read_b128 v[176:179], v189
	ds_read_b128 v[180:183], v189 offset:1024
	ds_read_b128 v[192:195], v189 offset:2048
	ds_read_b128 v[196:199], v189 offset:3072
	ds_read_b128 v[200:203], v189 offset:4096
	ds_read_b128 v[204:207], v189 offset:5120
	ds_read_b128 v[208:211], v189 offset:6144
	ds_read_b128 v[212:215], v189 offset:7168
	s_add_u32 s30, s28, 0xfff00080
	s_addc_u32 s31, s29, -1
	s_cmp_eq_u32 s55, 60
	s_cselect_b32 s35, s1, s31
	s_cselect_b32 s34, s21, s30
	s_cselect_b32 s31, s19, s54
	s_cselect_b32 s30, s52, s53
	v_lshl_add_u64 v[184:185], s[28:29], 0, v[160:161]
	s_add_i32 m0, s27, 0xc000
	s_nop 0
	global_load_lds_dwordx4 v[184:185], off
	v_lshl_add_u64 v[184:185], s[28:29], 0, v[162:163]
	s_add_i32 m0, s27, 0xe000
	s_nop 0
	global_load_lds_dwordx4 v[184:185], off
	s_waitcnt vmcnt(8)
	s_waitcnt lgkmcnt(0)
	s_barrier
	s_setprio 1
	s_waitcnt lgkmcnt(0)
	v_mfma_f32_16x16x32_bf16 v[124:127], v[128:131], v[176:179], v[124:127]
	v_mfma_f32_16x16x32_bf16 v[120:123], v[136:139], v[176:179], v[120:123]
	v_mfma_f32_16x16x32_bf16 v[108:111], v[128:131], v[192:195], v[108:111]
	v_mfma_f32_16x16x32_bf16 v[104:107], v[136:139], v[192:195], v[104:107]
	v_mfma_f32_16x16x32_bf16 v[92:95], v[128:131], v[200:203], v[92:95]
	v_mfma_f32_16x16x32_bf16 v[88:91], v[136:139], v[200:203], v[88:91]
	v_mfma_f32_16x16x32_bf16 v[76:79], v[128:131], v[208:211], v[76:79]
	v_mfma_f32_16x16x32_bf16 v[72:75], v[136:139], v[208:211], v[72:75]
	v_mfma_f32_16x16x32_bf16 v[124:127], v[132:135], v[180:183], v[124:127]
	v_mfma_f32_16x16x32_bf16 v[120:123], v[140:143], v[180:183], v[120:123]
	v_mfma_f32_16x16x32_bf16 v[108:111], v[132:135], v[196:199], v[108:111]
	v_mfma_f32_16x16x32_bf16 v[104:107], v[140:143], v[196:199], v[104:107]
	v_mfma_f32_16x16x32_bf16 v[92:95], v[132:135], v[204:207], v[92:95]
	v_mfma_f32_16x16x32_bf16 v[88:91], v[140:143], v[204:207], v[88:91]
	v_mfma_f32_16x16x32_bf16 v[76:79], v[132:135], v[212:215], v[76:79]
	v_mfma_f32_16x16x32_bf16 v[72:75], v[140:143], v[212:215], v[72:75]
	s_setprio 0
	s_setprio 1
	v_mfma_f32_16x16x32_bf16 v[116:119], v[144:147], v[176:179], v[116:119]
	v_mfma_f32_16x16x32_bf16 v[112:115], v[168:171], v[176:179], v[112:115]
	v_mfma_f32_16x16x32_bf16 v[100:103], v[144:147], v[192:195], v[100:103]
	v_mfma_f32_16x16x32_bf16 v[96:99], v[168:171], v[192:195], v[96:99]
	v_mfma_f32_16x16x32_bf16 v[84:87], v[144:147], v[200:203], v[84:87]
	v_mfma_f32_16x16x32_bf16 v[80:83], v[168:171], v[200:203], v[80:83]
	v_mfma_f32_16x16x32_bf16 v[68:71], v[144:147], v[208:211], v[68:71]
	v_mfma_f32_16x16x32_bf16 v[64:67], v[168:171], v[208:211], v[64:67]
	v_mfma_f32_16x16x32_bf16 v[116:119], v[148:151], v[180:183], v[116:119]
	v_mfma_f32_16x16x32_bf16 v[112:115], v[172:175], v[180:183], v[112:115]
	v_mfma_f32_16x16x32_bf16 v[100:103], v[148:151], v[196:199], v[100:103]
	v_mfma_f32_16x16x32_bf16 v[96:99], v[172:175], v[196:199], v[96:99]
	v_mfma_f32_16x16x32_bf16 v[84:87], v[148:151], v[204:207], v[84:87]
	v_mfma_f32_16x16x32_bf16 v[80:83], v[172:175], v[204:207], v[80:83]
	v_mfma_f32_16x16x32_bf16 v[68:71], v[148:151], v[212:215], v[68:71]
	v_mfma_f32_16x16x32_bf16 v[64:67], v[172:175], v[212:215], v[64:67]
	s_setprio 0
	s_barrier
	ds_read_b128 v[176:179], v189 offset:16384
	ds_read_b128 v[180:183], v189 offset:17408
	ds_read_b128 v[192:195], v189 offset:18432
	ds_read_b128 v[196:199], v189 offset:19456
	ds_read_b128 v[200:203], v189 offset:20480
	ds_read_b128 v[204:207], v189 offset:21504
	ds_read_b128 v[208:211], v189 offset:22528
	ds_read_b128 v[212:215], v189 offset:23552
	s_add_i32 s56, s50, s39
	v_lshl_add_u64 v[184:185], s[30:31], 0, v[154:155]
	s_mov_b32 m0, s56
	s_nop 0
	global_load_lds_dwordx4 v[184:185], off
	s_add_i32 m0, s56, 0x2000
	s_add_u32 s56, s30, 0x100000
	v_lshl_add_u64 v[216:217], s[30:31], 0, v[158:159]
	s_addc_u32 s57, s31, 0
	s_add_i32 s58, s51, s39
	global_load_lds_dwordx4 v[216:217], off
	v_lshl_add_u64 v[218:219], s[56:57], 0, v[154:155]
	s_mov_b32 m0, s58
	v_lshl_add_u64 v[220:221], s[34:35], 0, v[156:157]
	global_load_lds_dwordx4 v[218:219], off
	v_lshl_add_u64 v[218:219], s[56:57], 0, v[158:159]
	s_add_i32 m0, s58, 0x2000
	s_nop 0
	global_load_lds_dwordx4 v[218:219], off
	v_lshl_add_u64 v[218:219], s[34:35], 0, v[152:153]
	s_mov_b32 m0, s27
	s_nop 0
	global_load_lds_dwordx4 v[218:219], off
	s_mov_b32 m0, s40
	s_nop 0
	global_load_lds_dwordx4 v[220:221], off
	s_waitcnt vmcnt(8)
	s_waitcnt lgkmcnt(0)
	s_barrier
; #define PG8_STAGE(bufoff, gbase, voff) do { _Pragma("unroll") for (int _i = 0; _i < 2; ++_i) \
;         __builtin_amdgcn_global_load_lds((const unsigned*)((const char*)(gbase) + (voff)[_i]), (PG8_LAS unsigned*)(lds + (bufoff) + ldsw + _i * 8192), 16, 0, 0); } while (0)
; #define PG8_LDA(dst, b, h) do { _Pragma("unroll") for (int m = 0; m < 4; ++m) _Pragma("unroll") for (int k = 0; k < 2; ++k) dst[m][k] = *(const PG8_LAS bf16x8*)(lds + PG8_SA(b, h) + aoff + m * 2048 + k * 1024); } while (0)
; #define PG8_LDB(dst, b, h) do { _Pragma("unroll") for (int n = 0; n < 2; ++n) _Pragma("unroll") for (int k = 0; k < 2; ++k) dst[n][k] = *(const PG8_LAS bf16x8*)(lds + PG8_SB(b, h) + boff + n * 2048 + k * 1024); } while (0)
; #define PG8_MMA(ai, bj, At, Bt) do { __builtin_amdgcn_s_setprio(1); _Pragma("unroll") for (int m = 0; m < 4; ++m) _Pragma("unroll") for (int n = 0; n < 2; ++n) _Pragma("unroll") for (int k = 0; k < 2; ++k) \
;         acc[ai][bj][m][n] = __builtin_amdgcn_mfma_f32_16x16x32_bf16(Bt[n][k], At[m][k], acc[ai][bj][m][n], 0, 0, 0); __builtin_amdgcn_s_setprio(0); } while (0)
; #define PG8_WAIT_V(n) asm volatile("s_waitcnt vmcnt(" #n ")" ::: "memory")
; #define PG8_WAIT_L(n) asm volatile("s_waitcnt lgkmcnt(" #n ")" ::: "memory")
; #define PG8_BAR __builtin_amdgcn_s_barrier()
; #define PG8_SCHED __builtin_amdgcn_sched_barrier(0)
; template <class Epi, class Sched, bool ALIGN_EPI = false, bool SP2 = false>
; __device__ __forceinline__ void gemm_phase(PG8_LAS unsigned char* lds, const Gemm g, const Sched& S, const Epi& E, const int wid) {
;     ...
;             PG8_WAIT_V(8); PG8_WAIT_L(0); PG8_BAR; PG8_MMA(1, 0, At, B0); PG8_MMA(1, 1, At, B1); PG8_BAR; PG8_SCHED;
;             PG8_LDB(B0, 1, 0); PG8_LDB(B1, 1, 1); PG8_SCHED; PG8_LDA(At, 1, 0); PG8_STAGE(PG8_SA(0, 1), a2 + hstep, voffA);
;             PG8_WAIT_V(8); PG8_WAIT_L(0); PG8_BAR; PG8_MMA(0, 0, At, B0); PG8_MMA(0, 1, At, B1); PG8_BAR; PG8_SCHED;
	s_setprio 1
	s_waitcnt lgkmcnt(0)
	v_mfma_f32_16x16x32_bf16 v[60:63], v[128:131], v[176:179], v[60:63]
	v_mfma_f32_16x16x32_bf16 v[56:59], v[136:139], v[176:179], v[56:59]
	v_mfma_f32_16x16x32_bf16 v[44:47], v[128:131], v[192:195], v[44:47]
	v_mfma_f32_16x16x32_bf16 v[40:43], v[136:139], v[192:195], v[40:43]
	v_mfma_f32_16x16x32_bf16 v[28:31], v[128:131], v[200:203], v[28:31]
	v_mfma_f32_16x16x32_bf16 v[24:27], v[136:139], v[200:203], v[24:27]
	v_mfma_f32_16x16x32_bf16 v[12:15], v[128:131], v[208:211], v[12:15]
	v_mfma_f32_16x16x32_bf16 v[8:11], v[136:139], v[208:211], v[8:11]
	v_mfma_f32_16x16x32_bf16 v[60:63], v[132:135], v[180:183], v[60:63]
	v_mfma_f32_16x16x32_bf16 v[56:59], v[140:143], v[180:183], v[56:59]
	v_mfma_f32_16x16x32_bf16 v[44:47], v[132:135], v[196:199], v[44:47]
	v_mfma_f32_16x16x32_bf16 v[40:43], v[140:143], v[196:199], v[40:43]
	v_mfma_f32_16x16x32_bf16 v[28:31], v[132:135], v[204:207], v[28:31]
	v_mfma_f32_16x16x32_bf16 v[24:27], v[140:143], v[204:207], v[24:27]
	v_mfma_f32_16x16x32_bf16 v[12:15], v[132:135], v[212:215], v[12:15]
	v_mfma_f32_16x16x32_bf16 v[8:11], v[140:143], v[212:215], v[8:11]
	s_setprio 0
	s_setprio 1
	v_mfma_f32_16x16x32_bf16 v[52:55], v[144:147], v[176:179], v[52:55]
	v_mfma_f32_16x16x32_bf16 v[48:51], v[168:171], v[176:179], v[48:51]
	v_mfma_f32_16x16x32_bf16 v[36:39], v[144:147], v[192:195], v[36:39]
	v_mfma_f32_16x16x32_bf16 v[32:35], v[168:171], v[192:195], v[32:35]
	v_mfma_f32_16x16x32_bf16 v[20:23], v[144:147], v[200:203], v[20:23]
	v_mfma_f32_16x16x32_bf16 v[16:19], v[168:171], v[200:203], v[16:19]
	v_mfma_f32_16x16x32_bf16 v[4:7], v[144:147], v[208:211], v[4:7]
	v_mfma_f32_16x16x32_bf16 v[0:3], v[168:171], v[208:211], v[0:3]
	v_mfma_f32_16x16x32_bf16 v[52:55], v[148:151], v[180:183], v[52:55]
	v_mfma_f32_16x16x32_bf16 v[48:51], v[172:175], v[180:183], v[48:51]
	v_mfma_f32_16x16x32_bf16 v[36:39], v[148:151], v[196:199], v[36:39]
	v_mfma_f32_16x16x32_bf16 v[32:35], v[172:175], v[196:199], v[32:35]
	v_mfma_f32_16x16x32_bf16 v[20:23], v[148:151], v[204:207], v[20:23]
	v_mfma_f32_16x16x32_bf16 v[16:19], v[172:175], v[204:207], v[16:19]
	v_mfma_f32_16x16x32_bf16 v[4:7], v[148:151], v[212:215], v[4:7]
	v_mfma_f32_16x16x32_bf16 v[0:3], v[172:175], v[212:215], v[0:3]
	s_setprio 0
	s_barrier
	ds_read_b128 v[176:179], v189 offset:32768
	ds_read_b128 v[180:183], v189 offset:33792
	ds_read_b128 v[192:195], v189 offset:34816
	ds_read_b128 v[196:199], v189 offset:35840
	ds_read_b128 v[200:203], v189 offset:36864
	ds_read_b128 v[204:207], v189 offset:37888
	ds_read_b128 v[208:211], v189 offset:38912
	ds_read_b128 v[212:215], v189 offset:39936
	s_add_i32 s56, 0, 0x18000
	s_add_i32 s57, 0, 0x1c000
	v_add_u32_e32 v140, s56, v186
	v_add_u32_e32 v172, s57, v186
	ds_read_b128 v[128:131], v140
	ds_read_b128 v[132:135], v140 offset:1024
	ds_read_b128 v[136:139], v140 offset:2048
	ds_read_b128 v[140:143], v140 offset:3072
	ds_read_b128 v[144:147], v172
	ds_read_b128 v[148:151], v172 offset:1024
	ds_read_b128 v[168:171], v172 offset:2048
	ds_read_b128 v[172:175], v172 offset:3072
	s_add_u32 s34, s34, 0x100000
	s_addc_u32 s35, s35, 0
	s_mov_b32 m0, s41
	v_lshl_add_u64 v[222:223], s[34:35], 0, v[152:153]
	global_load_lds_dwordx4 v[222:223], off
	v_lshl_add_u64 v[222:223], s[34:35], 0, v[156:157]
	s_mov_b32 m0, s42
	s_nop 0
	global_load_lds_dwordx4 v[222:223], off
	s_waitcnt vmcnt(8)
	s_waitcnt lgkmcnt(0)
	s_barrier
	s_setprio 1
	s_waitcnt lgkmcnt(0)
	v_mfma_f32_16x16x32_bf16 v[124:127], v[128:131], v[176:179], v[124:127]
	v_mfma_f32_16x16x32_bf16 v[120:123], v[136:139], v[176:179], v[120:123]
	v_mfma_f32_16x16x32_bf16 v[108:111], v[128:131], v[192:195], v[108:111]
	v_mfma_f32_16x16x32_bf16 v[104:107], v[136:139], v[192:195], v[104:107]
	v_mfma_f32_16x16x32_bf16 v[92:95], v[128:131], v[200:203], v[92:95]
	v_mfma_f32_16x16x32_bf16 v[88:91], v[136:139], v[200:203], v[88:91]
	v_mfma_f32_16x16x32_bf16 v[76:79], v[128:131], v[208:211], v[76:79]
	v_mfma_f32_16x16x32_bf16 v[72:75], v[136:139], v[208:211], v[72:75]
	v_mfma_f32_16x16x32_bf16 v[124:127], v[132:135], v[180:183], v[124:127]
	v_mfma_f32_16x16x32_bf16 v[120:123], v[140:143], v[180:183], v[120:123]
	v_mfma_f32_16x16x32_bf16 v[108:111], v[132:135], v[196:199], v[108:111]
	v_mfma_f32_16x16x32_bf16 v[104:107], v[140:143], v[196:199], v[104:107]
	v_mfma_f32_16x16x32_bf16 v[92:95], v[132:135], v[204:207], v[92:95]
	v_mfma_f32_16x16x32_bf16 v[88:91], v[140:143], v[204:207], v[88:91]
	v_mfma_f32_16x16x32_bf16 v[76:79], v[132:135], v[212:215], v[76:79]
	v_mfma_f32_16x16x32_bf16 v[72:75], v[140:143], v[212:215], v[72:75]
	s_setprio 0
	s_setprio 1
	v_mfma_f32_16x16x32_bf16 v[116:119], v[144:147], v[176:179], v[116:119]
	v_mfma_f32_16x16x32_bf16 v[112:115], v[168:171], v[176:179], v[112:115]
	v_mfma_f32_16x16x32_bf16 v[100:103], v[144:147], v[192:195], v[100:103]
	v_mfma_f32_16x16x32_bf16 v[96:99], v[168:171], v[192:195], v[96:99]
	v_mfma_f32_16x16x32_bf16 v[84:87], v[144:147], v[200:203], v[84:87]
	v_mfma_f32_16x16x32_bf16 v[80:83], v[168:171], v[200:203], v[80:83]
	v_mfma_f32_16x16x32_bf16 v[68:71], v[144:147], v[208:211], v[68:71]
	v_mfma_f32_16x16x32_bf16 v[64:67], v[168:171], v[208:211], v[64:67]
	v_mfma_f32_16x16x32_bf16 v[116:119], v[148:151], v[180:183], v[116:119]
	v_mfma_f32_16x16x32_bf16 v[112:115], v[172:175], v[180:183], v[112:115]
	v_mfma_f32_16x16x32_bf16 v[100:103], v[148:151], v[196:199], v[100:103]
	v_mfma_f32_16x16x32_bf16 v[96:99], v[172:175], v[196:199], v[96:99]
	v_mfma_f32_16x16x32_bf16 v[84:87], v[148:151], v[204:207], v[84:87]
	v_mfma_f32_16x16x32_bf16 v[80:83], v[172:175], v[204:207], v[80:83]
	v_mfma_f32_16x16x32_bf16 v[68:71], v[148:151], v[212:215], v[68:71]
	v_mfma_f32_16x16x32_bf16 v[64:67], v[172:175], v[212:215], v[64:67]
	s_setprio 0
	s_barrier
; #define PG8_STAGE(bufoff, gbase, voff) do { _Pragma("unroll") for (int _i = 0; _i < 2; ++_i) \
;         __builtin_amdgcn_global_load_lds((const unsigned*)((const char*)(gbase) + (voff)[_i]), (PG8_LAS unsigned*)(lds + (bufoff) + ldsw + _i * 8192), 16, 0, 0); } while (0)
; #define PG8_LDA(dst, b, h) do { _Pragma("unroll") for (int m = 0; m < 4; ++m) _Pragma("unroll") for (int k = 0; k < 2; ++k) dst[m][k] = *(const PG8_LAS bf16x8*)(lds + PG8_SA(b, h) + aoff + m * 2048 + k * 1024); } while (0)
; #define PG8_MMA(ai, bj, At, Bt) do { __builtin_amdgcn_s_setprio(1); _Pragma("unroll") for (int m = 0; m < 4; ++m) _Pragma("unroll") for (int n = 0; n < 2; ++n) _Pragma("unroll") for (int k = 0; k < 2; ++k) \
;         acc[ai][bj][m][n] = __builtin_amdgcn_mfma_f32_16x16x32_bf16(Bt[n][k], At[m][k], acc[ai][bj][m][n], 0, 0, 0); __builtin_amdgcn_s_setprio(0); } while (0)
; #define PG8_WAIT_V(n) asm volatile("s_waitcnt vmcnt(" #n ")" ::: "memory")
; #define PG8_WAIT_L(n) asm volatile("s_waitcnt lgkmcnt(" #n ")" ::: "memory")
; #define PG8_BAR __builtin_amdgcn_s_barrier()
; #define PG8_SCHED __builtin_amdgcn_sched_barrier(0)
; template <class Epi, class Sched, bool ALIGN_EPI = false, bool SP2 = false>
; __device__ __forceinline__ void gemm_phase(PG8_LAS unsigned char* lds, const Gemm g, const Sched& S, const Epi& E, const int wid) {
;     ...
;         for (int t = 0; t < nt; t += 2) {
;             const bool last = (t == nt - 2);
;             const char* a1 = cA + (size_t)(t + 1) * kstep;
;             const char* a2 = last ? nA : cA + (size_t)(t + 2) * kstep; const char* b2 = last ? nB : cB + (size_t)(t + 2) * kstep;
;     ...
;             PG8_LDA(At, 1, 1); PG8_STAGE(PG8_SB(1, 0), b3, voffB); PG8_STAGE(PG8_SB(1, 1), b3 + hstep, voffB); PG8_STAGE(PG8_SA(1, 0), a3, voffA);
;             PG8_WAIT_V(8); PG8_WAIT_L(0); PG8_BAR; PG8_MMA(1, 0, At, B0); PG8_MMA(1, 1, At, B1); PG8_BAR; PG8_SCHED;
;     ...
;         if constexpr (ALIGN_EPI) { if (wr == 0) PG8_BAR; }
	ds_read_b128 v[176:179], v189 offset:49152
	ds_read_b128 v[180:183], v189 offset:50176
	ds_read_b128 v[192:195], v189 offset:51200
	ds_read_b128 v[196:199], v189 offset:52224
	ds_read_b128 v[200:203], v189 offset:53248
	ds_read_b128 v[204:207], v189 offset:54272
	ds_read_b128 v[208:211], v189 offset:55296
	ds_read_b128 v[212:215], v189 offset:56320
	s_add_i32 s34, s56, s39
	v_lshl_add_u64 v[184:185], v[184:185], 0, s[14:15]
	s_mov_b32 m0, s34
	s_nop 0
	global_load_lds_dwordx4 v[184:185], off
	s_add_i32 m0, s34, 0x2000
	s_add_u32 s30, s30, 0x100080
	v_lshl_add_u64 v[184:185], v[216:217], 0, s[14:15]
	s_addc_u32 s31, s31, 0
	s_add_i32 s34, s57, s39
	global_load_lds_dwordx4 v[184:185], off
	v_lshl_add_u64 v[184:185], s[30:31], 0, v[154:155]
	s_mov_b32 m0, s34
	s_nop 0
	global_load_lds_dwordx4 v[184:185], off
	v_lshl_add_u64 v[184:185], s[30:31], 0, v[158:159]
	s_add_i32 m0, s34, 0x2000
	s_nop 0
	global_load_lds_dwordx4 v[184:185], off
	v_lshl_add_u64 v[184:185], v[218:219], 0, s[14:15]
	s_mov_b32 m0, s46
	s_nop 0
	global_load_lds_dwordx4 v[184:185], off
	v_lshl_add_u64 v[184:185], v[220:221], 0, s[14:15]
	s_mov_b32 m0, s47
	s_nop 0
	global_load_lds_dwordx4 v[184:185], off
	s_waitcnt vmcnt(8)
	s_waitcnt lgkmcnt(0)
	s_barrier
	s_setprio 1
	s_waitcnt lgkmcnt(0)
	v_mfma_f32_16x16x32_bf16 v[60:63], v[128:131], v[176:179], v[60:63]
	v_mfma_f32_16x16x32_bf16 v[56:59], v[136:139], v[176:179], v[56:59]
	v_mfma_f32_16x16x32_bf16 v[44:47], v[128:131], v[192:195], v[44:47]
	v_mfma_f32_16x16x32_bf16 v[40:43], v[136:139], v[192:195], v[40:43]
	v_mfma_f32_16x16x32_bf16 v[28:31], v[128:131], v[200:203], v[28:31]
	v_mfma_f32_16x16x32_bf16 v[24:27], v[136:139], v[200:203], v[24:27]
	v_mfma_f32_16x16x32_bf16 v[12:15], v[128:131], v[208:211], v[12:15]
	v_mfma_f32_16x16x32_bf16 v[8:11], v[136:139], v[208:211], v[8:11]
	v_mfma_f32_16x16x32_bf16 v[60:63], v[132:135], v[180:183], v[60:63]
	v_mfma_f32_16x16x32_bf16 v[56:59], v[140:143], v[180:183], v[56:59]
	v_mfma_f32_16x16x32_bf16 v[44:47], v[132:135], v[196:199], v[44:47]
	v_mfma_f32_16x16x32_bf16 v[40:43], v[140:143], v[196:199], v[40:43]
	v_mfma_f32_16x16x32_bf16 v[28:31], v[132:135], v[204:207], v[28:31]
	v_mfma_f32_16x16x32_bf16 v[24:27], v[140:143], v[204:207], v[24:27]
	v_mfma_f32_16x16x32_bf16 v[12:15], v[132:135], v[212:215], v[12:15]
	v_mfma_f32_16x16x32_bf16 v[8:11], v[140:143], v[212:215], v[8:11]
	s_setprio 0
	s_setprio 1
	v_mfma_f32_16x16x32_bf16 v[52:55], v[144:147], v[176:179], v[52:55]
	v_mfma_f32_16x16x32_bf16 v[48:51], v[168:171], v[176:179], v[48:51]
	v_mfma_f32_16x16x32_bf16 v[36:39], v[144:147], v[192:195], v[36:39]
	v_mfma_f32_16x16x32_bf16 v[32:35], v[168:171], v[192:195], v[32:35]
	s_add_i32 s55, s55, 2
	s_add_u32 s28, s28, 0x100
	s_addc_u32 s29, s29, 0
	s_add_u32 s53, s53, 0x100
	s_addc_u32 s54, s54, 0
	s_cmp_gt_u32 s55, 61
	v_mfma_f32_16x16x32_bf16 v[20:23], v[144:147], v[200:203], v[20:23]
	v_mfma_f32_16x16x32_bf16 v[16:19], v[168:171], v[200:203], v[16:19]
	v_mfma_f32_16x16x32_bf16 v[4:7], v[144:147], v[208:211], v[4:7]
	v_mfma_f32_16x16x32_bf16 v[0:3], v[168:171], v[208:211], v[0:3]
	v_mfma_f32_16x16x32_bf16 v[52:55], v[148:151], v[180:183], v[52:55]
	v_mfma_f32_16x16x32_bf16 v[48:51], v[172:175], v[180:183], v[48:51]
	v_mfma_f32_16x16x32_bf16 v[36:39], v[148:151], v[196:199], v[36:39]
	v_mfma_f32_16x16x32_bf16 v[32:35], v[172:175], v[196:199], v[32:35]
	v_mfma_f32_16x16x32_bf16 v[20:23], v[148:151], v[204:207], v[20:23]
	v_mfma_f32_16x16x32_bf16 v[16:19], v[172:175], v[204:207], v[16:19]
	v_mfma_f32_16x16x32_bf16 v[4:7], v[148:151], v[212:215], v[4:7]
	v_mfma_f32_16x16x32_bf16 v[0:3], v[172:175], v[212:215], v[0:3]
	s_setprio 0
	s_barrier
	s_cbranch_scc0 .LBB0_2717
	s_and_b64 vcc, exec, s[16:17]
	s_cbranch_vccz .LBB0_2720
	s_barrier

; #define PG8_STAGE(bufoff, gbase, voff) do { _Pragma("unroll") for (int _i = 0; _i < 2; ++_i) \
;         __builtin_amdgcn_global_load_lds((const unsigned*)((const char*)(gbase) + (voff)[_i]), (PG8_LAS unsigned*)(lds + (bufoff) + ldsw + _i * 8192), 16, 0, 0); } while (0)
; #define PG8_LDA(dst, b, h) do { _Pragma("unroll") for (int m = 0; m < 4; ++m) _Pragma("unroll") for (int k = 0; k < 2; ++k) dst[m][k] = *(const PG8_LAS bf16x8*)(lds + PG8_SA(b, h) + aoff + m * 2048 + k * 1024); } while (0)
; #define PG8_LDB(dst, b, h) do { _Pragma("unroll") for (int n = 0; n < 2; ++n) _Pragma("unroll") for (int k = 0; k < 2; ++k) dst[n][k] = *(const PG8_LAS bf16x8*)(lds + PG8_SB(b, h) + boff + n * 2048 + k * 1024); } while (0)
; #define PG8_MMA(ai, bj, At, Bt) do { __builtin_amdgcn_s_setprio(1); _Pragma("unroll") for (int m = 0; m < 4; ++m) _Pragma("unroll") for (int n = 0; n < 2; ++n) _Pragma("unroll") for (int k = 0; k < 2; ++k) \
;         acc[ai][bj][m][n] = __builtin_amdgcn_mfma_f32_16x16x32_bf16(Bt[n][k], At[m][k], acc[ai][bj][m][n], 0, 0, 0); __builtin_amdgcn_s_setprio(0); } while (0)
; #define PG8_WAIT_V(n) asm volatile("s_waitcnt vmcnt(" #n ")" ::: "memory")
; #define PG8_WAIT_L(n) asm volatile("s_waitcnt lgkmcnt(" #n ")" ::: "memory")
; #define PG8_BAR __builtin_amdgcn_s_barrier()
; #define PG8_SCHED __builtin_amdgcn_sched_barrier(0)
; template <class Epi, class Sched, bool ALIGN_EPI = false, bool SP2 = false>
; __device__ __forceinline__ void gemm_phase(PG8_LAS unsigned char* lds, const Gemm g, const Sched& S, const Epi& E, const int wid) {
;     ...
;             const bool last = (t == nt - 2);
;             const char* a1 = cA + (size_t)(t + 1) * kstep;
;             const char* a2 = last ? nA : cA + (size_t)(t + 2) * kstep; const char* b2 = last ? nB : cB + (size_t)(t + 2) * kstep;
;             const char* a3 = a2 + kstep; const char* b3 = b2 + kstep;
;             if (last && has_next) S.a_ready(nxt);
;             if constexpr (SP2) {
;             PG8_LDB(B0, 0, 0); PG8_LDB(B1, 0, 1); PG8_SCHED; PG8_LDA(At, 0, 0); PG8_STAGE(PG8_SA(1, 1), a1 + hstep, voffA);
;             PG8_WAIT_V(8); PG8_WAIT_L(0); PG8_BAR; PG8_MMA(0, 0, At, B0); PG8_MMA(0, 1, At, B1); PG8_BAR; PG8_SCHED;
;             PG8_LDA(At, 0, 1); PG8_STAGE(PG8_SB(0, 0), b2, voffB); PG8_STAGE(PG8_SB(0, 1), b2 + hstep, voffB); PG8_STAGE(PG8_SA(0, 0), a2, voffA);
.LBB0_2810:
	ds_read_b128 v[144:147], v151
	ds_read_b128 v[156:159], v151 offset:1024
	ds_read_b128 v[160:163], v151 offset:2048
	ds_read_b128 v[164:167], v151 offset:3072
	ds_read_b128 v[168:171], v152
	ds_read_b128 v[172:175], v152 offset:1024
	ds_read_b128 v[176:179], v152 offset:2048
	ds_read_b128 v[180:183], v152 offset:3072
	ds_read_b128 v[184:187], v153
	ds_read_b128 v[188:191], v153 offset:1024
	ds_read_b128 v[192:195], v153 offset:2048
	ds_read_b128 v[196:199], v153 offset:3072
	ds_read_b128 v[200:203], v153 offset:4096
	ds_read_b128 v[204:207], v153 offset:5120
	ds_read_b128 v[208:211], v153 offset:6144
	ds_read_b128 v[212:215], v153 offset:7168
	s_add_u32 s6, s2, 0xfff00080
	s_addc_u32 s7, s3, -1
	s_cmp_eq_u32 s57, 60
	s_cselect_b32 s29, s23, s7
	s_cselect_b32 s28, s53, s6
	s_cselect_b32 s7, s21, s56
	s_cselect_b32 s6, s54, s55
	v_lshl_add_u64 v[148:149], s[2:3], 0, v[136:137]
	s_add_i32 m0, s42, 0xc000
	s_nop 0
	global_load_lds_dwordx4 v[148:149], off
	v_lshl_add_u64 v[148:149], s[2:3], 0, v[138:139]
	s_add_i32 m0, s42, 0xe000
	s_nop 0
	global_load_lds_dwordx4 v[148:149], off
	s_waitcnt vmcnt(8)
	s_waitcnt lgkmcnt(0)
	s_barrier
	s_setprio 1
	s_waitcnt lgkmcnt(0)
	v_mfma_f32_16x16x32_bf16 v[124:127], v[144:147], v[184:187], v[124:127]
	v_mfma_f32_16x16x32_bf16 v[116:119], v[160:163], v[184:187], v[116:119]
	v_mfma_f32_16x16x32_bf16 v[108:111], v[144:147], v[192:195], v[108:111]
	v_mfma_f32_16x16x32_bf16 v[100:103], v[160:163], v[192:195], v[100:103]
	v_mfma_f32_16x16x32_bf16 v[92:95], v[144:147], v[200:203], v[92:95]
	v_mfma_f32_16x16x32_bf16 v[84:87], v[160:163], v[200:203], v[84:87]
	v_mfma_f32_16x16x32_bf16 v[76:79], v[144:147], v[208:211], v[76:79]
	v_mfma_f32_16x16x32_bf16 v[68:71], v[160:163], v[208:211], v[68:71]
	v_mfma_f32_16x16x32_bf16 v[124:127], v[156:159], v[188:191], v[124:127]
	v_mfma_f32_16x16x32_bf16 v[116:119], v[164:167], v[188:191], v[116:119]
	v_mfma_f32_16x16x32_bf16 v[108:111], v[156:159], v[196:199], v[108:111]
	v_mfma_f32_16x16x32_bf16 v[100:103], v[164:167], v[196:199], v[100:103]
	v_mfma_f32_16x16x32_bf16 v[92:95], v[156:159], v[204:207], v[92:95]
	v_mfma_f32_16x16x32_bf16 v[84:87], v[164:167], v[204:207], v[84:87]
	v_mfma_f32_16x16x32_bf16 v[76:79], v[156:159], v[212:215], v[76:79]
	v_mfma_f32_16x16x32_bf16 v[68:71], v[164:167], v[212:215], v[68:71]
	s_setprio 0
	s_setprio 1
	v_mfma_f32_16x16x32_bf16 v[120:123], v[168:171], v[184:187], v[120:123]
	v_mfma_f32_16x16x32_bf16 v[112:115], v[176:179], v[184:187], v[112:115]
	v_mfma_f32_16x16x32_bf16 v[104:107], v[168:171], v[192:195], v[104:107]
	v_mfma_f32_16x16x32_bf16 v[96:99], v[176:179], v[192:195], v[96:99]
	v_mfma_f32_16x16x32_bf16 v[88:91], v[168:171], v[200:203], v[88:91]
	v_mfma_f32_16x16x32_bf16 v[80:83], v[176:179], v[200:203], v[80:83]
	v_mfma_f32_16x16x32_bf16 v[72:75], v[168:171], v[208:211], v[72:75]
	v_mfma_f32_16x16x32_bf16 v[64:67], v[176:179], v[208:211], v[64:67]
	v_mfma_f32_16x16x32_bf16 v[120:123], v[172:175], v[188:191], v[120:123]
	v_mfma_f32_16x16x32_bf16 v[112:115], v[180:183], v[188:191], v[112:115]
	v_mfma_f32_16x16x32_bf16 v[104:107], v[172:175], v[196:199], v[104:107]
	v_mfma_f32_16x16x32_bf16 v[96:99], v[180:183], v[196:199], v[96:99]
	v_mfma_f32_16x16x32_bf16 v[88:91], v[172:175], v[204:207], v[88:91]
	v_mfma_f32_16x16x32_bf16 v[80:83], v[180:183], v[204:207], v[80:83]
	v_mfma_f32_16x16x32_bf16 v[72:75], v[172:175], v[212:215], v[72:75]
	v_mfma_f32_16x16x32_bf16 v[64:67], v[180:183], v[212:215], v[64:67]
	s_setprio 0
	s_barrier
	ds_read_b128 v[184:187], v153 offset:16384
	ds_read_b128 v[188:191], v153 offset:17408
	ds_read_b128 v[192:195], v153 offset:18432
	ds_read_b128 v[196:199], v153 offset:19456
	ds_read_b128 v[200:203], v153 offset:20480
	ds_read_b128 v[204:207], v153 offset:21504
	ds_read_b128 v[208:211], v153 offset:22528
	ds_read_b128 v[212:215], v153 offset:23552
	s_add_i32 s58, s50, s33
	v_lshl_add_u64 v[148:149], s[6:7], 0, v[130:131]
	s_mov_b32 m0, s58
	s_nop 0
	global_load_lds_dwordx4 v[148:149], off
	s_add_i32 m0, s58, 0x2000
	s_add_u32 s58, s6, 0x100000
	v_lshl_add_u64 v[216:217], s[6:7], 0, v[134:135]
	s_addc_u32 s59, s7, 0
	s_add_i32 s60, s51, s33
	global_load_lds_dwordx4 v[216:217], off
	v_lshl_add_u64 v[218:219], s[58:59], 0, v[130:131]
	s_mov_b32 m0, s60
	v_lshl_add_u64 v[220:221], s[28:29], 0, v[132:133]
	global_load_lds_dwordx4 v[218:219], off
	v_lshl_add_u64 v[218:219], s[58:59], 0, v[134:135]
	s_add_i32 m0, s60, 0x2000
	s_nop 0
	global_load_lds_dwordx4 v[218:219], off
	v_lshl_add_u64 v[218:219], s[28:29], 0, v[128:129]
	s_mov_b32 m0, s42
	s_nop 0
	global_load_lds_dwordx4 v[218:219], off
	s_mov_b32 m0, s43
	s_nop 0
	global_load_lds_dwordx4 v[220:221], off
	s_waitcnt vmcnt(8)
	s_waitcnt lgkmcnt(0)
	s_barrier
; #define PG8_STAGE(bufoff, gbase, voff) do { _Pragma("unroll") for (int _i = 0; _i < 2; ++_i) \
;         __builtin_amdgcn_global_load_lds((const unsigned*)((const char*)(gbase) + (voff)[_i]), (PG8_LAS unsigned*)(lds + (bufoff) + ldsw + _i * 8192), 16, 0, 0); } while (0)
; #define PG8_LDA(dst, b, h) do { _Pragma("unroll") for (int m = 0; m < 4; ++m) _Pragma("unroll") for (int k = 0; k < 2; ++k) dst[m][k] = *(const PG8_LAS bf16x8*)(lds + PG8_SA(b, h) + aoff + m * 2048 + k * 1024); } while (0)
; #define PG8_LDB(dst, b, h) do { _Pragma("unroll") for (int n = 0; n < 2; ++n) _Pragma("unroll") for (int k = 0; k < 2; ++k) dst[n][k] = *(const PG8_LAS bf16x8*)(lds + PG8_SB(b, h) + boff + n * 2048 + k * 1024); } while (0)
; #define PG8_MMA(ai, bj, At, Bt) do { __builtin_amdgcn_s_setprio(1); _Pragma("unroll") for (int m = 0; m < 4; ++m) _Pragma("unroll") for (int n = 0; n < 2; ++n) _Pragma("unroll") for (int k = 0; k < 2; ++k) \
;         acc[ai][bj][m][n] = __builtin_amdgcn_mfma_f32_16x16x32_bf16(Bt[n][k], At[m][k], acc[ai][bj][m][n], 0, 0, 0); __builtin_amdgcn_s_setprio(0); } while (0)
; #define PG8_WAIT_V(n) asm volatile("s_waitcnt vmcnt(" #n ")" ::: "memory")
; #define PG8_WAIT_L(n) asm volatile("s_waitcnt lgkmcnt(" #n ")" ::: "memory")
; #define PG8_BAR __builtin_amdgcn_s_barrier()
; #define PG8_SCHED __builtin_amdgcn_sched_barrier(0)
; template <class Epi, class Sched, bool ALIGN_EPI = false, bool SP2 = false>
; __device__ __forceinline__ void gemm_phase(PG8_LAS unsigned char* lds, const Gemm g, const Sched& S, const Epi& E, const int wid) {
;     ...
;             PG8_WAIT_V(8); PG8_WAIT_L(0); PG8_BAR; PG8_MMA(1, 0, At, B0); PG8_MMA(1, 1, At, B1); PG8_BAR; PG8_SCHED;
;             PG8_LDB(B0, 1, 0); PG8_LDB(B1, 1, 1); PG8_SCHED; PG8_LDA(At, 1, 0); PG8_STAGE(PG8_SA(0, 1), a2 + hstep, voffA);
;             PG8_WAIT_V(8); PG8_WAIT_L(0); PG8_BAR; PG8_MMA(0, 0, At, B0); PG8_MMA(0, 1, At, B1); PG8_BAR; PG8_SCHED;
	s_setprio 1
	s_waitcnt lgkmcnt(0)
	v_mfma_f32_16x16x32_bf16 v[60:63], v[144:147], v[184:187], v[60:63]
	v_mfma_f32_16x16x32_bf16 v[52:55], v[160:163], v[184:187], v[52:55]
	v_mfma_f32_16x16x32_bf16 v[44:47], v[144:147], v[192:195], v[44:47]
	v_mfma_f32_16x16x32_bf16 v[36:39], v[160:163], v[192:195], v[36:39]
	v_mfma_f32_16x16x32_bf16 v[28:31], v[144:147], v[200:203], v[28:31]
	v_mfma_f32_16x16x32_bf16 v[20:23], v[160:163], v[200:203], v[20:23]
	v_mfma_f32_16x16x32_bf16 v[12:15], v[144:147], v[208:211], v[12:15]
	v_mfma_f32_16x16x32_bf16 v[4:7], v[160:163], v[208:211], v[4:7]
	v_mfma_f32_16x16x32_bf16 v[60:63], v[156:159], v[188:191], v[60:63]
	v_mfma_f32_16x16x32_bf16 v[52:55], v[164:167], v[188:191], v[52:55]
	v_mfma_f32_16x16x32_bf16 v[44:47], v[156:159], v[196:199], v[44:47]
	v_mfma_f32_16x16x32_bf16 v[36:39], v[164:167], v[196:199], v[36:39]
	v_mfma_f32_16x16x32_bf16 v[28:31], v[156:159], v[204:207], v[28:31]
	v_mfma_f32_16x16x32_bf16 v[20:23], v[164:167], v[204:207], v[20:23]
	v_mfma_f32_16x16x32_bf16 v[12:15], v[156:159], v[212:215], v[12:15]
	v_mfma_f32_16x16x32_bf16 v[4:7], v[164:167], v[212:215], v[4:7]
	s_setprio 0
	s_setprio 1
	v_mfma_f32_16x16x32_bf16 v[56:59], v[168:171], v[184:187], v[56:59]
	v_mfma_f32_16x16x32_bf16 v[48:51], v[176:179], v[184:187], v[48:51]
	v_mfma_f32_16x16x32_bf16 v[40:43], v[168:171], v[192:195], v[40:43]
	v_mfma_f32_16x16x32_bf16 v[32:35], v[176:179], v[192:195], v[32:35]
	v_mfma_f32_16x16x32_bf16 v[24:27], v[168:171], v[200:203], v[24:27]
	v_mfma_f32_16x16x32_bf16 v[16:19], v[176:179], v[200:203], v[16:19]
	v_mfma_f32_16x16x32_bf16 v[8:11], v[168:171], v[208:211], v[8:11]
	v_mfma_f32_16x16x32_bf16 v[0:3], v[176:179], v[208:211], v[0:3]
	v_mfma_f32_16x16x32_bf16 v[56:59], v[172:175], v[188:191], v[56:59]
	v_mfma_f32_16x16x32_bf16 v[48:51], v[180:183], v[188:191], v[48:51]
	v_mfma_f32_16x16x32_bf16 v[40:43], v[172:175], v[196:199], v[40:43]
	v_mfma_f32_16x16x32_bf16 v[32:35], v[180:183], v[196:199], v[32:35]
	v_mfma_f32_16x16x32_bf16 v[24:27], v[172:175], v[204:207], v[24:27]
	v_mfma_f32_16x16x32_bf16 v[16:19], v[180:183], v[204:207], v[16:19]
	v_mfma_f32_16x16x32_bf16 v[8:11], v[172:175], v[212:215], v[8:11]
	v_mfma_f32_16x16x32_bf16 v[0:3], v[180:183], v[212:215], v[0:3]
	s_setprio 0
	s_barrier
	ds_read_b128 v[184:187], v153 offset:32768
	ds_read_b128 v[188:191], v153 offset:33792
	ds_read_b128 v[192:195], v153 offset:34816
	ds_read_b128 v[196:199], v153 offset:35840
	ds_read_b128 v[200:203], v153 offset:36864
	ds_read_b128 v[204:207], v153 offset:37888
	ds_read_b128 v[208:211], v153 offset:38912
	ds_read_b128 v[212:215], v153 offset:39936
	s_add_i32 s58, 0, 0x18000
	v_add_u32_e32 v155, s58, v150
	s_add_i32 s59, 0, 0x1c000
	ds_read_b128 v[144:147], v155
	ds_read_b128 v[156:159], v155 offset:1024
	ds_read_b128 v[160:163], v155 offset:2048
	ds_read_b128 v[164:167], v155 offset:3072
	v_add_u32_e32 v155, s59, v150
	ds_read_b128 v[168:171], v155
	ds_read_b128 v[172:175], v155 offset:1024
	ds_read_b128 v[176:179], v155 offset:2048
	ds_read_b128 v[180:183], v155 offset:3072
	s_add_u32 s28, s28, 0x100000
	s_addc_u32 s29, s29, 0
	s_mov_b32 m0, s44
	v_lshl_add_u64 v[222:223], s[28:29], 0, v[128:129]
	global_load_lds_dwordx4 v[222:223], off
	v_lshl_add_u64 v[222:223], s[28:29], 0, v[132:133]
	s_mov_b32 m0, s45
	s_nop 0
	global_load_lds_dwordx4 v[222:223], off
	s_waitcnt vmcnt(8)
	s_waitcnt lgkmcnt(0)
	s_barrier
	s_setprio 1
	s_waitcnt lgkmcnt(0)
	v_mfma_f32_16x16x32_bf16 v[124:127], v[144:147], v[184:187], v[124:127]
	v_mfma_f32_16x16x32_bf16 v[116:119], v[160:163], v[184:187], v[116:119]
	v_mfma_f32_16x16x32_bf16 v[108:111], v[144:147], v[192:195], v[108:111]
	v_mfma_f32_16x16x32_bf16 v[100:103], v[160:163], v[192:195], v[100:103]
	v_mfma_f32_16x16x32_bf16 v[92:95], v[144:147], v[200:203], v[92:95]
	v_mfma_f32_16x16x32_bf16 v[84:87], v[160:163], v[200:203], v[84:87]
	v_mfma_f32_16x16x32_bf16 v[76:79], v[144:147], v[208:211], v[76:79]
	v_mfma_f32_16x16x32_bf16 v[68:71], v[160:163], v[208:211], v[68:71]
	v_mfma_f32_16x16x32_bf16 v[124:127], v[156:159], v[188:191], v[124:127]
	v_mfma_f32_16x16x32_bf16 v[116:119], v[164:167], v[188:191], v[116:119]
	v_mfma_f32_16x16x32_bf16 v[108:111], v[156:159], v[196:199], v[108:111]
	v_mfma_f32_16x16x32_bf16 v[100:103], v[164:167], v[196:199], v[100:103]
	v_mfma_f32_16x16x32_bf16 v[92:95], v[156:159], v[204:207], v[92:95]
	v_mfma_f32_16x16x32_bf16 v[84:87], v[164:167], v[204:207], v[84:87]
	v_mfma_f32_16x16x32_bf16 v[76:79], v[156:159], v[212:215], v[76:79]
	v_mfma_f32_16x16x32_bf16 v[68:71], v[164:167], v[212:215], v[68:71]
	s_setprio 0
	s_setprio 1
	v_mfma_f32_16x16x32_bf16 v[120:123], v[168:171], v[184:187], v[120:123]
	v_mfma_f32_16x16x32_bf16 v[112:115], v[176:179], v[184:187], v[112:115]
	v_mfma_f32_16x16x32_bf16 v[104:107], v[168:171], v[192:195], v[104:107]
	v_mfma_f32_16x16x32_bf16 v[96:99], v[176:179], v[192:195], v[96:99]
	v_mfma_f32_16x16x32_bf16 v[88:91], v[168:171], v[200:203], v[88:91]
	v_mfma_f32_16x16x32_bf16 v[80:83], v[176:179], v[200:203], v[80:83]
	v_mfma_f32_16x16x32_bf16 v[72:75], v[168:171], v[208:211], v[72:75]
	v_mfma_f32_16x16x32_bf16 v[64:67], v[176:179], v[208:211], v[64:67]
	v_mfma_f32_16x16x32_bf16 v[120:123], v[172:175], v[188:191], v[120:123]
	v_mfma_f32_16x16x32_bf16 v[112:115], v[180:183], v[188:191], v[112:115]
	v_mfma_f32_16x16x32_bf16 v[104:107], v[172:175], v[196:199], v[104:107]
	v_mfma_f32_16x16x32_bf16 v[96:99], v[180:183], v[196:199], v[96:99]
	v_mfma_f32_16x16x32_bf16 v[88:91], v[172:175], v[204:207], v[88:91]
	v_mfma_f32_16x16x32_bf16 v[80:83], v[180:183], v[204:207], v[80:83]
	v_mfma_f32_16x16x32_bf16 v[72:75], v[172:175], v[212:215], v[72:75]
	v_mfma_f32_16x16x32_bf16 v[64:67], v[180:183], v[212:215], v[64:67]
	s_setprio 0
	s_barrier
; #define PG8_STAGE(bufoff, gbase, voff) do { _Pragma("unroll") for (int _i = 0; _i < 2; ++_i) \
;         __builtin_amdgcn_global_load_lds((const unsigned*)((const char*)(gbase) + (voff)[_i]), (PG8_LAS unsigned*)(lds + (bufoff) + ldsw + _i * 8192), 16, 0, 0); } while (0)
; #define PG8_LDA(dst, b, h) do { _Pragma("unroll") for (int m = 0; m < 4; ++m) _Pragma("unroll") for (int k = 0; k < 2; ++k) dst[m][k] = *(const PG8_LAS bf16x8*)(lds + PG8_SA(b, h) + aoff + m * 2048 + k * 1024); } while (0)
; #define PG8_MMA(ai, bj, At, Bt) do { __builtin_amdgcn_s_setprio(1); _Pragma("unroll") for (int m = 0; m < 4; ++m) _Pragma("unroll") for (int n = 0; n < 2; ++n) _Pragma("unroll") for (int k = 0; k < 2; ++k) \
;         acc[ai][bj][m][n] = __builtin_amdgcn_mfma_f32_16x16x32_bf16(Bt[n][k], At[m][k], acc[ai][bj][m][n], 0, 0, 0); __builtin_amdgcn_s_setprio(0); } while (0)
; #define PG8_WAIT_V(n) asm volatile("s_waitcnt vmcnt(" #n ")" ::: "memory")
; #define PG8_WAIT_L(n) asm volatile("s_waitcnt lgkmcnt(" #n ")" ::: "memory")
; #define PG8_BAR __builtin_amdgcn_s_barrier()
; #define PG8_SCHED __builtin_amdgcn_sched_barrier(0)
; template <class Epi, class Sched, bool ALIGN_EPI = false, bool SP2 = false>
; __device__ __forceinline__ void gemm_phase(PG8_LAS unsigned char* lds, const Gemm g, const Sched& S, const Epi& E, const int wid) {
;     ...
;         for (int t = 0; t < nt; t += 2) {
;             const bool last = (t == nt - 2);
;             const char* a1 = cA + (size_t)(t + 1) * kstep;
;             const char* a2 = last ? nA : cA + (size_t)(t + 2) * kstep; const char* b2 = last ? nB : cB + (size_t)(t + 2) * kstep;
;     ...
;             PG8_LDA(At, 1, 1); PG8_STAGE(PG8_SB(1, 0), b3, voffB); PG8_STAGE(PG8_SB(1, 1), b3 + hstep, voffB); PG8_STAGE(PG8_SA(1, 0), a3, voffA);
;             PG8_WAIT_V(8); PG8_WAIT_L(0); PG8_BAR; PG8_MMA(1, 0, At, B0); PG8_MMA(1, 1, At, B1); PG8_BAR; PG8_SCHED;
;     ...
;         if constexpr (ALIGN_EPI) { if (wr == 0) PG8_BAR; }
	ds_read_b128 v[184:187], v153 offset:49152
	ds_read_b128 v[188:191], v153 offset:50176
	ds_read_b128 v[192:195], v153 offset:51200
	ds_read_b128 v[196:199], v153 offset:52224
	ds_read_b128 v[200:203], v153 offset:53248
	ds_read_b128 v[204:207], v153 offset:54272
	ds_read_b128 v[208:211], v153 offset:55296
	ds_read_b128 v[212:215], v153 offset:56320
	s_add_i32 s28, s58, s33
	v_lshl_add_u64 v[148:149], v[148:149], 0, s[16:17]
	s_mov_b32 m0, s28
	s_nop 0
	global_load_lds_dwordx4 v[148:149], off
	s_add_i32 m0, s28, 0x2000
	s_add_u32 s6, s6, 0x100080
	v_lshl_add_u64 v[148:149], v[216:217], 0, s[16:17]
	s_addc_u32 s7, s7, 0
	s_add_i32 s28, s59, s33
	global_load_lds_dwordx4 v[148:149], off
	v_lshl_add_u64 v[148:149], s[6:7], 0, v[130:131]
	s_mov_b32 m0, s28
	s_nop 0
	global_load_lds_dwordx4 v[148:149], off
	v_lshl_add_u64 v[148:149], s[6:7], 0, v[134:135]
	s_add_i32 m0, s28, 0x2000
	s_nop 0
	global_load_lds_dwordx4 v[148:149], off
	v_lshl_add_u64 v[148:149], v[218:219], 0, s[16:17]
	s_mov_b32 m0, s47
	s_nop 0
	global_load_lds_dwordx4 v[148:149], off
	v_lshl_add_u64 v[148:149], v[220:221], 0, s[16:17]
	s_mov_b32 m0, s48
	s_nop 0
	global_load_lds_dwordx4 v[148:149], off
	s_waitcnt vmcnt(8)
	s_waitcnt lgkmcnt(0)
	s_barrier
	s_setprio 1
	s_waitcnt lgkmcnt(0)
	v_mfma_f32_16x16x32_bf16 v[60:63], v[144:147], v[184:187], v[60:63]
	v_mfma_f32_16x16x32_bf16 v[52:55], v[160:163], v[184:187], v[52:55]
	v_mfma_f32_16x16x32_bf16 v[44:47], v[144:147], v[192:195], v[44:47]
	v_mfma_f32_16x16x32_bf16 v[36:39], v[160:163], v[192:195], v[36:39]
	v_mfma_f32_16x16x32_bf16 v[28:31], v[144:147], v[200:203], v[28:31]
	v_mfma_f32_16x16x32_bf16 v[20:23], v[160:163], v[200:203], v[20:23]
	v_mfma_f32_16x16x32_bf16 v[12:15], v[144:147], v[208:211], v[12:15]
	v_mfma_f32_16x16x32_bf16 v[4:7], v[160:163], v[208:211], v[4:7]
	v_mfma_f32_16x16x32_bf16 v[60:63], v[156:159], v[188:191], v[60:63]
	v_mfma_f32_16x16x32_bf16 v[52:55], v[164:167], v[188:191], v[52:55]
	v_mfma_f32_16x16x32_bf16 v[44:47], v[156:159], v[196:199], v[44:47]
	v_mfma_f32_16x16x32_bf16 v[36:39], v[164:167], v[196:199], v[36:39]
	v_mfma_f32_16x16x32_bf16 v[28:31], v[156:159], v[204:207], v[28:31]
	v_mfma_f32_16x16x32_bf16 v[20:23], v[164:167], v[204:207], v[20:23]
	v_mfma_f32_16x16x32_bf16 v[12:15], v[156:159], v[212:215], v[12:15]
	v_mfma_f32_16x16x32_bf16 v[4:7], v[164:167], v[212:215], v[4:7]
	s_setprio 0
	s_setprio 1
	v_mfma_f32_16x16x32_bf16 v[56:59], v[168:171], v[184:187], v[56:59]
	v_mfma_f32_16x16x32_bf16 v[48:51], v[176:179], v[184:187], v[48:51]
	v_mfma_f32_16x16x32_bf16 v[40:43], v[168:171], v[192:195], v[40:43]
	v_mfma_f32_16x16x32_bf16 v[32:35], v[176:179], v[192:195], v[32:35]
	s_add_i32 s57, s57, 2
	s_add_u32 s2, s2, 0x100
	s_addc_u32 s3, s3, 0
	s_add_u32 s55, s55, 0x100
	s_addc_u32 s56, s56, 0
	s_cmp_gt_u32 s57, 61
	v_mfma_f32_16x16x32_bf16 v[24:27], v[168:171], v[200:203], v[24:27]
	v_mfma_f32_16x16x32_bf16 v[16:19], v[176:179], v[200:203], v[16:19]
	v_mfma_f32_16x16x32_bf16 v[8:11], v[168:171], v[208:211], v[8:11]
	v_mfma_f32_16x16x32_bf16 v[0:3], v[176:179], v[208:211], v[0:3]
	v_mfma_f32_16x16x32_bf16 v[56:59], v[172:175], v[188:191], v[56:59]
	v_mfma_f32_16x16x32_bf16 v[48:51], v[180:183], v[188:191], v[48:51]
	v_mfma_f32_16x16x32_bf16 v[40:43], v[172:175], v[196:199], v[40:43]
	v_mfma_f32_16x16x32_bf16 v[32:35], v[180:183], v[196:199], v[32:35]
	v_mfma_f32_16x16x32_bf16 v[24:27], v[172:175], v[204:207], v[24:27]
	v_mfma_f32_16x16x32_bf16 v[16:19], v[180:183], v[204:207], v[16:19]
	v_mfma_f32_16x16x32_bf16 v[8:11], v[172:175], v[212:215], v[8:11]
	v_mfma_f32_16x16x32_bf16 v[0:3], v[180:183], v[212:215], v[0:3]
	s_setprio 0
	s_barrier
	s_cbranch_scc0 .LBB0_2810
	s_and_b64 vcc, exec, s[18:19]
	s_cbranch_vccz .LBB0_2813
	s_barrier

; #define PG8_STAGE(bufoff, gbase, voff) do { _Pragma("unroll") for (int _i = 0; _i < 2; ++_i) \
;         __builtin_amdgcn_global_load_lds((const unsigned*)((const char*)(gbase) + (voff)[_i]), (PG8_LAS unsigned*)(lds + (bufoff) + ldsw + _i * 8192), 16, 0, 0); } while (0)
; #define PG8_LDA(dst, b, h) do { _Pragma("unroll") for (int m = 0; m < 4; ++m) _Pragma("unroll") for (int k = 0; k < 2; ++k) dst[m][k] = *(const PG8_LAS bf16x8*)(lds + PG8_SA(b, h) + aoff + m * 2048 + k * 1024); } while (0)
; #define PG8_LDB(dst, b, h) do { _Pragma("unroll") for (int n = 0; n < 2; ++n) _Pragma("unroll") for (int k = 0; k < 2; ++k) dst[n][k] = *(const PG8_LAS bf16x8*)(lds + PG8_SB(b, h) + boff + n * 2048 + k * 1024); } while (0)
; #define PG8_MMA(ai, bj, At, Bt) do { __builtin_amdgcn_s_setprio(1); _Pragma("unroll") for (int m = 0; m < 4; ++m) _Pragma("unroll") for (int n = 0; n < 2; ++n) _Pragma("unroll") for (int k = 0; k < 2; ++k) \
;         acc[ai][bj][m][n] = __builtin_amdgcn_mfma_f32_16x16x32_bf16(Bt[n][k], At[m][k], acc[ai][bj][m][n], 0, 0, 0); __builtin_amdgcn_s_setprio(0); } while (0)
; #define PG8_WAIT_V(n) asm volatile("s_waitcnt vmcnt(" #n ")" ::: "memory")
; #define PG8_WAIT_L(n) asm volatile("s_waitcnt lgkmcnt(" #n ")" ::: "memory")
; #define PG8_BAR __builtin_amdgcn_s_barrier()
; #define PG8_SCHED __builtin_amdgcn_sched_barrier(0)
; template <class Epi, class Sched, bool ALIGN_EPI = false, bool SP2 = false>
; __device__ __forceinline__ void gemm_phase(PG8_LAS unsigned char* lds, const Gemm g, const Sched& S, const Epi& E, const int wid) {
;     ...
;             const bool last = (t == nt - 2);
;             const char* a1 = cA + (size_t)(t + 1) * kstep;
;             const char* a2 = last ? nA : cA + (size_t)(t + 2) * kstep; const char* b2 = last ? nB : cB + (size_t)(t + 2) * kstep;
;             const char* a3 = a2 + kstep; const char* b3 = b2 + kstep;
;             if (last && has_next) S.a_ready(nxt);
;             if constexpr (SP2) {
;             PG8_LDB(B0, 0, 0); PG8_LDB(B1, 0, 1); PG8_SCHED; PG8_LDA(At, 0, 0); PG8_STAGE(PG8_SA(1, 1), a1 + hstep, voffA);
;             PG8_WAIT_V(8); PG8_WAIT_L(0); PG8_BAR; PG8_MMA(0, 0, At, B0); PG8_MMA(0, 1, At, B1); PG8_BAR; PG8_SCHED;
;             PG8_LDA(At, 0, 1); PG8_STAGE(PG8_SB(0, 0), b2, voffB); PG8_STAGE(PG8_SB(0, 1), b2 + hstep, voffB); PG8_STAGE(PG8_SA(0, 0), a2, voffA);
.LBB0_2826:
	ds_read_b128 v[144:147], v151
	ds_read_b128 v[156:159], v151 offset:1024
	ds_read_b128 v[160:163], v151 offset:2048
	ds_read_b128 v[164:167], v151 offset:3072
	ds_read_b128 v[168:171], v152
	ds_read_b128 v[172:175], v152 offset:1024
	ds_read_b128 v[176:179], v152 offset:2048
	ds_read_b128 v[180:183], v152 offset:3072
	ds_read_b128 v[184:187], v153
	ds_read_b128 v[188:191], v153 offset:1024
	ds_read_b128 v[192:195], v153 offset:2048
	ds_read_b128 v[196:199], v153 offset:3072
	ds_read_b128 v[200:203], v153 offset:4096
	ds_read_b128 v[204:207], v153 offset:5120
	ds_read_b128 v[208:211], v153 offset:6144
	ds_read_b128 v[212:215], v153 offset:7168
	s_add_u32 s6, s2, 0xfff00080
	s_addc_u32 s7, s3, -1
	s_cmp_eq_u32 s58, 60
	s_cselect_b32 s29, s23, s7
	s_cselect_b32 s28, s54, s6
	s_cselect_b32 s7, s21, s57
	s_cselect_b32 s6, s55, s56
	v_lshl_add_u64 v[148:149], s[2:3], 0, v[136:137]
	s_add_i32 m0, s43, 0xc000
	s_nop 0
	global_load_lds_dwordx4 v[148:149], off
	v_lshl_add_u64 v[148:149], s[2:3], 0, v[138:139]
	s_add_i32 m0, s43, 0xe000
	s_nop 0
	global_load_lds_dwordx4 v[148:149], off
	s_waitcnt vmcnt(8)
	s_waitcnt lgkmcnt(0)
	s_barrier
	s_setprio 1
	s_waitcnt lgkmcnt(0)
	v_mfma_f32_16x16x32_bf16 v[124:127], v[144:147], v[184:187], v[124:127]
	v_mfma_f32_16x16x32_bf16 v[116:119], v[160:163], v[184:187], v[116:119]
	v_mfma_f32_16x16x32_bf16 v[108:111], v[144:147], v[192:195], v[108:111]
	v_mfma_f32_16x16x32_bf16 v[100:103], v[160:163], v[192:195], v[100:103]
	v_mfma_f32_16x16x32_bf16 v[92:95], v[144:147], v[200:203], v[92:95]
	v_mfma_f32_16x16x32_bf16 v[84:87], v[160:163], v[200:203], v[84:87]
	v_mfma_f32_16x16x32_bf16 v[76:79], v[144:147], v[208:211], v[76:79]
	v_mfma_f32_16x16x32_bf16 v[68:71], v[160:163], v[208:211], v[68:71]
	v_mfma_f32_16x16x32_bf16 v[124:127], v[156:159], v[188:191], v[124:127]
	v_mfma_f32_16x16x32_bf16 v[116:119], v[164:167], v[188:191], v[116:119]
	v_mfma_f32_16x16x32_bf16 v[108:111], v[156:159], v[196:199], v[108:111]
	v_mfma_f32_16x16x32_bf16 v[100:103], v[164:167], v[196:199], v[100:103]
	v_mfma_f32_16x16x32_bf16 v[92:95], v[156:159], v[204:207], v[92:95]
	v_mfma_f32_16x16x32_bf16 v[84:87], v[164:167], v[204:207], v[84:87]
	v_mfma_f32_16x16x32_bf16 v[76:79], v[156:159], v[212:215], v[76:79]
	v_mfma_f32_16x16x32_bf16 v[68:71], v[164:167], v[212:215], v[68:71]
	s_setprio 0
	s_setprio 1
	v_mfma_f32_16x16x32_bf16 v[120:123], v[168:171], v[184:187], v[120:123]
	v_mfma_f32_16x16x32_bf16 v[112:115], v[176:179], v[184:187], v[112:115]
	v_mfma_f32_16x16x32_bf16 v[104:107], v[168:171], v[192:195], v[104:107]
	v_mfma_f32_16x16x32_bf16 v[96:99], v[176:179], v[192:195], v[96:99]
	v_mfma_f32_16x16x32_bf16 v[88:91], v[168:171], v[200:203], v[88:91]
	v_mfma_f32_16x16x32_bf16 v[80:83], v[176:179], v[200:203], v[80:83]
	v_mfma_f32_16x16x32_bf16 v[72:75], v[168:171], v[208:211], v[72:75]
	v_mfma_f32_16x16x32_bf16 v[64:67], v[176:179], v[208:211], v[64:67]
	v_mfma_f32_16x16x32_bf16 v[120:123], v[172:175], v[188:191], v[120:123]
	v_mfma_f32_16x16x32_bf16 v[112:115], v[180:183], v[188:191], v[112:115]
	v_mfma_f32_16x16x32_bf16 v[104:107], v[172:175], v[196:199], v[104:107]
	v_mfma_f32_16x16x32_bf16 v[96:99], v[180:183], v[196:199], v[96:99]
	v_mfma_f32_16x16x32_bf16 v[88:91], v[172:175], v[204:207], v[88:91]
	v_mfma_f32_16x16x32_bf16 v[80:83], v[180:183], v[204:207], v[80:83]
	v_mfma_f32_16x16x32_bf16 v[72:75], v[172:175], v[212:215], v[72:75]
	v_mfma_f32_16x16x32_bf16 v[64:67], v[180:183], v[212:215], v[64:67]
	s_setprio 0
	s_barrier
	ds_read_b128 v[184:187], v153 offset:16384
	ds_read_b128 v[188:191], v153 offset:17408
	ds_read_b128 v[192:195], v153 offset:18432
	ds_read_b128 v[196:199], v153 offset:19456
	ds_read_b128 v[200:203], v153 offset:20480
	ds_read_b128 v[204:207], v153 offset:21504
	ds_read_b128 v[208:211], v153 offset:22528
	ds_read_b128 v[212:215], v153 offset:23552
	s_add_i32 s59, s51, s33
	v_lshl_add_u64 v[148:149], s[6:7], 0, v[132:133]
	s_mov_b32 m0, s59
	s_nop 0
	global_load_lds_dwordx4 v[148:149], off
	s_add_i32 m0, s59, 0x2000
	s_add_u32 s60, s6, 0x100000
	v_lshl_add_u64 v[216:217], s[6:7], 0, v[128:129]
	s_addc_u32 s61, s7, 0
	s_add_i32 s59, s52, s33
	global_load_lds_dwordx4 v[216:217], off
	v_lshl_add_u64 v[218:219], s[60:61], 0, v[132:133]
	s_mov_b32 m0, s59
	v_lshl_add_u64 v[220:221], s[28:29], 0, v[130:131]
	global_load_lds_dwordx4 v[218:219], off
	v_lshl_add_u64 v[218:219], s[60:61], 0, v[128:129]
	s_add_i32 m0, s59, 0x2000
	s_nop 0
	global_load_lds_dwordx4 v[218:219], off
	v_lshl_add_u64 v[218:219], s[28:29], 0, v[134:135]
	s_mov_b32 m0, s43
	s_nop 0
	global_load_lds_dwordx4 v[218:219], off
	s_mov_b32 m0, s44
	s_nop 0
	global_load_lds_dwordx4 v[220:221], off
	s_waitcnt vmcnt(8)
	s_waitcnt lgkmcnt(0)
	s_barrier
; #define PG8_STAGE(bufoff, gbase, voff) do { _Pragma("unroll") for (int _i = 0; _i < 2; ++_i) \
;         __builtin_amdgcn_global_load_lds((const unsigned*)((const char*)(gbase) + (voff)[_i]), (PG8_LAS unsigned*)(lds + (bufoff) + ldsw + _i * 8192), 16, 0, 0); } while (0)
; #define PG8_LDA(dst, b, h) do { _Pragma("unroll") for (int m = 0; m < 4; ++m) _Pragma("unroll") for (int k = 0; k < 2; ++k) dst[m][k] = *(const PG8_LAS bf16x8*)(lds + PG8_SA(b, h) + aoff + m * 2048 + k * 1024); } while (0)
; #define PG8_LDB(dst, b, h) do { _Pragma("unroll") for (int n = 0; n < 2; ++n) _Pragma("unroll") for (int k = 0; k < 2; ++k) dst[n][k] = *(const PG8_LAS bf16x8*)(lds + PG8_SB(b, h) + boff + n * 2048 + k * 1024); } while (0)
; #define PG8_MMA(ai, bj, At, Bt) do { __builtin_amdgcn_s_setprio(1); _Pragma("unroll") for (int m = 0; m < 4; ++m) _Pragma("unroll") for (int n = 0; n < 2; ++n) _Pragma("unroll") for (int k = 0; k < 2; ++k) \
;         acc[ai][bj][m][n] = __builtin_amdgcn_mfma_f32_16x16x32_bf16(Bt[n][k], At[m][k], acc[ai][bj][m][n], 0, 0, 0); __builtin_amdgcn_s_setprio(0); } while (0)
; #define PG8_WAIT_V(n) asm volatile("s_waitcnt vmcnt(" #n ")" ::: "memory")
; #define PG8_WAIT_L(n) asm volatile("s_waitcnt lgkmcnt(" #n ")" ::: "memory")
; #define PG8_BAR __builtin_amdgcn_s_barrier()
; #define PG8_SCHED __builtin_amdgcn_sched_barrier(0)
; template <class Epi, class Sched, bool ALIGN_EPI = false, bool SP2 = false>
; __device__ __forceinline__ void gemm_phase(PG8_LAS unsigned char* lds, const Gemm g, const Sched& S, const Epi& E, const int wid) {
;     ...
;             PG8_WAIT_V(8); PG8_WAIT_L(0); PG8_BAR; PG8_MMA(1, 0, At, B0); PG8_MMA(1, 1, At, B1); PG8_BAR; PG8_SCHED;
;             PG8_LDB(B0, 1, 0); PG8_LDB(B1, 1, 1); PG8_SCHED; PG8_LDA(At, 1, 0); PG8_STAGE(PG8_SA(0, 1), a2 + hstep, voffA);
;             PG8_WAIT_V(8); PG8_WAIT_L(0); PG8_BAR; PG8_MMA(0, 0, At, B0); PG8_MMA(0, 1, At, B1); PG8_BAR; PG8_SCHED;
	s_setprio 1
	s_waitcnt lgkmcnt(0)
	v_mfma_f32_16x16x32_bf16 v[60:63], v[144:147], v[184:187], v[60:63]
	v_mfma_f32_16x16x32_bf16 v[52:55], v[160:163], v[184:187], v[52:55]
	v_mfma_f32_16x16x32_bf16 v[44:47], v[144:147], v[192:195], v[44:47]
	v_mfma_f32_16x16x32_bf16 v[36:39], v[160:163], v[192:195], v[36:39]
	v_mfma_f32_16x16x32_bf16 v[28:31], v[144:147], v[200:203], v[28:31]
	v_mfma_f32_16x16x32_bf16 v[20:23], v[160:163], v[200:203], v[20:23]
	v_mfma_f32_16x16x32_bf16 v[12:15], v[144:147], v[208:211], v[12:15]
	v_mfma_f32_16x16x32_bf16 v[4:7], v[160:163], v[208:211], v[4:7]
	v_mfma_f32_16x16x32_bf16 v[60:63], v[156:159], v[188:191], v[60:63]
	v_mfma_f32_16x16x32_bf16 v[52:55], v[164:167], v[188:191], v[52:55]
	v_mfma_f32_16x16x32_bf16 v[44:47], v[156:159], v[196:199], v[44:47]
	v_mfma_f32_16x16x32_bf16 v[36:39], v[164:167], v[196:199], v[36:39]
	v_mfma_f32_16x16x32_bf16 v[28:31], v[156:159], v[204:207], v[28:31]
	v_mfma_f32_16x16x32_bf16 v[20:23], v[164:167], v[204:207], v[20:23]
	v_mfma_f32_16x16x32_bf16 v[12:15], v[156:159], v[212:215], v[12:15]
	v_mfma_f32_16x16x32_bf16 v[4:7], v[164:167], v[212:215], v[4:7]
	s_setprio 0
	s_setprio 1
	v_mfma_f32_16x16x32_bf16 v[56:59], v[168:171], v[184:187], v[56:59]
	v_mfma_f32_16x16x32_bf16 v[48:51], v[176:179], v[184:187], v[48:51]
	v_mfma_f32_16x16x32_bf16 v[40:43], v[168:171], v[192:195], v[40:43]
	v_mfma_f32_16x16x32_bf16 v[32:35], v[176:179], v[192:195], v[32:35]
	v_mfma_f32_16x16x32_bf16 v[24:27], v[168:171], v[200:203], v[24:27]
	v_mfma_f32_16x16x32_bf16 v[16:19], v[176:179], v[200:203], v[16:19]
	v_mfma_f32_16x16x32_bf16 v[8:11], v[168:171], v[208:211], v[8:11]
	v_mfma_f32_16x16x32_bf16 v[0:3], v[176:179], v[208:211], v[0:3]
	v_mfma_f32_16x16x32_bf16 v[56:59], v[172:175], v[188:191], v[56:59]
	v_mfma_f32_16x16x32_bf16 v[48:51], v[180:183], v[188:191], v[48:51]
	v_mfma_f32_16x16x32_bf16 v[40:43], v[172:175], v[196:199], v[40:43]
	v_mfma_f32_16x16x32_bf16 v[32:35], v[180:183], v[196:199], v[32:35]
	v_mfma_f32_16x16x32_bf16 v[24:27], v[172:175], v[204:207], v[24:27]
	v_mfma_f32_16x16x32_bf16 v[16:19], v[180:183], v[204:207], v[16:19]
	v_mfma_f32_16x16x32_bf16 v[8:11], v[172:175], v[212:215], v[8:11]
	v_mfma_f32_16x16x32_bf16 v[0:3], v[180:183], v[212:215], v[0:3]
	s_setprio 0
	s_barrier
	ds_read_b128 v[184:187], v153 offset:32768
	ds_read_b128 v[188:191], v153 offset:33792
	ds_read_b128 v[192:195], v153 offset:34816
	ds_read_b128 v[196:199], v153 offset:35840
	ds_read_b128 v[200:203], v153 offset:36864
	ds_read_b128 v[204:207], v153 offset:37888
	ds_read_b128 v[208:211], v153 offset:38912
	ds_read_b128 v[212:215], v153 offset:39936
	s_add_i32 s59, 0, 0x18000
	v_add_u32_e32 v155, s59, v150
	s_add_i32 s60, 0, 0x1c000
	ds_read_b128 v[144:147], v155
	ds_read_b128 v[156:159], v155 offset:1024
	ds_read_b128 v[160:163], v155 offset:2048
	ds_read_b128 v[164:167], v155 offset:3072
	v_add_u32_e32 v155, s60, v150
	ds_read_b128 v[168:171], v155
	ds_read_b128 v[172:175], v155 offset:1024
	ds_read_b128 v[176:179], v155 offset:2048
	ds_read_b128 v[180:183], v155 offset:3072
	s_add_u32 s28, s28, 0x100000
	s_addc_u32 s29, s29, 0
	s_mov_b32 m0, s45
	v_lshl_add_u64 v[222:223], s[28:29], 0, v[134:135]
	global_load_lds_dwordx4 v[222:223], off
	v_lshl_add_u64 v[222:223], s[28:29], 0, v[130:131]
	s_mov_b32 m0, s46
	s_nop 0
	global_load_lds_dwordx4 v[222:223], off
	s_waitcnt vmcnt(8)
	s_waitcnt lgkmcnt(0)
	s_barrier
	s_setprio 1
	s_waitcnt lgkmcnt(0)
	v_mfma_f32_16x16x32_bf16 v[124:127], v[144:147], v[184:187], v[124:127]
	v_mfma_f32_16x16x32_bf16 v[116:119], v[160:163], v[184:187], v[116:119]
	v_mfma_f32_16x16x32_bf16 v[108:111], v[144:147], v[192:195], v[108:111]
	v_mfma_f32_16x16x32_bf16 v[100:103], v[160:163], v[192:195], v[100:103]
	v_mfma_f32_16x16x32_bf16 v[92:95], v[144:147], v[200:203], v[92:95]
	v_mfma_f32_16x16x32_bf16 v[84:87], v[160:163], v[200:203], v[84:87]
	v_mfma_f32_16x16x32_bf16 v[76:79], v[144:147], v[208:211], v[76:79]
	v_mfma_f32_16x16x32_bf16 v[68:71], v[160:163], v[208:211], v[68:71]
	v_mfma_f32_16x16x32_bf16 v[124:127], v[156:159], v[188:191], v[124:127]
	v_mfma_f32_16x16x32_bf16 v[116:119], v[164:167], v[188:191], v[116:119]
	v_mfma_f32_16x16x32_bf16 v[108:111], v[156:159], v[196:199], v[108:111]
	v_mfma_f32_16x16x32_bf16 v[100:103], v[164:167], v[196:199], v[100:103]
	v_mfma_f32_16x16x32_bf16 v[92:95], v[156:159], v[204:207], v[92:95]
	v_mfma_f32_16x16x32_bf16 v[84:87], v[164:167], v[204:207], v[84:87]
	v_mfma_f32_16x16x32_bf16 v[76:79], v[156:159], v[212:215], v[76:79]
	v_mfma_f32_16x16x32_bf16 v[68:71], v[164:167], v[212:215], v[68:71]
	s_setprio 0
	s_setprio 1
	v_mfma_f32_16x16x32_bf16 v[120:123], v[168:171], v[184:187], v[120:123]
	v_mfma_f32_16x16x32_bf16 v[112:115], v[176:179], v[184:187], v[112:115]
	v_mfma_f32_16x16x32_bf16 v[104:107], v[168:171], v[192:195], v[104:107]
	v_mfma_f32_16x16x32_bf16 v[96:99], v[176:179], v[192:195], v[96:99]
	v_mfma_f32_16x16x32_bf16 v[88:91], v[168:171], v[200:203], v[88:91]
	v_mfma_f32_16x16x32_bf16 v[80:83], v[176:179], v[200:203], v[80:83]
	v_mfma_f32_16x16x32_bf16 v[72:75], v[168:171], v[208:211], v[72:75]
	v_mfma_f32_16x16x32_bf16 v[64:67], v[176:179], v[208:211], v[64:67]
	v_mfma_f32_16x16x32_bf16 v[120:123], v[172:175], v[188:191], v[120:123]
	v_mfma_f32_16x16x32_bf16 v[112:115], v[180:183], v[188:191], v[112:115]
	v_mfma_f32_16x16x32_bf16 v[104:107], v[172:175], v[196:199], v[104:107]
	v_mfma_f32_16x16x32_bf16 v[96:99], v[180:183], v[196:199], v[96:99]
	v_mfma_f32_16x16x32_bf16 v[88:91], v[172:175], v[204:207], v[88:91]
	v_mfma_f32_16x16x32_bf16 v[80:83], v[180:183], v[204:207], v[80:83]
	v_mfma_f32_16x16x32_bf16 v[72:75], v[172:175], v[212:215], v[72:75]
	v_mfma_f32_16x16x32_bf16 v[64:67], v[180:183], v[212:215], v[64:67]
	s_setprio 0
	s_barrier
; #define PG8_STAGE(bufoff, gbase, voff) do { _Pragma("unroll") for (int _i = 0; _i < 2; ++_i) \
;         __builtin_amdgcn_global_load_lds((const unsigned*)((const char*)(gbase) + (voff)[_i]), (PG8_LAS unsigned*)(lds + (bufoff) + ldsw + _i * 8192), 16, 0, 0); } while (0)
; #define PG8_LDA(dst, b, h) do { _Pragma("unroll") for (int m = 0; m < 4; ++m) _Pragma("unroll") for (int k = 0; k < 2; ++k) dst[m][k] = *(const PG8_LAS bf16x8*)(lds + PG8_SA(b, h) + aoff + m * 2048 + k * 1024); } while (0)
; #define PG8_MMA(ai, bj, At, Bt) do { __builtin_amdgcn_s_setprio(1); _Pragma("unroll") for (int m = 0; m < 4; ++m) _Pragma("unroll") for (int n = 0; n < 2; ++n) _Pragma("unroll") for (int k = 0; k < 2; ++k) \
;         acc[ai][bj][m][n] = __builtin_amdgcn_mfma_f32_16x16x32_bf16(Bt[n][k], At[m][k], acc[ai][bj][m][n], 0, 0, 0); __builtin_amdgcn_s_setprio(0); } while (0)
; #define PG8_WAIT_V(n) asm volatile("s_waitcnt vmcnt(" #n ")" ::: "memory")
; #define PG8_WAIT_L(n) asm volatile("s_waitcnt lgkmcnt(" #n ")" ::: "memory")
; #define PG8_BAR __builtin_amdgcn_s_barrier()
; #define PG8_SCHED __builtin_amdgcn_sched_barrier(0)
; template <class Epi, class Sched, bool ALIGN_EPI = false, bool SP2 = false>
; __device__ __forceinline__ void gemm_phase(PG8_LAS unsigned char* lds, const Gemm g, const Sched& S, const Epi& E, const int wid) {
;     ...
;         for (int t = 0; t < nt; t += 2) {
;             const bool last = (t == nt - 2);
;             const char* a1 = cA + (size_t)(t + 1) * kstep;
;             const char* a2 = last ? nA : cA + (size_t)(t + 2) * kstep; const char* b2 = last ? nB : cB + (size_t)(t + 2) * kstep;
;     ...
;             PG8_LDA(At, 1, 1); PG8_STAGE(PG8_SB(1, 0), b3, voffB); PG8_STAGE(PG8_SB(1, 1), b3 + hstep, voffB); PG8_STAGE(PG8_SA(1, 0), a3, voffA);
;             PG8_WAIT_V(8); PG8_WAIT_L(0); PG8_BAR; PG8_MMA(1, 0, At, B0); PG8_MMA(1, 1, At, B1); PG8_BAR; PG8_SCHED;
;     ...
;         if constexpr (ALIGN_EPI) { if (wr == 0) PG8_BAR; }
	ds_read_b128 v[184:187], v153 offset:49152
	ds_read_b128 v[188:191], v153 offset:50176
	ds_read_b128 v[192:195], v153 offset:51200
	ds_read_b128 v[196:199], v153 offset:52224
	ds_read_b128 v[200:203], v153 offset:53248
	ds_read_b128 v[204:207], v153 offset:54272
	ds_read_b128 v[208:211], v153 offset:55296
	ds_read_b128 v[212:215], v153 offset:56320
	s_add_i32 s28, s59, s33
	v_lshl_add_u64 v[148:149], v[148:149], 0, s[16:17]
	s_mov_b32 m0, s28
	s_nop 0
	global_load_lds_dwordx4 v[148:149], off
	s_add_i32 m0, s28, 0x2000
	s_add_u32 s6, s6, 0x100080
	v_lshl_add_u64 v[148:149], v[216:217], 0, s[16:17]
	s_addc_u32 s7, s7, 0
	s_add_i32 s28, s60, s33
	global_load_lds_dwordx4 v[148:149], off
	v_lshl_add_u64 v[148:149], s[6:7], 0, v[132:133]
	s_mov_b32 m0, s28
	s_nop 0
	global_load_lds_dwordx4 v[148:149], off
	v_lshl_add_u64 v[148:149], s[6:7], 0, v[128:129]
	s_add_i32 m0, s28, 0x2000
	s_nop 0
	global_load_lds_dwordx4 v[148:149], off
	v_lshl_add_u64 v[148:149], v[218:219], 0, s[16:17]
	s_mov_b32 m0, s48
	s_nop 0
	global_load_lds_dwordx4 v[148:149], off
	v_lshl_add_u64 v[148:149], v[220:221], 0, s[16:17]
	s_mov_b32 m0, s49
	s_nop 0
	global_load_lds_dwordx4 v[148:149], off
	s_waitcnt vmcnt(8)
	s_waitcnt lgkmcnt(0)
	s_barrier
	s_setprio 1
	s_waitcnt lgkmcnt(0)
	v_mfma_f32_16x16x32_bf16 v[60:63], v[144:147], v[184:187], v[60:63]
	v_mfma_f32_16x16x32_bf16 v[52:55], v[160:163], v[184:187], v[52:55]
	v_mfma_f32_16x16x32_bf16 v[44:47], v[144:147], v[192:195], v[44:47]
	v_mfma_f32_16x16x32_bf16 v[36:39], v[160:163], v[192:195], v[36:39]
	v_mfma_f32_16x16x32_bf16 v[28:31], v[144:147], v[200:203], v[28:31]
	v_mfma_f32_16x16x32_bf16 v[20:23], v[160:163], v[200:203], v[20:23]
	v_mfma_f32_16x16x32_bf16 v[12:15], v[144:147], v[208:211], v[12:15]
	v_mfma_f32_16x16x32_bf16 v[4:7], v[160:163], v[208:211], v[4:7]
	v_mfma_f32_16x16x32_bf16 v[60:63], v[156:159], v[188:191], v[60:63]
	v_mfma_f32_16x16x32_bf16 v[52:55], v[164:167], v[188:191], v[52:55]
	v_mfma_f32_16x16x32_bf16 v[44:47], v[156:159], v[196:199], v[44:47]
	v_mfma_f32_16x16x32_bf16 v[36:39], v[164:167], v[196:199], v[36:39]
	v_mfma_f32_16x16x32_bf16 v[28:31], v[156:159], v[204:207], v[28:31]
	v_mfma_f32_16x16x32_bf16 v[20:23], v[164:167], v[204:207], v[20:23]
	v_mfma_f32_16x16x32_bf16 v[12:15], v[156:159], v[212:215], v[12:15]
	v_mfma_f32_16x16x32_bf16 v[4:7], v[164:167], v[212:215], v[4:7]
	s_setprio 0
	s_setprio 1
	v_mfma_f32_16x16x32_bf16 v[56:59], v[168:171], v[184:187], v[56:59]
	v_mfma_f32_16x16x32_bf16 v[48:51], v[176:179], v[184:187], v[48:51]
	v_mfma_f32_16x16x32_bf16 v[40:43], v[168:171], v[192:195], v[40:43]
	v_mfma_f32_16x16x32_bf16 v[32:35], v[176:179], v[192:195], v[32:35]
	s_add_i32 s58, s58, 2
	s_add_u32 s2, s2, 0x100
	s_addc_u32 s3, s3, 0
	s_add_u32 s56, s56, 0x100
	s_addc_u32 s57, s57, 0
	s_cmp_gt_u32 s58, 61
	v_mfma_f32_16x16x32_bf16 v[24:27], v[168:171], v[200:203], v[24:27]
	v_mfma_f32_16x16x32_bf16 v[16:19], v[176:179], v[200:203], v[16:19]
	v_mfma_f32_16x16x32_bf16 v[8:11], v[168:171], v[208:211], v[8:11]
	v_mfma_f32_16x16x32_bf16 v[0:3], v[176:179], v[208:211], v[0:3]
	v_mfma_f32_16x16x32_bf16 v[56:59], v[172:175], v[188:191], v[56:59]
	v_mfma_f32_16x16x32_bf16 v[48:51], v[180:183], v[188:191], v[48:51]
	v_mfma_f32_16x16x32_bf16 v[40:43], v[172:175], v[196:199], v[40:43]
	v_mfma_f32_16x16x32_bf16 v[32:35], v[180:183], v[196:199], v[32:35]
	v_mfma_f32_16x16x32_bf16 v[24:27], v[172:175], v[204:207], v[24:27]
	v_mfma_f32_16x16x32_bf16 v[16:19], v[180:183], v[204:207], v[16:19]
	v_mfma_f32_16x16x32_bf16 v[8:11], v[172:175], v[212:215], v[8:11]
	v_mfma_f32_16x16x32_bf16 v[0:3], v[180:183], v[212:215], v[0:3]
	s_setprio 0
	s_barrier
	s_cbranch_scc0 .LBB0_2826
	s_and_b64 vcc, exec, s[18:19]
	s_cbranch_vccz .LBB0_2829
	s_barrier

; #define PG8_STAGE(bufoff, gbase, voff) do { _Pragma("unroll") for (int _i = 0; _i < 2; ++_i) \
;         __builtin_amdgcn_global_load_lds((const unsigned*)((const char*)(gbase) + (voff)[_i]), (PG8_LAS unsigned*)(lds + (bufoff) + ldsw + _i * 8192), 16, 0, 0); } while (0)
; #define PG8_LDA(dst, b, h) do { _Pragma("unroll") for (int m = 0; m < 4; ++m) _Pragma("unroll") for (int k = 0; k < 2; ++k) dst[m][k] = *(const PG8_LAS bf16x8*)(lds + PG8_SA(b, h) + aoff + m * 2048 + k * 1024); } while (0)
; #define PG8_LDB(dst, b, h) do { _Pragma("unroll") for (int n = 0; n < 2; ++n) _Pragma("unroll") for (int k = 0; k < 2; ++k) dst[n][k] = *(const PG8_LAS bf16x8*)(lds + PG8_SB(b, h) + boff + n * 2048 + k * 1024); } while (0)
; #define PG8_MMA(ai, bj, At, Bt) do { __builtin_amdgcn_s_setprio(1); _Pragma("unroll") for (int m = 0; m < 4; ++m) _Pragma("unroll") for (int n = 0; n < 2; ++n) _Pragma("unroll") for (int k = 0; k < 2; ++k) \
;         acc[ai][bj][m][n] = __builtin_amdgcn_mfma_f32_16x16x32_bf16(Bt[n][k], At[m][k], acc[ai][bj][m][n], 0, 0, 0); __builtin_amdgcn_s_setprio(0); } while (0)
; #define PG8_WAIT_V(n) asm volatile("s_waitcnt vmcnt(" #n ")" ::: "memory")
; #define PG8_WAIT_L(n) asm volatile("s_waitcnt lgkmcnt(" #n ")" ::: "memory")
; #define PG8_BAR __builtin_amdgcn_s_barrier()
; #define PG8_SCHED __builtin_amdgcn_sched_barrier(0)
; template <class Epi, class Sched, bool ALIGN_EPI = false, bool SP2 = false>
; __device__ __forceinline__ void gemm_phase(PG8_LAS unsigned char* lds, const Gemm g, const Sched& S, const Epi& E, const int wid) {
;     ...
;             const bool last = (t == nt - 2);
;             const char* a1 = cA + (size_t)(t + 1) * kstep;
;             const char* a2 = last ? nA : cA + (size_t)(t + 2) * kstep; const char* b2 = last ? nB : cB + (size_t)(t + 2) * kstep;
;             const char* a3 = a2 + kstep; const char* b3 = b2 + kstep;
;             if (last && has_next) S.a_ready(nxt);
;             if constexpr (SP2) {
;             PG8_LDB(B0, 0, 0); PG8_LDB(B1, 0, 1); PG8_SCHED; PG8_LDA(At, 0, 0); PG8_STAGE(PG8_SA(1, 1), a1 + hstep, voffA);
;             PG8_WAIT_V(8); PG8_WAIT_L(0); PG8_BAR; PG8_MMA(0, 0, At, B0); PG8_MMA(0, 1, At, B1); PG8_BAR; PG8_SCHED;
;             PG8_LDA(At, 0, 1); PG8_STAGE(PG8_SB(0, 0), b2, voffB); PG8_STAGE(PG8_SB(0, 1), b2 + hstep, voffB); PG8_STAGE(PG8_SA(0, 0), a2, voffA);
.LBB0_2852:
	ds_read_b128 v[148:151], v145
	ds_read_b128 v[152:155], v145 offset:1024
	ds_read_b128 v[156:159], v145 offset:2048
	ds_read_b128 v[160:163], v145 offset:3072
	ds_read_b128 v[164:167], v146
	ds_read_b128 v[168:171], v146 offset:1024
	ds_read_b128 v[172:175], v146 offset:2048
	ds_read_b128 v[176:179], v146 offset:3072
	ds_read_b128 v[180:183], v147
	ds_read_b128 v[184:187], v147 offset:1024
	ds_read_b128 v[188:191], v147 offset:2048
	ds_read_b128 v[192:195], v147 offset:3072
	ds_read_b128 v[196:199], v147 offset:4096
	ds_read_b128 v[200:203], v147 offset:5120
	ds_read_b128 v[204:207], v147 offset:6144
	ds_read_b128 v[208:211], v147 offset:7168
	s_add_i32 s65, s34, 2
	s_add_u32 s66, s30, 0x80
	s_addc_u32 s35, s31, 0
	s_cmp_eq_u32 s39, s34
	s_cselect_b32 s34, s0, s66
	s_cselect_b32 s35, s1, s35
	s_cselect_b32 s67, s29, s64
	s_cselect_b32 s66, s28, s63
	v_lshl_add_u64 v[212:213], s[30:31], 0, v[136:137]
	s_add_i32 m0, s46, 0xc000
	s_nop 0
	global_load_lds_dwordx4 v[212:213], off
	v_lshl_add_u64 v[212:213], s[30:31], 0, v[138:139]
	s_add_i32 m0, s46, 0xe000
	s_nop 0
	global_load_lds_dwordx4 v[212:213], off
	s_waitcnt vmcnt(8)
	s_waitcnt lgkmcnt(0)
	s_barrier
	s_setprio 1
	s_waitcnt lgkmcnt(0)
	v_mfma_f32_16x16x32_bf16 v[120:123], v[148:151], v[180:183], v[120:123]
	v_mfma_f32_16x16x32_bf16 v[124:127], v[156:159], v[180:183], v[124:127]
	v_mfma_f32_16x16x32_bf16 v[108:111], v[148:151], v[188:191], v[108:111]
	v_mfma_f32_16x16x32_bf16 v[104:107], v[156:159], v[188:191], v[104:107]
	v_mfma_f32_16x16x32_bf16 v[92:95], v[148:151], v[196:199], v[92:95]
	v_mfma_f32_16x16x32_bf16 v[88:91], v[156:159], v[196:199], v[88:91]
	v_mfma_f32_16x16x32_bf16 v[76:79], v[148:151], v[204:207], v[76:79]
	v_mfma_f32_16x16x32_bf16 v[72:75], v[156:159], v[204:207], v[72:75]
	v_mfma_f32_16x16x32_bf16 v[120:123], v[152:155], v[184:187], v[120:123]
	v_mfma_f32_16x16x32_bf16 v[124:127], v[160:163], v[184:187], v[124:127]
	v_mfma_f32_16x16x32_bf16 v[108:111], v[152:155], v[192:195], v[108:111]
	v_mfma_f32_16x16x32_bf16 v[104:107], v[160:163], v[192:195], v[104:107]
	v_mfma_f32_16x16x32_bf16 v[92:95], v[152:155], v[200:203], v[92:95]
	v_mfma_f32_16x16x32_bf16 v[88:91], v[160:163], v[200:203], v[88:91]
	v_mfma_f32_16x16x32_bf16 v[76:79], v[152:155], v[208:211], v[76:79]
	v_mfma_f32_16x16x32_bf16 v[72:75], v[160:163], v[208:211], v[72:75]
	s_setprio 0
	s_setprio 1
	v_mfma_f32_16x16x32_bf16 v[116:119], v[164:167], v[180:183], v[116:119]
	v_mfma_f32_16x16x32_bf16 v[112:115], v[172:175], v[180:183], v[112:115]
	v_mfma_f32_16x16x32_bf16 v[100:103], v[164:167], v[188:191], v[100:103]
	v_mfma_f32_16x16x32_bf16 v[96:99], v[172:175], v[188:191], v[96:99]
	v_mfma_f32_16x16x32_bf16 v[84:87], v[164:167], v[196:199], v[84:87]
	v_mfma_f32_16x16x32_bf16 v[80:83], v[172:175], v[196:199], v[80:83]
	v_mfma_f32_16x16x32_bf16 v[68:71], v[164:167], v[204:207], v[68:71]
	v_mfma_f32_16x16x32_bf16 v[64:67], v[172:175], v[204:207], v[64:67]
	v_mfma_f32_16x16x32_bf16 v[116:119], v[168:171], v[184:187], v[116:119]
	v_mfma_f32_16x16x32_bf16 v[112:115], v[176:179], v[184:187], v[112:115]
	v_mfma_f32_16x16x32_bf16 v[100:103], v[168:171], v[192:195], v[100:103]
	v_mfma_f32_16x16x32_bf16 v[96:99], v[176:179], v[192:195], v[96:99]
	v_mfma_f32_16x16x32_bf16 v[84:87], v[168:171], v[200:203], v[84:87]
	v_mfma_f32_16x16x32_bf16 v[80:83], v[176:179], v[200:203], v[80:83]
	v_mfma_f32_16x16x32_bf16 v[68:71], v[168:171], v[208:211], v[68:71]
	v_mfma_f32_16x16x32_bf16 v[64:67], v[176:179], v[208:211], v[64:67]
	s_setprio 0
	s_barrier
	ds_read_b128 v[180:183], v147 offset:16384
	ds_read_b128 v[184:187], v147 offset:17408
	ds_read_b128 v[188:191], v147 offset:18432
	ds_read_b128 v[192:195], v147 offset:19456
	ds_read_b128 v[196:199], v147 offset:20480
	ds_read_b128 v[200:203], v147 offset:21504
	ds_read_b128 v[204:207], v147 offset:22528
	ds_read_b128 v[208:211], v147 offset:23552
	s_add_i32 s68, s54, s33
	v_lshl_add_u64 v[212:213], s[66:67], 0, v[132:133]
	s_mov_b32 m0, s68
	s_nop 0
	global_load_lds_dwordx4 v[212:213], off
	s_add_i32 m0, s68, 0x2000
	v_lshl_add_u64 v[214:215], s[66:67], 0, v[128:129]
	s_add_u32 s66, s66, s2
	s_addc_u32 s67, s67, s3
	s_add_i32 s68, s55, s33
	global_load_lds_dwordx4 v[214:215], off
	v_lshl_add_u64 v[216:217], s[66:67], 0, v[132:133]
	s_mov_b32 m0, s68
	v_lshl_add_u64 v[218:219], s[66:67], 0, v[128:129]
	global_load_lds_dwordx4 v[216:217], off
	s_add_i32 m0, s68, 0x2000
	v_lshl_add_u64 v[220:221], s[34:35], 0, v[134:135]
	global_load_lds_dwordx4 v[218:219], off
	s_mov_b32 m0, s46
	v_lshl_add_u64 v[222:223], s[34:35], 0, v[130:131]
	global_load_lds_dwordx4 v[220:221], off
	s_mov_b32 m0, s47
	s_nop 0
	global_load_lds_dwordx4 v[222:223], off
	s_waitcnt vmcnt(8)
	s_waitcnt lgkmcnt(0)
	s_barrier
; #define PG8_STAGE(bufoff, gbase, voff) do { _Pragma("unroll") for (int _i = 0; _i < 2; ++_i) \
;         __builtin_amdgcn_global_load_lds((const unsigned*)((const char*)(gbase) + (voff)[_i]), (PG8_LAS unsigned*)(lds + (bufoff) + ldsw + _i * 8192), 16, 0, 0); } while (0)
; #define PG8_LDA(dst, b, h) do { _Pragma("unroll") for (int m = 0; m < 4; ++m) _Pragma("unroll") for (int k = 0; k < 2; ++k) dst[m][k] = *(const PG8_LAS bf16x8*)(lds + PG8_SA(b, h) + aoff + m * 2048 + k * 1024); } while (0)
; #define PG8_LDB(dst, b, h) do { _Pragma("unroll") for (int n = 0; n < 2; ++n) _Pragma("unroll") for (int k = 0; k < 2; ++k) dst[n][k] = *(const PG8_LAS bf16x8*)(lds + PG8_SB(b, h) + boff + n * 2048 + k * 1024); } while (0)
; #define PG8_MMA(ai, bj, At, Bt) do { __builtin_amdgcn_s_setprio(1); _Pragma("unroll") for (int m = 0; m < 4; ++m) _Pragma("unroll") for (int n = 0; n < 2; ++n) _Pragma("unroll") for (int k = 0; k < 2; ++k) \
;         acc[ai][bj][m][n] = __builtin_amdgcn_mfma_f32_16x16x32_bf16(Bt[n][k], At[m][k], acc[ai][bj][m][n], 0, 0, 0); __builtin_amdgcn_s_setprio(0); } while (0)
; #define PG8_WAIT_V(n) asm volatile("s_waitcnt vmcnt(" #n ")" ::: "memory")
; #define PG8_WAIT_L(n) asm volatile("s_waitcnt lgkmcnt(" #n ")" ::: "memory")
; #define PG8_BAR __builtin_amdgcn_s_barrier()
; #define PG8_SCHED __builtin_amdgcn_sched_barrier(0)
; template <class Epi, class Sched, bool ALIGN_EPI = false, bool SP2 = false>
; __device__ __forceinline__ void gemm_phase(PG8_LAS unsigned char* lds, const Gemm g, const Sched& S, const Epi& E, const int wid) {
;     ...
;             PG8_WAIT_V(8); PG8_WAIT_L(0); PG8_BAR; PG8_MMA(1, 0, At, B0); PG8_MMA(1, 1, At, B1); PG8_BAR; PG8_SCHED;
;             PG8_LDB(B0, 1, 0); PG8_LDB(B1, 1, 1); PG8_SCHED; PG8_LDA(At, 1, 0); PG8_STAGE(PG8_SA(0, 1), a2 + hstep, voffA);
;             PG8_WAIT_V(8); PG8_WAIT_L(0); PG8_BAR; PG8_MMA(0, 0, At, B0); PG8_MMA(0, 1, At, B1); PG8_BAR; PG8_SCHED;
	s_setprio 1
	s_waitcnt lgkmcnt(0)
	v_mfma_f32_16x16x32_bf16 v[60:63], v[148:151], v[180:183], v[60:63]
	v_mfma_f32_16x16x32_bf16 v[56:59], v[156:159], v[180:183], v[56:59]
	v_mfma_f32_16x16x32_bf16 v[44:47], v[148:151], v[188:191], v[44:47]
	v_mfma_f32_16x16x32_bf16 v[40:43], v[156:159], v[188:191], v[40:43]
	v_mfma_f32_16x16x32_bf16 v[28:31], v[148:151], v[196:199], v[28:31]
	v_mfma_f32_16x16x32_bf16 v[24:27], v[156:159], v[196:199], v[24:27]
	v_mfma_f32_16x16x32_bf16 v[12:15], v[148:151], v[204:207], v[12:15]
	v_mfma_f32_16x16x32_bf16 v[8:11], v[156:159], v[204:207], v[8:11]
	v_mfma_f32_16x16x32_bf16 v[60:63], v[152:155], v[184:187], v[60:63]
	v_mfma_f32_16x16x32_bf16 v[56:59], v[160:163], v[184:187], v[56:59]
	v_mfma_f32_16x16x32_bf16 v[44:47], v[152:155], v[192:195], v[44:47]
	v_mfma_f32_16x16x32_bf16 v[40:43], v[160:163], v[192:195], v[40:43]
	v_mfma_f32_16x16x32_bf16 v[28:31], v[152:155], v[200:203], v[28:31]
	v_mfma_f32_16x16x32_bf16 v[24:27], v[160:163], v[200:203], v[24:27]
	v_mfma_f32_16x16x32_bf16 v[12:15], v[152:155], v[208:211], v[12:15]
	v_mfma_f32_16x16x32_bf16 v[8:11], v[160:163], v[208:211], v[8:11]
	s_setprio 0
	s_setprio 1
	v_mfma_f32_16x16x32_bf16 v[52:55], v[164:167], v[180:183], v[52:55]
	v_mfma_f32_16x16x32_bf16 v[48:51], v[172:175], v[180:183], v[48:51]
	v_mfma_f32_16x16x32_bf16 v[36:39], v[164:167], v[188:191], v[36:39]
	v_mfma_f32_16x16x32_bf16 v[32:35], v[172:175], v[188:191], v[32:35]
	v_mfma_f32_16x16x32_bf16 v[20:23], v[164:167], v[196:199], v[20:23]
	v_mfma_f32_16x16x32_bf16 v[16:19], v[172:175], v[196:199], v[16:19]
	v_mfma_f32_16x16x32_bf16 v[4:7], v[164:167], v[204:207], v[4:7]
	v_mfma_f32_16x16x32_bf16 v[0:3], v[172:175], v[204:207], v[0:3]
	v_mfma_f32_16x16x32_bf16 v[52:55], v[168:171], v[184:187], v[52:55]
	v_mfma_f32_16x16x32_bf16 v[48:51], v[176:179], v[184:187], v[48:51]
	v_mfma_f32_16x16x32_bf16 v[36:39], v[168:171], v[192:195], v[36:39]
	v_mfma_f32_16x16x32_bf16 v[32:35], v[176:179], v[192:195], v[32:35]
	v_mfma_f32_16x16x32_bf16 v[20:23], v[168:171], v[200:203], v[20:23]
	v_mfma_f32_16x16x32_bf16 v[16:19], v[176:179], v[200:203], v[16:19]
	v_mfma_f32_16x16x32_bf16 v[4:7], v[168:171], v[208:211], v[4:7]
	v_mfma_f32_16x16x32_bf16 v[0:3], v[176:179], v[208:211], v[0:3]
	s_setprio 0
	s_barrier
	ds_read_b128 v[180:183], v147 offset:32768
	ds_read_b128 v[184:187], v147 offset:33792
	ds_read_b128 v[188:191], v147 offset:34816
	ds_read_b128 v[192:195], v147 offset:35840
	ds_read_b128 v[196:199], v147 offset:36864
	ds_read_b128 v[200:203], v147 offset:37888
	ds_read_b128 v[204:207], v147 offset:38912
	ds_read_b128 v[208:211], v147 offset:39936
	s_add_i32 s66, 0, 0x18000
	s_add_i32 s67, 0, 0x1c000
	v_add_u32_e32 v160, s66, v144
	v_add_u32_e32 v176, s67, v144
	ds_read_b128 v[148:151], v160
	ds_read_b128 v[152:155], v160 offset:1024
	ds_read_b128 v[156:159], v160 offset:2048
	ds_read_b128 v[160:163], v160 offset:3072
	ds_read_b128 v[164:167], v176
	ds_read_b128 v[168:171], v176 offset:1024
	ds_read_b128 v[172:175], v176 offset:2048
	ds_read_b128 v[176:179], v176 offset:3072
	s_add_u32 s34, s34, s2
	s_addc_u32 s35, s35, s3
	s_mov_b32 m0, s48
	v_lshl_add_u64 v[224:225], s[34:35], 0, v[134:135]
	global_load_lds_dwordx4 v[224:225], off
	v_lshl_add_u64 v[224:225], s[34:35], 0, v[130:131]
	s_mov_b32 m0, s49
	s_nop 0
	global_load_lds_dwordx4 v[224:225], off
	s_waitcnt vmcnt(8)
	s_waitcnt lgkmcnt(0)
	s_barrier
	s_setprio 1
	s_waitcnt lgkmcnt(0)
	v_mfma_f32_16x16x32_bf16 v[120:123], v[148:151], v[180:183], v[120:123]
	v_mfma_f32_16x16x32_bf16 v[124:127], v[156:159], v[180:183], v[124:127]
	v_mfma_f32_16x16x32_bf16 v[108:111], v[148:151], v[188:191], v[108:111]
	v_mfma_f32_16x16x32_bf16 v[104:107], v[156:159], v[188:191], v[104:107]
	v_mfma_f32_16x16x32_bf16 v[92:95], v[148:151], v[196:199], v[92:95]
	v_mfma_f32_16x16x32_bf16 v[88:91], v[156:159], v[196:199], v[88:91]
	v_mfma_f32_16x16x32_bf16 v[76:79], v[148:151], v[204:207], v[76:79]
	v_mfma_f32_16x16x32_bf16 v[72:75], v[156:159], v[204:207], v[72:75]
	v_mfma_f32_16x16x32_bf16 v[120:123], v[152:155], v[184:187], v[120:123]
	v_mfma_f32_16x16x32_bf16 v[124:127], v[160:163], v[184:187], v[124:127]
	v_mfma_f32_16x16x32_bf16 v[108:111], v[152:155], v[192:195], v[108:111]
	v_mfma_f32_16x16x32_bf16 v[104:107], v[160:163], v[192:195], v[104:107]
	v_mfma_f32_16x16x32_bf16 v[92:95], v[152:155], v[200:203], v[92:95]
	v_mfma_f32_16x16x32_bf16 v[88:91], v[160:163], v[200:203], v[88:91]
	v_mfma_f32_16x16x32_bf16 v[76:79], v[152:155], v[208:211], v[76:79]
	v_mfma_f32_16x16x32_bf16 v[72:75], v[160:163], v[208:211], v[72:75]
	s_setprio 0
	s_setprio 1
	v_mfma_f32_16x16x32_bf16 v[116:119], v[164:167], v[180:183], v[116:119]
	v_mfma_f32_16x16x32_bf16 v[112:115], v[172:175], v[180:183], v[112:115]
	v_mfma_f32_16x16x32_bf16 v[100:103], v[164:167], v[188:191], v[100:103]
	v_mfma_f32_16x16x32_bf16 v[96:99], v[172:175], v[188:191], v[96:99]
	v_mfma_f32_16x16x32_bf16 v[84:87], v[164:167], v[196:199], v[84:87]
	v_mfma_f32_16x16x32_bf16 v[80:83], v[172:175], v[196:199], v[80:83]
	v_mfma_f32_16x16x32_bf16 v[68:71], v[164:167], v[204:207], v[68:71]
	v_mfma_f32_16x16x32_bf16 v[64:67], v[172:175], v[204:207], v[64:67]
	v_mfma_f32_16x16x32_bf16 v[116:119], v[168:171], v[184:187], v[116:119]
	v_mfma_f32_16x16x32_bf16 v[112:115], v[176:179], v[184:187], v[112:115]
	v_mfma_f32_16x16x32_bf16 v[100:103], v[168:171], v[192:195], v[100:103]
	v_mfma_f32_16x16x32_bf16 v[96:99], v[176:179], v[192:195], v[96:99]
	v_mfma_f32_16x16x32_bf16 v[84:87], v[168:171], v[200:203], v[84:87]
	v_mfma_f32_16x16x32_bf16 v[80:83], v[176:179], v[200:203], v[80:83]
	v_mfma_f32_16x16x32_bf16 v[68:71], v[168:171], v[208:211], v[68:71]
	v_mfma_f32_16x16x32_bf16 v[64:67], v[176:179], v[208:211], v[64:67]
	s_setprio 0
	s_barrier
; #define PG8_STAGE(bufoff, gbase, voff) do { _Pragma("unroll") for (int _i = 0; _i < 2; ++_i) \
;         __builtin_amdgcn_global_load_lds((const unsigned*)((const char*)(gbase) + (voff)[_i]), (PG8_LAS unsigned*)(lds + (bufoff) + ldsw + _i * 8192), 16, 0, 0); } while (0)
; #define PG8_LDA(dst, b, h) do { _Pragma("unroll") for (int m = 0; m < 4; ++m) _Pragma("unroll") for (int k = 0; k < 2; ++k) dst[m][k] = *(const PG8_LAS bf16x8*)(lds + PG8_SA(b, h) + aoff + m * 2048 + k * 1024); } while (0)
; #define PG8_MMA(ai, bj, At, Bt) do { __builtin_amdgcn_s_setprio(1); _Pragma("unroll") for (int m = 0; m < 4; ++m) _Pragma("unroll") for (int n = 0; n < 2; ++n) _Pragma("unroll") for (int k = 0; k < 2; ++k) \
;         acc[ai][bj][m][n] = __builtin_amdgcn_mfma_f32_16x16x32_bf16(Bt[n][k], At[m][k], acc[ai][bj][m][n], 0, 0, 0); __builtin_amdgcn_s_setprio(0); } while (0)
; #define PG8_WAIT_V(n) asm volatile("s_waitcnt vmcnt(" #n ")" ::: "memory")
; #define PG8_WAIT_L(n) asm volatile("s_waitcnt lgkmcnt(" #n ")" ::: "memory")
; #define PG8_BAR __builtin_amdgcn_s_barrier()
; #define PG8_SCHED __builtin_amdgcn_sched_barrier(0)
; template <class Epi, class Sched, bool ALIGN_EPI = false, bool SP2 = false>
; __device__ __forceinline__ void gemm_phase(PG8_LAS unsigned char* lds, const Gemm g, const Sched& S, const Epi& E, const int wid) {
;     ...
;         for (int t = 0; t < nt; t += 2) {
;             const bool last = (t == nt - 2);
;             const char* a1 = cA + (size_t)(t + 1) * kstep;
;             const char* a2 = last ? nA : cA + (size_t)(t + 2) * kstep; const char* b2 = last ? nB : cB + (size_t)(t + 2) * kstep;
;     ...
;             PG8_LDA(At, 1, 1); PG8_STAGE(PG8_SB(1, 0), b3, voffB); PG8_STAGE(PG8_SB(1, 1), b3 + hstep, voffB); PG8_STAGE(PG8_SA(1, 0), a3, voffA);
;             PG8_WAIT_V(8); PG8_WAIT_L(0); PG8_BAR; PG8_MMA(1, 0, At, B0); PG8_MMA(1, 1, At, B1); PG8_BAR; PG8_SCHED;
	ds_read_b128 v[180:183], v147 offset:49152
	ds_read_b128 v[184:187], v147 offset:50176
	ds_read_b128 v[188:191], v147 offset:51200
	ds_read_b128 v[192:195], v147 offset:52224
	ds_read_b128 v[196:199], v147 offset:53248
	ds_read_b128 v[200:203], v147 offset:54272
	ds_read_b128 v[204:207], v147 offset:55296
	ds_read_b128 v[208:211], v147 offset:56320
	s_add_i32 s34, s66, s33
	v_lshl_add_u64 v[212:213], v[212:213], 0, s[14:15]
	s_mov_b32 m0, s34
	s_nop 0
	global_load_lds_dwordx4 v[212:213], off
	v_lshl_add_u64 v[212:213], v[214:215], 0, s[14:15]
	s_add_i32 m0, s34, 0x2000
	s_add_i32 s34, s67, s33
	global_load_lds_dwordx4 v[212:213], off
	v_lshl_add_u64 v[212:213], v[216:217], 0, s[14:15]
	s_mov_b32 m0, s34
	s_nop 0
	global_load_lds_dwordx4 v[212:213], off
	v_lshl_add_u64 v[212:213], v[218:219], 0, s[14:15]
	s_add_i32 m0, s34, 0x2000
	s_nop 0
	global_load_lds_dwordx4 v[212:213], off
	v_lshl_add_u64 v[212:213], v[220:221], 0, s[14:15]
	s_mov_b32 m0, s40
	s_nop 0
	global_load_lds_dwordx4 v[212:213], off
	v_lshl_add_u64 v[212:213], v[222:223], 0, s[14:15]
	s_mov_b32 m0, s51
	s_nop 0
	global_load_lds_dwordx4 v[212:213], off
	s_waitcnt vmcnt(8)
	s_waitcnt lgkmcnt(0)
	s_barrier
	s_setprio 1
	s_waitcnt lgkmcnt(0)
	v_mfma_f32_16x16x32_bf16 v[60:63], v[148:151], v[180:183], v[60:63]
	v_mfma_f32_16x16x32_bf16 v[56:59], v[156:159], v[180:183], v[56:59]
	v_mfma_f32_16x16x32_bf16 v[44:47], v[148:151], v[188:191], v[44:47]
	v_mfma_f32_16x16x32_bf16 v[40:43], v[156:159], v[188:191], v[40:43]
	v_mfma_f32_16x16x32_bf16 v[28:31], v[148:151], v[196:199], v[28:31]
	v_mfma_f32_16x16x32_bf16 v[24:27], v[156:159], v[196:199], v[24:27]
	v_mfma_f32_16x16x32_bf16 v[12:15], v[148:151], v[204:207], v[12:15]
	v_mfma_f32_16x16x32_bf16 v[8:11], v[156:159], v[204:207], v[8:11]
	v_mfma_f32_16x16x32_bf16 v[60:63], v[152:155], v[184:187], v[60:63]
	v_mfma_f32_16x16x32_bf16 v[56:59], v[160:163], v[184:187], v[56:59]
	v_mfma_f32_16x16x32_bf16 v[44:47], v[152:155], v[192:195], v[44:47]
	v_mfma_f32_16x16x32_bf16 v[40:43], v[160:163], v[192:195], v[40:43]
	v_mfma_f32_16x16x32_bf16 v[28:31], v[152:155], v[200:203], v[28:31]
	v_mfma_f32_16x16x32_bf16 v[24:27], v[160:163], v[200:203], v[24:27]
	v_mfma_f32_16x16x32_bf16 v[12:15], v[152:155], v[208:211], v[12:15]
	v_mfma_f32_16x16x32_bf16 v[8:11], v[160:163], v[208:211], v[8:11]
	s_setprio 0
	s_setprio 1
	v_mfma_f32_16x16x32_bf16 v[52:55], v[164:167], v[180:183], v[52:55]
	v_mfma_f32_16x16x32_bf16 v[48:51], v[172:175], v[180:183], v[48:51]
	v_mfma_f32_16x16x32_bf16 v[36:39], v[164:167], v[188:191], v[36:39]
	v_mfma_f32_16x16x32_bf16 v[32:35], v[172:175], v[188:191], v[32:35]
	s_add_u32 s30, s30, 0x100
	s_addc_u32 s31, s31, 0
	s_add_u32 s63, s63, 0x100
	s_addc_u32 s64, s64, 0
	s_cmp_ge_i32 s65, s52
	s_mov_b32 s34, s65
	v_mfma_f32_16x16x32_bf16 v[20:23], v[164:167], v[196:199], v[20:23]
	v_mfma_f32_16x16x32_bf16 v[16:19], v[172:175], v[196:199], v[16:19]
	v_mfma_f32_16x16x32_bf16 v[4:7], v[164:167], v[204:207], v[4:7]
	v_mfma_f32_16x16x32_bf16 v[0:3], v[172:175], v[204:207], v[0:3]
	v_mfma_f32_16x16x32_bf16 v[52:55], v[168:171], v[184:187], v[52:55]
	v_mfma_f32_16x16x32_bf16 v[48:51], v[176:179], v[184:187], v[48:51]
	v_mfma_f32_16x16x32_bf16 v[36:39], v[168:171], v[192:195], v[36:39]
	v_mfma_f32_16x16x32_bf16 v[32:35], v[176:179], v[192:195], v[32:35]
	v_mfma_f32_16x16x32_bf16 v[20:23], v[168:171], v[200:203], v[20:23]
	v_mfma_f32_16x16x32_bf16 v[16:19], v[176:179], v[200:203], v[16:19]
	v_mfma_f32_16x16x32_bf16 v[4:7], v[168:171], v[208:211], v[4:7]
	v_mfma_f32_16x16x32_bf16 v[0:3], v[176:179], v[208:211], v[0:3]
	s_setprio 0
	s_barrier
	s_cbranch_scc0 .LBB0_2852

; #define PG8_STAGE(bufoff, gbase, voff) do { _Pragma("unroll") for (int _i = 0; _i < 2; ++_i) \
;         __builtin_amdgcn_global_load_lds((const unsigned*)((const char*)(gbase) + (voff)[_i]), (PG8_LAS unsigned*)(lds + (bufoff) + ldsw + _i * 8192), 16, 0, 0); } while (0)
; #define PG8_LDA(dst, b, h) do { _Pragma("unroll") for (int m = 0; m < 4; ++m) _Pragma("unroll") for (int k = 0; k < 2; ++k) dst[m][k] = *(const PG8_LAS bf16x8*)(lds + PG8_SA(b, h) + aoff + m * 2048 + k * 1024); } while (0)
; #define PG8_LDB(dst, b, h) do { _Pragma("unroll") for (int n = 0; n < 2; ++n) _Pragma("unroll") for (int k = 0; k < 2; ++k) dst[n][k] = *(const PG8_LAS bf16x8*)(lds + PG8_SB(b, h) + boff + n * 2048 + k * 1024); } while (0)
; #define PG8_MMA(ai, bj, At, Bt) do { __builtin_amdgcn_s_setprio(1); _Pragma("unroll") for (int m = 0; m < 4; ++m) _Pragma("unroll") for (int n = 0; n < 2; ++n) _Pragma("unroll") for (int k = 0; k < 2; ++k) \
;         acc[ai][bj][m][n] = __builtin_amdgcn_mfma_f32_16x16x32_bf16(Bt[n][k], At[m][k], acc[ai][bj][m][n], 0, 0, 0); __builtin_amdgcn_s_setprio(0); } while (0)
; #define PG8_WAIT_V(n) asm volatile("s_waitcnt vmcnt(" #n ")" ::: "memory")
; #define PG8_WAIT_L(n) asm volatile("s_waitcnt lgkmcnt(" #n ")" ::: "memory")
; #define PG8_BAR __builtin_amdgcn_s_barrier()
; #define PG8_SCHED __builtin_amdgcn_sched_barrier(0)
; template <class Epi, class Sched, bool ALIGN_EPI = false, bool SP2 = false>
; __device__ __forceinline__ void gemm_phase(PG8_LAS unsigned char* lds, const Gemm g, const Sched& S, const Epi& E, const int wid) {
;     ...
;             const bool last = (t == nt - 2);
;             const char* a1 = cA + (size_t)(t + 1) * kstep;
;             const char* a2 = last ? nA : cA + (size_t)(t + 2) * kstep; const char* b2 = last ? nB : cB + (size_t)(t + 2) * kstep;
;             const char* a3 = a2 + kstep; const char* b3 = b2 + kstep;
;             if (last && has_next) S.a_ready(nxt);
;             if constexpr (SP2) {
;             PG8_LDB(B0, 0, 0); PG8_LDB(B1, 0, 1); PG8_SCHED; PG8_LDA(At, 0, 0); PG8_STAGE(PG8_SA(1, 1), a1 + hstep, voffA);
;             PG8_WAIT_V(8); PG8_WAIT_L(0); PG8_BAR; PG8_MMA(0, 0, At, B0); PG8_MMA(0, 1, At, B1); PG8_BAR; PG8_SCHED;
;             PG8_LDA(At, 0, 1); PG8_STAGE(PG8_SB(0, 0), b2, voffB); PG8_STAGE(PG8_SB(0, 1), b2 + hstep, voffB); PG8_STAGE(PG8_SA(0, 0), a2, voffA);
.LBB0_2935:
	ds_read_b128 v[128:131], v187
	ds_read_b128 v[132:135], v187 offset:1024
	ds_read_b128 v[136:139], v187 offset:2048
	ds_read_b128 v[140:143], v187 offset:3072
	ds_read_b128 v[144:147], v188
	ds_read_b128 v[148:151], v188 offset:1024
	ds_read_b128 v[168:171], v188 offset:2048
	ds_read_b128 v[172:175], v188 offset:3072
	ds_read_b128 v[176:179], v189
	ds_read_b128 v[180:183], v189 offset:1024
	ds_read_b128 v[192:195], v189 offset:2048
	ds_read_b128 v[196:199], v189 offset:3072
	ds_read_b128 v[200:203], v189 offset:4096
	ds_read_b128 v[204:207], v189 offset:5120
	ds_read_b128 v[208:211], v189 offset:6144
	ds_read_b128 v[212:215], v189 offset:7168
	s_add_u32 s0, s22, 0x100
	s_addc_u32 s1, s23, 0
	s_cmpk_eq_i32 s53, 0xa8
	s_cselect_b32 s27, s19, s1
	s_cselect_b32 s26, s18, s0
	s_cselect_b32 s25, s21, s52
	s_cselect_b32 s24, s20, s51
	v_lshl_add_u64 v[184:185], s[22:23], 0, v[160:161]
	s_add_i32 m0, s34, 0xc000
	s_nop 0
	global_load_lds_dwordx4 v[184:185], off
	v_lshl_add_u64 v[184:185], s[22:23], 0, v[162:163]
	s_add_i32 m0, s34, 0xe000
	s_nop 0
	global_load_lds_dwordx4 v[184:185], off
	s_waitcnt vmcnt(8)
	s_waitcnt lgkmcnt(0)
	s_barrier
	s_setprio 1
	s_waitcnt lgkmcnt(0)
	v_mfma_f32_16x16x32_bf16 v[124:127], v[128:131], v[176:179], v[124:127]
	v_mfma_f32_16x16x32_bf16 v[120:123], v[136:139], v[176:179], v[120:123]
	v_mfma_f32_16x16x32_bf16 v[108:111], v[128:131], v[192:195], v[108:111]
	v_mfma_f32_16x16x32_bf16 v[104:107], v[136:139], v[192:195], v[104:107]
	v_mfma_f32_16x16x32_bf16 v[92:95], v[128:131], v[200:203], v[92:95]
	v_mfma_f32_16x16x32_bf16 v[88:91], v[136:139], v[200:203], v[88:91]
	v_mfma_f32_16x16x32_bf16 v[76:79], v[128:131], v[208:211], v[76:79]
	v_mfma_f32_16x16x32_bf16 v[72:75], v[136:139], v[208:211], v[72:75]
	v_mfma_f32_16x16x32_bf16 v[124:127], v[132:135], v[180:183], v[124:127]
	v_mfma_f32_16x16x32_bf16 v[120:123], v[140:143], v[180:183], v[120:123]
	v_mfma_f32_16x16x32_bf16 v[108:111], v[132:135], v[196:199], v[108:111]
	v_mfma_f32_16x16x32_bf16 v[104:107], v[140:143], v[196:199], v[104:107]
	v_mfma_f32_16x16x32_bf16 v[92:95], v[132:135], v[204:207], v[92:95]
	v_mfma_f32_16x16x32_bf16 v[88:91], v[140:143], v[204:207], v[88:91]
	v_mfma_f32_16x16x32_bf16 v[76:79], v[132:135], v[212:215], v[76:79]
	v_mfma_f32_16x16x32_bf16 v[72:75], v[140:143], v[212:215], v[72:75]
	s_setprio 0
	s_setprio 1
	v_mfma_f32_16x16x32_bf16 v[116:119], v[144:147], v[176:179], v[116:119]
	v_mfma_f32_16x16x32_bf16 v[112:115], v[168:171], v[176:179], v[112:115]
	v_mfma_f32_16x16x32_bf16 v[100:103], v[144:147], v[192:195], v[100:103]
	v_mfma_f32_16x16x32_bf16 v[96:99], v[168:171], v[192:195], v[96:99]
	v_mfma_f32_16x16x32_bf16 v[84:87], v[144:147], v[200:203], v[84:87]
	v_mfma_f32_16x16x32_bf16 v[80:83], v[168:171], v[200:203], v[80:83]
	v_mfma_f32_16x16x32_bf16 v[68:71], v[144:147], v[208:211], v[68:71]
	v_mfma_f32_16x16x32_bf16 v[64:67], v[168:171], v[208:211], v[64:67]
	v_mfma_f32_16x16x32_bf16 v[116:119], v[148:151], v[180:183], v[116:119]
	v_mfma_f32_16x16x32_bf16 v[112:115], v[172:175], v[180:183], v[112:115]
	v_mfma_f32_16x16x32_bf16 v[100:103], v[148:151], v[196:199], v[100:103]
	v_mfma_f32_16x16x32_bf16 v[96:99], v[172:175], v[196:199], v[96:99]
	v_mfma_f32_16x16x32_bf16 v[84:87], v[148:151], v[204:207], v[84:87]
	v_mfma_f32_16x16x32_bf16 v[80:83], v[172:175], v[204:207], v[80:83]
	v_mfma_f32_16x16x32_bf16 v[68:71], v[148:151], v[212:215], v[68:71]
	v_mfma_f32_16x16x32_bf16 v[64:67], v[172:175], v[212:215], v[64:67]
	s_setprio 0
	s_barrier
	ds_read_b128 v[176:179], v189 offset:16384
	ds_read_b128 v[180:183], v189 offset:17408
	ds_read_b128 v[192:195], v189 offset:18432
	ds_read_b128 v[196:199], v189 offset:19456
	ds_read_b128 v[200:203], v189 offset:20480
	ds_read_b128 v[204:207], v189 offset:21504
	ds_read_b128 v[208:211], v189 offset:22528
	ds_read_b128 v[212:215], v189 offset:23552
	s_add_i32 s22, s45, s33
	v_lshl_add_u64 v[184:185], s[24:25], 0, v[154:155]
	s_mov_b32 m0, s22
	s_nop 0
	global_load_lds_dwordx4 v[184:185], off
	s_add_i32 m0, s22, 0x2000
	s_add_u32 s22, s24, 0x2b0000
	v_lshl_add_u64 v[216:217], s[24:25], 0, v[158:159]
	s_addc_u32 s23, s25, 0
	s_add_i32 s54, s46, s33
	global_load_lds_dwordx4 v[216:217], off
	v_lshl_add_u64 v[218:219], s[22:23], 0, v[154:155]
	s_mov_b32 m0, s54
	v_lshl_add_u64 v[220:221], s[26:27], 0, v[156:157]
	global_load_lds_dwordx4 v[218:219], off
	v_lshl_add_u64 v[218:219], s[22:23], 0, v[158:159]
	s_add_i32 m0, s54, 0x2000
	s_nop 0
	global_load_lds_dwordx4 v[218:219], off
	v_lshl_add_u64 v[218:219], s[26:27], 0, v[152:153]
	s_mov_b32 m0, s34
	s_nop 0
	global_load_lds_dwordx4 v[218:219], off
	s_mov_b32 m0, s35
	s_nop 0
	global_load_lds_dwordx4 v[220:221], off
	s_waitcnt vmcnt(8)
	s_waitcnt lgkmcnt(0)
	s_barrier
; #define PG8_STAGE(bufoff, gbase, voff) do { _Pragma("unroll") for (int _i = 0; _i < 2; ++_i) \
;         __builtin_amdgcn_global_load_lds((const unsigned*)((const char*)(gbase) + (voff)[_i]), (PG8_LAS unsigned*)(lds + (bufoff) + ldsw + _i * 8192), 16, 0, 0); } while (0)
; #define PG8_LDA(dst, b, h) do { _Pragma("unroll") for (int m = 0; m < 4; ++m) _Pragma("unroll") for (int k = 0; k < 2; ++k) dst[m][k] = *(const PG8_LAS bf16x8*)(lds + PG8_SA(b, h) + aoff + m * 2048 + k * 1024); } while (0)
; #define PG8_LDB(dst, b, h) do { _Pragma("unroll") for (int n = 0; n < 2; ++n) _Pragma("unroll") for (int k = 0; k < 2; ++k) dst[n][k] = *(const PG8_LAS bf16x8*)(lds + PG8_SB(b, h) + boff + n * 2048 + k * 1024); } while (0)
; #define PG8_MMA(ai, bj, At, Bt) do { __builtin_amdgcn_s_setprio(1); _Pragma("unroll") for (int m = 0; m < 4; ++m) _Pragma("unroll") for (int n = 0; n < 2; ++n) _Pragma("unroll") for (int k = 0; k < 2; ++k) \
;         acc[ai][bj][m][n] = __builtin_amdgcn_mfma_f32_16x16x32_bf16(Bt[n][k], At[m][k], acc[ai][bj][m][n], 0, 0, 0); __builtin_amdgcn_s_setprio(0); } while (0)
; #define PG8_WAIT_V(n) asm volatile("s_waitcnt vmcnt(" #n ")" ::: "memory")
; #define PG8_WAIT_L(n) asm volatile("s_waitcnt lgkmcnt(" #n ")" ::: "memory")
; #define PG8_BAR __builtin_amdgcn_s_barrier()
; #define PG8_SCHED __builtin_amdgcn_sched_barrier(0)
; template <class Epi, class Sched, bool ALIGN_EPI = false, bool SP2 = false>
; __device__ __forceinline__ void gemm_phase(PG8_LAS unsigned char* lds, const Gemm g, const Sched& S, const Epi& E, const int wid) {
;     ...
;             PG8_WAIT_V(8); PG8_WAIT_L(0); PG8_BAR; PG8_MMA(1, 0, At, B0); PG8_MMA(1, 1, At, B1); PG8_BAR; PG8_SCHED;
;             PG8_LDB(B0, 1, 0); PG8_LDB(B1, 1, 1); PG8_SCHED; PG8_LDA(At, 1, 0); PG8_STAGE(PG8_SA(0, 1), a2 + hstep, voffA);
;             PG8_WAIT_V(8); PG8_WAIT_L(0); PG8_BAR; PG8_MMA(0, 0, At, B0); PG8_MMA(0, 1, At, B1); PG8_BAR; PG8_SCHED;
	s_setprio 1
	s_waitcnt lgkmcnt(0)
	v_mfma_f32_16x16x32_bf16 v[60:63], v[128:131], v[176:179], v[60:63]
	v_mfma_f32_16x16x32_bf16 v[56:59], v[136:139], v[176:179], v[56:59]
	v_mfma_f32_16x16x32_bf16 v[44:47], v[128:131], v[192:195], v[44:47]
	v_mfma_f32_16x16x32_bf16 v[40:43], v[136:139], v[192:195], v[40:43]
	v_mfma_f32_16x16x32_bf16 v[28:31], v[128:131], v[200:203], v[28:31]
	v_mfma_f32_16x16x32_bf16 v[24:27], v[136:139], v[200:203], v[24:27]
	v_mfma_f32_16x16x32_bf16 v[12:15], v[128:131], v[208:211], v[12:15]
	v_mfma_f32_16x16x32_bf16 v[8:11], v[136:139], v[208:211], v[8:11]
	v_mfma_f32_16x16x32_bf16 v[60:63], v[132:135], v[180:183], v[60:63]
	v_mfma_f32_16x16x32_bf16 v[56:59], v[140:143], v[180:183], v[56:59]
	v_mfma_f32_16x16x32_bf16 v[44:47], v[132:135], v[196:199], v[44:47]
	v_mfma_f32_16x16x32_bf16 v[40:43], v[140:143], v[196:199], v[40:43]
	v_mfma_f32_16x16x32_bf16 v[28:31], v[132:135], v[204:207], v[28:31]
	v_mfma_f32_16x16x32_bf16 v[24:27], v[140:143], v[204:207], v[24:27]
	v_mfma_f32_16x16x32_bf16 v[12:15], v[132:135], v[212:215], v[12:15]
	v_mfma_f32_16x16x32_bf16 v[8:11], v[140:143], v[212:215], v[8:11]
	s_setprio 0
	s_setprio 1
	v_mfma_f32_16x16x32_bf16 v[52:55], v[144:147], v[176:179], v[52:55]
	v_mfma_f32_16x16x32_bf16 v[48:51], v[168:171], v[176:179], v[48:51]
	v_mfma_f32_16x16x32_bf16 v[36:39], v[144:147], v[192:195], v[36:39]
	v_mfma_f32_16x16x32_bf16 v[32:35], v[168:171], v[192:195], v[32:35]
	v_mfma_f32_16x16x32_bf16 v[20:23], v[144:147], v[200:203], v[20:23]
	v_mfma_f32_16x16x32_bf16 v[16:19], v[168:171], v[200:203], v[16:19]
	v_mfma_f32_16x16x32_bf16 v[4:7], v[144:147], v[208:211], v[4:7]
	v_mfma_f32_16x16x32_bf16 v[0:3], v[168:171], v[208:211], v[0:3]
	v_mfma_f32_16x16x32_bf16 v[52:55], v[148:151], v[180:183], v[52:55]
	v_mfma_f32_16x16x32_bf16 v[48:51], v[172:175], v[180:183], v[48:51]
	v_mfma_f32_16x16x32_bf16 v[36:39], v[148:151], v[196:199], v[36:39]
	v_mfma_f32_16x16x32_bf16 v[32:35], v[172:175], v[196:199], v[32:35]
	v_mfma_f32_16x16x32_bf16 v[20:23], v[148:151], v[204:207], v[20:23]
	v_mfma_f32_16x16x32_bf16 v[16:19], v[172:175], v[204:207], v[16:19]
	v_mfma_f32_16x16x32_bf16 v[4:7], v[148:151], v[212:215], v[4:7]
	v_mfma_f32_16x16x32_bf16 v[0:3], v[172:175], v[212:215], v[0:3]
	s_setprio 0
	s_barrier
	ds_read_b128 v[176:179], v189 offset:32768
	ds_read_b128 v[180:183], v189 offset:33792
	ds_read_b128 v[192:195], v189 offset:34816
	ds_read_b128 v[196:199], v189 offset:35840
	ds_read_b128 v[200:203], v189 offset:36864
	ds_read_b128 v[204:207], v189 offset:37888
	ds_read_b128 v[208:211], v189 offset:38912
	ds_read_b128 v[212:215], v189 offset:39936
	s_add_i32 s54, 0, 0x18000
	s_add_i32 s55, 0, 0x1c000
	v_add_u32_e32 v140, s54, v186
	v_add_u32_e32 v172, s55, v186
	ds_read_b128 v[128:131], v140
	ds_read_b128 v[132:135], v140 offset:1024
	ds_read_b128 v[136:139], v140 offset:2048
	ds_read_b128 v[140:143], v140 offset:3072
	ds_read_b128 v[144:147], v172
	ds_read_b128 v[148:151], v172 offset:1024
	ds_read_b128 v[168:171], v172 offset:2048
	ds_read_b128 v[172:175], v172 offset:3072
	s_add_u32 s22, s26, 0x2b0000
	s_addc_u32 s23, s27, 0
	s_mov_b32 m0, s36
	v_lshl_add_u64 v[222:223], s[22:23], 0, v[152:153]
	global_load_lds_dwordx4 v[222:223], off
	v_lshl_add_u64 v[222:223], s[22:23], 0, v[156:157]
	s_mov_b32 m0, s37
	s_nop 0
	global_load_lds_dwordx4 v[222:223], off
	s_waitcnt vmcnt(8)
	s_waitcnt lgkmcnt(0)
	s_barrier
	s_setprio 1
	s_waitcnt lgkmcnt(0)
	v_mfma_f32_16x16x32_bf16 v[124:127], v[128:131], v[176:179], v[124:127]
	v_mfma_f32_16x16x32_bf16 v[120:123], v[136:139], v[176:179], v[120:123]
	v_mfma_f32_16x16x32_bf16 v[108:111], v[128:131], v[192:195], v[108:111]
	v_mfma_f32_16x16x32_bf16 v[104:107], v[136:139], v[192:195], v[104:107]
	v_mfma_f32_16x16x32_bf16 v[92:95], v[128:131], v[200:203], v[92:95]
	v_mfma_f32_16x16x32_bf16 v[88:91], v[136:139], v[200:203], v[88:91]
	v_mfma_f32_16x16x32_bf16 v[76:79], v[128:131], v[208:211], v[76:79]
	v_mfma_f32_16x16x32_bf16 v[72:75], v[136:139], v[208:211], v[72:75]
	v_mfma_f32_16x16x32_bf16 v[124:127], v[132:135], v[180:183], v[124:127]
	v_mfma_f32_16x16x32_bf16 v[120:123], v[140:143], v[180:183], v[120:123]
	v_mfma_f32_16x16x32_bf16 v[108:111], v[132:135], v[196:199], v[108:111]
	v_mfma_f32_16x16x32_bf16 v[104:107], v[140:143], v[196:199], v[104:107]
	v_mfma_f32_16x16x32_bf16 v[92:95], v[132:135], v[204:207], v[92:95]
	v_mfma_f32_16x16x32_bf16 v[88:91], v[140:143], v[204:207], v[88:91]
	v_mfma_f32_16x16x32_bf16 v[76:79], v[132:135], v[212:215], v[76:79]
	v_mfma_f32_16x16x32_bf16 v[72:75], v[140:143], v[212:215], v[72:75]
	s_setprio 0
	s_setprio 1
	v_mfma_f32_16x16x32_bf16 v[116:119], v[144:147], v[176:179], v[116:119]
	v_mfma_f32_16x16x32_bf16 v[112:115], v[168:171], v[176:179], v[112:115]
	v_mfma_f32_16x16x32_bf16 v[100:103], v[144:147], v[192:195], v[100:103]
	v_mfma_f32_16x16x32_bf16 v[96:99], v[168:171], v[192:195], v[96:99]
	v_mfma_f32_16x16x32_bf16 v[84:87], v[144:147], v[200:203], v[84:87]
	v_mfma_f32_16x16x32_bf16 v[80:83], v[168:171], v[200:203], v[80:83]
	v_mfma_f32_16x16x32_bf16 v[68:71], v[144:147], v[208:211], v[68:71]
	v_mfma_f32_16x16x32_bf16 v[64:67], v[168:171], v[208:211], v[64:67]
	v_mfma_f32_16x16x32_bf16 v[116:119], v[148:151], v[180:183], v[116:119]
	v_mfma_f32_16x16x32_bf16 v[112:115], v[172:175], v[180:183], v[112:115]
	v_mfma_f32_16x16x32_bf16 v[100:103], v[148:151], v[196:199], v[100:103]
	v_mfma_f32_16x16x32_bf16 v[96:99], v[172:175], v[196:199], v[96:99]
	v_mfma_f32_16x16x32_bf16 v[84:87], v[148:151], v[204:207], v[84:87]
	v_mfma_f32_16x16x32_bf16 v[80:83], v[172:175], v[204:207], v[80:83]
	v_mfma_f32_16x16x32_bf16 v[68:71], v[148:151], v[212:215], v[68:71]
	v_mfma_f32_16x16x32_bf16 v[64:67], v[172:175], v[212:215], v[64:67]
	s_setprio 0
	s_barrier
; #define PG8_STAGE(bufoff, gbase, voff) do { _Pragma("unroll") for (int _i = 0; _i < 2; ++_i) \
;         __builtin_amdgcn_global_load_lds((const unsigned*)((const char*)(gbase) + (voff)[_i]), (PG8_LAS unsigned*)(lds + (bufoff) + ldsw + _i * 8192), 16, 0, 0); } while (0)
; #define PG8_LDA(dst, b, h) do { _Pragma("unroll") for (int m = 0; m < 4; ++m) _Pragma("unroll") for (int k = 0; k < 2; ++k) dst[m][k] = *(const PG8_LAS bf16x8*)(lds + PG8_SA(b, h) + aoff + m * 2048 + k * 1024); } while (0)
; #define PG8_MMA(ai, bj, At, Bt) do { __builtin_amdgcn_s_setprio(1); _Pragma("unroll") for (int m = 0; m < 4; ++m) _Pragma("unroll") for (int n = 0; n < 2; ++n) _Pragma("unroll") for (int k = 0; k < 2; ++k) \
;         acc[ai][bj][m][n] = __builtin_amdgcn_mfma_f32_16x16x32_bf16(Bt[n][k], At[m][k], acc[ai][bj][m][n], 0, 0, 0); __builtin_amdgcn_s_setprio(0); } while (0)
; #define PG8_WAIT_V(n) asm volatile("s_waitcnt vmcnt(" #n ")" ::: "memory")
; #define PG8_WAIT_L(n) asm volatile("s_waitcnt lgkmcnt(" #n ")" ::: "memory")
; #define PG8_BAR __builtin_amdgcn_s_barrier()
; #define PG8_SCHED __builtin_amdgcn_sched_barrier(0)
; template <class Epi, class Sched, bool ALIGN_EPI = false, bool SP2 = false>
; __device__ __forceinline__ void gemm_phase(PG8_LAS unsigned char* lds, const Gemm g, const Sched& S, const Epi& E, const int wid) {
;     ...
;         for (int t = 0; t < nt; t += 2) {
;             const bool last = (t == nt - 2);
;             const char* a1 = cA + (size_t)(t + 1) * kstep;
;             const char* a2 = last ? nA : cA + (size_t)(t + 2) * kstep; const char* b2 = last ? nB : cB + (size_t)(t + 2) * kstep;
;     ...
;             PG8_LDA(At, 1, 1); PG8_STAGE(PG8_SB(1, 0), b3, voffB); PG8_STAGE(PG8_SB(1, 1), b3 + hstep, voffB); PG8_STAGE(PG8_SA(1, 0), a3, voffA);
;             PG8_WAIT_V(8); PG8_WAIT_L(0); PG8_BAR; PG8_MMA(1, 0, At, B0); PG8_MMA(1, 1, At, B1); PG8_BAR; PG8_SCHED;
;     ...
;         if constexpr (ALIGN_EPI) { if (wr == 0) PG8_BAR; }
	ds_read_b128 v[176:179], v189 offset:49152
	ds_read_b128 v[180:183], v189 offset:50176
	ds_read_b128 v[192:195], v189 offset:51200
	ds_read_b128 v[196:199], v189 offset:52224
	ds_read_b128 v[200:203], v189 offset:53248
	ds_read_b128 v[204:207], v189 offset:54272
	ds_read_b128 v[208:211], v189 offset:55296
	ds_read_b128 v[212:215], v189 offset:56320
	s_add_i32 s22, s54, s33
	v_lshl_add_u64 v[184:185], v[184:185], 0, s[14:15]
	s_mov_b32 m0, s22
	s_nop 0
	global_load_lds_dwordx4 v[184:185], off
	s_add_i32 m0, s22, 0x2000
	s_add_u32 s22, s24, 0x2b0080
	v_lshl_add_u64 v[184:185], v[216:217], 0, s[14:15]
	s_addc_u32 s23, s25, 0
	s_add_i32 s24, s55, s33
	global_load_lds_dwordx4 v[184:185], off
	v_lshl_add_u64 v[184:185], s[22:23], 0, v[154:155]
	s_mov_b32 m0, s24
	s_nop 0
	global_load_lds_dwordx4 v[184:185], off
	v_lshl_add_u64 v[184:185], s[22:23], 0, v[158:159]
	s_add_i32 m0, s24, 0x2000
	s_nop 0
	global_load_lds_dwordx4 v[184:185], off
	v_lshl_add_u64 v[184:185], v[218:219], 0, s[14:15]
	s_mov_b32 m0, s41
	s_nop 0
	global_load_lds_dwordx4 v[184:185], off
	v_lshl_add_u64 v[184:185], v[220:221], 0, s[14:15]
	s_mov_b32 m0, s42
	s_nop 0
	global_load_lds_dwordx4 v[184:185], off
	s_waitcnt vmcnt(8)
	s_waitcnt lgkmcnt(0)
	s_barrier
	s_setprio 1
	s_waitcnt lgkmcnt(0)
	v_mfma_f32_16x16x32_bf16 v[60:63], v[128:131], v[176:179], v[60:63]
	v_mfma_f32_16x16x32_bf16 v[56:59], v[136:139], v[176:179], v[56:59]
	v_mfma_f32_16x16x32_bf16 v[44:47], v[128:131], v[192:195], v[44:47]
	v_mfma_f32_16x16x32_bf16 v[40:43], v[136:139], v[192:195], v[40:43]
	v_mfma_f32_16x16x32_bf16 v[28:31], v[128:131], v[200:203], v[28:31]
	v_mfma_f32_16x16x32_bf16 v[24:27], v[136:139], v[200:203], v[24:27]
	v_mfma_f32_16x16x32_bf16 v[12:15], v[128:131], v[208:211], v[12:15]
	v_mfma_f32_16x16x32_bf16 v[8:11], v[136:139], v[208:211], v[8:11]
	v_mfma_f32_16x16x32_bf16 v[60:63], v[132:135], v[180:183], v[60:63]
	v_mfma_f32_16x16x32_bf16 v[56:59], v[140:143], v[180:183], v[56:59]
	v_mfma_f32_16x16x32_bf16 v[44:47], v[132:135], v[196:199], v[44:47]
	v_mfma_f32_16x16x32_bf16 v[40:43], v[140:143], v[196:199], v[40:43]
	v_mfma_f32_16x16x32_bf16 v[28:31], v[132:135], v[204:207], v[28:31]
	v_mfma_f32_16x16x32_bf16 v[24:27], v[140:143], v[204:207], v[24:27]
	v_mfma_f32_16x16x32_bf16 v[12:15], v[132:135], v[212:215], v[12:15]
	v_mfma_f32_16x16x32_bf16 v[8:11], v[140:143], v[212:215], v[8:11]
	s_setprio 0
	s_setprio 1
	v_mfma_f32_16x16x32_bf16 v[52:55], v[144:147], v[176:179], v[52:55]
	v_mfma_f32_16x16x32_bf16 v[48:51], v[168:171], v[176:179], v[48:51]
	v_mfma_f32_16x16x32_bf16 v[36:39], v[144:147], v[192:195], v[36:39]
	v_mfma_f32_16x16x32_bf16 v[32:35], v[168:171], v[192:195], v[32:35]
	s_add_i32 s53, s53, 2
	s_add_u32 s51, s51, 0x100
	s_addc_u32 s52, s52, 0
	s_cmpk_gt_u32 s53, 0xa9
	s_mov_b64 s[22:23], s[0:1]
	v_mfma_f32_16x16x32_bf16 v[20:23], v[144:147], v[200:203], v[20:23]
	v_mfma_f32_16x16x32_bf16 v[16:19], v[168:171], v[200:203], v[16:19]
	v_mfma_f32_16x16x32_bf16 v[4:7], v[144:147], v[208:211], v[4:7]
	v_mfma_f32_16x16x32_bf16 v[0:3], v[168:171], v[208:211], v[0:3]
	v_mfma_f32_16x16x32_bf16 v[52:55], v[148:151], v[180:183], v[52:55]
	v_mfma_f32_16x16x32_bf16 v[48:51], v[172:175], v[180:183], v[48:51]
	v_mfma_f32_16x16x32_bf16 v[36:39], v[148:151], v[196:199], v[36:39]
	v_mfma_f32_16x16x32_bf16 v[32:35], v[172:175], v[196:199], v[32:35]
	v_mfma_f32_16x16x32_bf16 v[20:23], v[148:151], v[204:207], v[20:23]
	v_mfma_f32_16x16x32_bf16 v[16:19], v[172:175], v[204:207], v[16:19]
	v_mfma_f32_16x16x32_bf16 v[4:7], v[148:151], v[212:215], v[4:7]
	v_mfma_f32_16x16x32_bf16 v[0:3], v[172:175], v[212:215], v[0:3]
	s_setprio 0
	s_barrier
	s_cbranch_scc0 .LBB0_2935
	s_and_b64 vcc, exec, s[16:17]
	s_cbranch_vccz .LBB0_2938
	s_barrier

; #define PG8_STAGE(bufoff, gbase, voff) do { _Pragma("unroll") for (int _i = 0; _i < 2; ++_i) \
;         __builtin_amdgcn_global_load_lds((const unsigned*)((const char*)(gbase) + (voff)[_i]), (PG8_LAS unsigned*)(lds + (bufoff) + ldsw + _i * 8192), 16, 0, 0); } while (0)
; #define PG8_LDA(dst, b, h) do { _Pragma("unroll") for (int m = 0; m < 4; ++m) _Pragma("unroll") for (int k = 0; k < 2; ++k) dst[m][k] = *(const PG8_LAS bf16x8*)(lds + PG8_SA(b, h) + aoff + m * 2048 + k * 1024); } while (0)
; #define PG8_LDB(dst, b, h) do { _Pragma("unroll") for (int n = 0; n < 2; ++n) _Pragma("unroll") for (int k = 0; k < 2; ++k) dst[n][k] = *(const PG8_LAS bf16x8*)(lds + PG8_SB(b, h) + boff + n * 2048 + k * 1024); } while (0)
; #define PG8_MMA(ai, bj, At, Bt) do { __builtin_amdgcn_s_setprio(1); _Pragma("unroll") for (int m = 0; m < 4; ++m) _Pragma("unroll") for (int n = 0; n < 2; ++n) _Pragma("unroll") for (int k = 0; k < 2; ++k) \
;         acc[ai][bj][m][n] = __builtin_amdgcn_mfma_f32_16x16x32_bf16(Bt[n][k], At[m][k], acc[ai][bj][m][n], 0, 0, 0); __builtin_amdgcn_s_setprio(0); } while (0)
; #define PG8_WAIT_V(n) asm volatile("s_waitcnt vmcnt(" #n ")" ::: "memory")
; #define PG8_WAIT_L(n) asm volatile("s_waitcnt lgkmcnt(" #n ")" ::: "memory")
; #define PG8_BAR __builtin_amdgcn_s_barrier()
; #define PG8_SCHED __builtin_amdgcn_sched_barrier(0)
; template <class Epi, class Sched, bool ALIGN_EPI = false, bool SP2 = false>
; __device__ __forceinline__ void gemm_phase(PG8_LAS unsigned char* lds, const Gemm g, const Sched& S, const Epi& E, const int wid) {
;     ...
;             const bool last = (t == nt - 2);
;             const char* a1 = cA + (size_t)(t + 1) * kstep;
;             const char* a2 = last ? nA : cA + (size_t)(t + 2) * kstep; const char* b2 = last ? nB : cB + (size_t)(t + 2) * kstep;
;             const char* a3 = a2 + kstep; const char* b3 = b2 + kstep;
;             if (last && has_next) S.a_ready(nxt);
;             if constexpr (SP2) {
;             PG8_LDB(B0, 0, 0); PG8_LDB(B1, 0, 1); PG8_SCHED; PG8_LDA(At, 0, 0); PG8_STAGE(PG8_SA(1, 1), a1 + hstep, voffA);
;             PG8_WAIT_V(8); PG8_WAIT_L(0); PG8_BAR; PG8_MMA(0, 0, At, B0); PG8_MMA(0, 1, At, B1); PG8_BAR; PG8_SCHED;
;             PG8_LDA(At, 0, 1); PG8_STAGE(PG8_SB(0, 0), b2, voffB); PG8_STAGE(PG8_SB(0, 1), b2 + hstep, voffB); PG8_STAGE(PG8_SA(0, 0), a2, voffA);
.LBB0_3030:
	ds_read_b128 v[128:131], v181
	ds_read_b128 v[132:135], v181 offset:1024
	ds_read_b128 v[136:139], v181 offset:2048
	ds_read_b128 v[140:143], v181 offset:3072
	ds_read_b128 v[144:147], v182
	ds_read_b128 v[148:151], v182 offset:1024
	ds_read_b128 v[168:171], v182 offset:2048
	ds_read_b128 v[172:175], v182 offset:3072
	ds_read_b128 v[176:179], v183
	ds_read_b128 v[186:189], v183 offset:1024
	ds_read_b128 v[190:193], v183 offset:2048
	ds_read_b128 v[194:197], v183 offset:3072
	ds_read_b128 v[198:201], v183 offset:4096
	ds_read_b128 v[202:205], v183 offset:5120
	ds_read_b128 v[206:209], v183 offset:6144
	ds_read_b128 v[210:213], v183 offset:7168
	s_add_u32 s36, s34, 0xfff00080
	s_addc_u32 s37, s35, -1
	s_cmp_eq_u32 s57, 60
	s_cselect_b32 s39, s1, s37
	s_cselect_b32 s38, s7, s36
	s_cselect_b32 s37, s25, s56
	s_cselect_b32 s36, s27, s55
	v_lshl_add_u64 v[214:215], s[34:35], 0, v[160:161]
	s_add_i32 m0, s42, 0xc000
	s_nop 0
	global_load_lds_dwordx4 v[214:215], off
	v_lshl_add_u64 v[214:215], s[34:35], 0, v[162:163]
	s_add_i32 m0, s42, 0xe000
	s_nop 0
	global_load_lds_dwordx4 v[214:215], off
	s_waitcnt vmcnt(8)
	s_waitcnt lgkmcnt(0)
	s_barrier
	s_setprio 1
	s_waitcnt lgkmcnt(0)
	v_mfma_f32_16x16x32_bf16 v[124:127], v[128:131], v[176:179], v[124:127]
	v_mfma_f32_16x16x32_bf16 v[120:123], v[136:139], v[176:179], v[120:123]
	v_mfma_f32_16x16x32_bf16 v[108:111], v[128:131], v[190:193], v[108:111]
	v_mfma_f32_16x16x32_bf16 v[104:107], v[136:139], v[190:193], v[104:107]
	v_mfma_f32_16x16x32_bf16 v[92:95], v[128:131], v[198:201], v[92:95]
	v_mfma_f32_16x16x32_bf16 v[88:91], v[136:139], v[198:201], v[88:91]
	v_mfma_f32_16x16x32_bf16 v[76:79], v[128:131], v[206:209], v[76:79]
	v_mfma_f32_16x16x32_bf16 v[72:75], v[136:139], v[206:209], v[72:75]
	v_mfma_f32_16x16x32_bf16 v[124:127], v[132:135], v[186:189], v[124:127]
	v_mfma_f32_16x16x32_bf16 v[120:123], v[140:143], v[186:189], v[120:123]
	v_mfma_f32_16x16x32_bf16 v[108:111], v[132:135], v[194:197], v[108:111]
	v_mfma_f32_16x16x32_bf16 v[104:107], v[140:143], v[194:197], v[104:107]
	v_mfma_f32_16x16x32_bf16 v[92:95], v[132:135], v[202:205], v[92:95]
	v_mfma_f32_16x16x32_bf16 v[88:91], v[140:143], v[202:205], v[88:91]
	v_mfma_f32_16x16x32_bf16 v[76:79], v[132:135], v[210:213], v[76:79]
	v_mfma_f32_16x16x32_bf16 v[72:75], v[140:143], v[210:213], v[72:75]
	s_setprio 0
	s_setprio 1
	v_mfma_f32_16x16x32_bf16 v[116:119], v[144:147], v[176:179], v[116:119]
	v_mfma_f32_16x16x32_bf16 v[112:115], v[168:171], v[176:179], v[112:115]
	v_mfma_f32_16x16x32_bf16 v[100:103], v[144:147], v[190:193], v[100:103]
	v_mfma_f32_16x16x32_bf16 v[96:99], v[168:171], v[190:193], v[96:99]
	v_mfma_f32_16x16x32_bf16 v[84:87], v[144:147], v[198:201], v[84:87]
	v_mfma_f32_16x16x32_bf16 v[80:83], v[168:171], v[198:201], v[80:83]
	v_mfma_f32_16x16x32_bf16 v[68:71], v[144:147], v[206:209], v[68:71]
	v_mfma_f32_16x16x32_bf16 v[64:67], v[168:171], v[206:209], v[64:67]
	v_mfma_f32_16x16x32_bf16 v[116:119], v[148:151], v[186:189], v[116:119]
	v_mfma_f32_16x16x32_bf16 v[112:115], v[172:175], v[186:189], v[112:115]
	v_mfma_f32_16x16x32_bf16 v[100:103], v[148:151], v[194:197], v[100:103]
	v_mfma_f32_16x16x32_bf16 v[96:99], v[172:175], v[194:197], v[96:99]
	v_mfma_f32_16x16x32_bf16 v[84:87], v[148:151], v[202:205], v[84:87]
	v_mfma_f32_16x16x32_bf16 v[80:83], v[172:175], v[202:205], v[80:83]
	v_mfma_f32_16x16x32_bf16 v[68:71], v[148:151], v[210:213], v[68:71]
	v_mfma_f32_16x16x32_bf16 v[64:67], v[172:175], v[210:213], v[64:67]
	s_setprio 0
	s_barrier
	ds_read_b128 v[176:179], v183 offset:16384
	ds_read_b128 v[186:189], v183 offset:17408
	ds_read_b128 v[190:193], v183 offset:18432
	ds_read_b128 v[194:197], v183 offset:19456
	ds_read_b128 v[198:201], v183 offset:20480
	ds_read_b128 v[202:205], v183 offset:21504
	ds_read_b128 v[206:209], v183 offset:22528
	ds_read_b128 v[210:213], v183 offset:23552
	s_add_i32 s58, s53, s41
	v_lshl_add_u64 v[214:215], s[36:37], 0, v[154:155]
	s_mov_b32 m0, s58
	s_nop 0
	global_load_lds_dwordx4 v[214:215], off
	s_add_i32 m0, s58, 0x2000
	s_add_u32 s58, s36, 0x100000
	v_lshl_add_u64 v[216:217], s[36:37], 0, v[158:159]
	s_addc_u32 s59, s37, 0
	s_add_i32 s60, s54, s41
	global_load_lds_dwordx4 v[216:217], off
	v_lshl_add_u64 v[218:219], s[58:59], 0, v[154:155]
	s_mov_b32 m0, s60
	v_lshl_add_u64 v[220:221], s[38:39], 0, v[156:157]
	global_load_lds_dwordx4 v[218:219], off
	v_lshl_add_u64 v[218:219], s[58:59], 0, v[158:159]
	s_add_i32 m0, s60, 0x2000
	s_nop 0
	global_load_lds_dwordx4 v[218:219], off
	v_lshl_add_u64 v[218:219], s[38:39], 0, v[152:153]
	s_mov_b32 m0, s42
	s_nop 0
	global_load_lds_dwordx4 v[218:219], off
	s_mov_b32 m0, s43
	s_nop 0
	global_load_lds_dwordx4 v[220:221], off
	s_waitcnt vmcnt(8)
	s_waitcnt lgkmcnt(0)
	s_barrier
; #define PG8_STAGE(bufoff, gbase, voff) do { _Pragma("unroll") for (int _i = 0; _i < 2; ++_i) \
;         __builtin_amdgcn_global_load_lds((const unsigned*)((const char*)(gbase) + (voff)[_i]), (PG8_LAS unsigned*)(lds + (bufoff) + ldsw + _i * 8192), 16, 0, 0); } while (0)
; #define PG8_LDA(dst, b, h) do { _Pragma("unroll") for (int m = 0; m < 4; ++m) _Pragma("unroll") for (int k = 0; k < 2; ++k) dst[m][k] = *(const PG8_LAS bf16x8*)(lds + PG8_SA(b, h) + aoff + m * 2048 + k * 1024); } while (0)
; #define PG8_LDB(dst, b, h) do { _Pragma("unroll") for (int n = 0; n < 2; ++n) _Pragma("unroll") for (int k = 0; k < 2; ++k) dst[n][k] = *(const PG8_LAS bf16x8*)(lds + PG8_SB(b, h) + boff + n * 2048 + k * 1024); } while (0)
; #define PG8_MMA(ai, bj, At, Bt) do { __builtin_amdgcn_s_setprio(1); _Pragma("unroll") for (int m = 0; m < 4; ++m) _Pragma("unroll") for (int n = 0; n < 2; ++n) _Pragma("unroll") for (int k = 0; k < 2; ++k) \
;         acc[ai][bj][m][n] = __builtin_amdgcn_mfma_f32_16x16x32_bf16(Bt[n][k], At[m][k], acc[ai][bj][m][n], 0, 0, 0); __builtin_amdgcn_s_setprio(0); } while (0)
; #define PG8_WAIT_V(n) asm volatile("s_waitcnt vmcnt(" #n ")" ::: "memory")
; #define PG8_WAIT_L(n) asm volatile("s_waitcnt lgkmcnt(" #n ")" ::: "memory")
; #define PG8_BAR __builtin_amdgcn_s_barrier()
; #define PG8_SCHED __builtin_amdgcn_sched_barrier(0)
; template <class Epi, class Sched, bool ALIGN_EPI = false, bool SP2 = false>
; __device__ __forceinline__ void gemm_phase(PG8_LAS unsigned char* lds, const Gemm g, const Sched& S, const Epi& E, const int wid) {
;     ...
;             PG8_WAIT_V(8); PG8_WAIT_L(0); PG8_BAR; PG8_MMA(1, 0, At, B0); PG8_MMA(1, 1, At, B1); PG8_BAR; PG8_SCHED;
;             PG8_LDB(B0, 1, 0); PG8_LDB(B1, 1, 1); PG8_SCHED; PG8_LDA(At, 1, 0); PG8_STAGE(PG8_SA(0, 1), a2 + hstep, voffA);
;             PG8_WAIT_V(8); PG8_WAIT_L(0); PG8_BAR; PG8_MMA(0, 0, At, B0); PG8_MMA(0, 1, At, B1); PG8_BAR; PG8_SCHED;
	s_setprio 1
	s_waitcnt lgkmcnt(0)
	v_mfma_f32_16x16x32_bf16 v[60:63], v[128:131], v[176:179], v[60:63]
	v_mfma_f32_16x16x32_bf16 v[56:59], v[136:139], v[176:179], v[56:59]
	v_mfma_f32_16x16x32_bf16 v[44:47], v[128:131], v[190:193], v[44:47]
	v_mfma_f32_16x16x32_bf16 v[40:43], v[136:139], v[190:193], v[40:43]
	v_mfma_f32_16x16x32_bf16 v[28:31], v[128:131], v[198:201], v[28:31]
	v_mfma_f32_16x16x32_bf16 v[24:27], v[136:139], v[198:201], v[24:27]
	v_mfma_f32_16x16x32_bf16 v[12:15], v[128:131], v[206:209], v[12:15]
	v_mfma_f32_16x16x32_bf16 v[8:11], v[136:139], v[206:209], v[8:11]
	v_mfma_f32_16x16x32_bf16 v[60:63], v[132:135], v[186:189], v[60:63]
	v_mfma_f32_16x16x32_bf16 v[56:59], v[140:143], v[186:189], v[56:59]
	v_mfma_f32_16x16x32_bf16 v[44:47], v[132:135], v[194:197], v[44:47]
	v_mfma_f32_16x16x32_bf16 v[40:43], v[140:143], v[194:197], v[40:43]
	v_mfma_f32_16x16x32_bf16 v[28:31], v[132:135], v[202:205], v[28:31]
	v_mfma_f32_16x16x32_bf16 v[24:27], v[140:143], v[202:205], v[24:27]
	v_mfma_f32_16x16x32_bf16 v[12:15], v[132:135], v[210:213], v[12:15]
	v_mfma_f32_16x16x32_bf16 v[8:11], v[140:143], v[210:213], v[8:11]
	s_setprio 0
	s_setprio 1
	v_mfma_f32_16x16x32_bf16 v[52:55], v[144:147], v[176:179], v[52:55]
	v_mfma_f32_16x16x32_bf16 v[48:51], v[168:171], v[176:179], v[48:51]
	v_mfma_f32_16x16x32_bf16 v[36:39], v[144:147], v[190:193], v[36:39]
	v_mfma_f32_16x16x32_bf16 v[32:35], v[168:171], v[190:193], v[32:35]
	v_mfma_f32_16x16x32_bf16 v[20:23], v[144:147], v[198:201], v[20:23]
	v_mfma_f32_16x16x32_bf16 v[16:19], v[168:171], v[198:201], v[16:19]
	v_mfma_f32_16x16x32_bf16 v[4:7], v[144:147], v[206:209], v[4:7]
	v_mfma_f32_16x16x32_bf16 v[0:3], v[168:171], v[206:209], v[0:3]
	v_mfma_f32_16x16x32_bf16 v[52:55], v[148:151], v[186:189], v[52:55]
	v_mfma_f32_16x16x32_bf16 v[48:51], v[172:175], v[186:189], v[48:51]
	v_mfma_f32_16x16x32_bf16 v[36:39], v[148:151], v[194:197], v[36:39]
	v_mfma_f32_16x16x32_bf16 v[32:35], v[172:175], v[194:197], v[32:35]
	v_mfma_f32_16x16x32_bf16 v[20:23], v[148:151], v[202:205], v[20:23]
	v_mfma_f32_16x16x32_bf16 v[16:19], v[172:175], v[202:205], v[16:19]
	v_mfma_f32_16x16x32_bf16 v[4:7], v[148:151], v[210:213], v[4:7]
	v_mfma_f32_16x16x32_bf16 v[0:3], v[172:175], v[210:213], v[0:3]
	s_setprio 0
	s_barrier
	ds_read_b128 v[176:179], v183 offset:32768
	ds_read_b128 v[186:189], v183 offset:33792
	ds_read_b128 v[190:193], v183 offset:34816
	ds_read_b128 v[194:197], v183 offset:35840
	ds_read_b128 v[198:201], v183 offset:36864
	ds_read_b128 v[202:205], v183 offset:37888
	ds_read_b128 v[206:209], v183 offset:38912
	ds_read_b128 v[210:213], v183 offset:39936
	s_add_i32 s58, 0, 0x18000
	s_add_i32 s59, 0, 0x1c000
	v_add_u32_e32 v140, s58, v180
	v_add_u32_e32 v172, s59, v180
	ds_read_b128 v[128:131], v140
	ds_read_b128 v[132:135], v140 offset:1024
	ds_read_b128 v[136:139], v140 offset:2048
	ds_read_b128 v[140:143], v140 offset:3072
	ds_read_b128 v[144:147], v172
	ds_read_b128 v[148:151], v172 offset:1024
	ds_read_b128 v[168:171], v172 offset:2048
	ds_read_b128 v[172:175], v172 offset:3072
	s_add_u32 s38, s38, 0x100000
	s_addc_u32 s39, s39, 0
	s_mov_b32 m0, s44
	v_lshl_add_u64 v[222:223], s[38:39], 0, v[152:153]
	global_load_lds_dwordx4 v[222:223], off
	v_lshl_add_u64 v[222:223], s[38:39], 0, v[156:157]
	s_mov_b32 m0, s45
	s_nop 0
	global_load_lds_dwordx4 v[222:223], off
	s_waitcnt vmcnt(8)
	s_waitcnt lgkmcnt(0)
	s_barrier
	s_setprio 1
	s_waitcnt lgkmcnt(0)
	v_mfma_f32_16x16x32_bf16 v[124:127], v[128:131], v[176:179], v[124:127]
	v_mfma_f32_16x16x32_bf16 v[120:123], v[136:139], v[176:179], v[120:123]
	v_mfma_f32_16x16x32_bf16 v[108:111], v[128:131], v[190:193], v[108:111]
	v_mfma_f32_16x16x32_bf16 v[104:107], v[136:139], v[190:193], v[104:107]
	v_mfma_f32_16x16x32_bf16 v[92:95], v[128:131], v[198:201], v[92:95]
	v_mfma_f32_16x16x32_bf16 v[88:91], v[136:139], v[198:201], v[88:91]
	v_mfma_f32_16x16x32_bf16 v[76:79], v[128:131], v[206:209], v[76:79]
	v_mfma_f32_16x16x32_bf16 v[72:75], v[136:139], v[206:209], v[72:75]
	v_mfma_f32_16x16x32_bf16 v[124:127], v[132:135], v[186:189], v[124:127]
	v_mfma_f32_16x16x32_bf16 v[120:123], v[140:143], v[186:189], v[120:123]
	v_mfma_f32_16x16x32_bf16 v[108:111], v[132:135], v[194:197], v[108:111]
	v_mfma_f32_16x16x32_bf16 v[104:107], v[140:143], v[194:197], v[104:107]
	v_mfma_f32_16x16x32_bf16 v[92:95], v[132:135], v[202:205], v[92:95]
	v_mfma_f32_16x16x32_bf16 v[88:91], v[140:143], v[202:205], v[88:91]
	v_mfma_f32_16x16x32_bf16 v[76:79], v[132:135], v[210:213], v[76:79]
	v_mfma_f32_16x16x32_bf16 v[72:75], v[140:143], v[210:213], v[72:75]
	s_setprio 0
	s_setprio 1
	v_mfma_f32_16x16x32_bf16 v[116:119], v[144:147], v[176:179], v[116:119]
	v_mfma_f32_16x16x32_bf16 v[112:115], v[168:171], v[176:179], v[112:115]
	v_mfma_f32_16x16x32_bf16 v[100:103], v[144:147], v[190:193], v[100:103]
	v_mfma_f32_16x16x32_bf16 v[96:99], v[168:171], v[190:193], v[96:99]
	v_mfma_f32_16x16x32_bf16 v[84:87], v[144:147], v[198:201], v[84:87]
	v_mfma_f32_16x16x32_bf16 v[80:83], v[168:171], v[198:201], v[80:83]
	v_mfma_f32_16x16x32_bf16 v[68:71], v[144:147], v[206:209], v[68:71]
	v_mfma_f32_16x16x32_bf16 v[64:67], v[168:171], v[206:209], v[64:67]
	v_mfma_f32_16x16x32_bf16 v[116:119], v[148:151], v[186:189], v[116:119]
	v_mfma_f32_16x16x32_bf16 v[112:115], v[172:175], v[186:189], v[112:115]
	v_mfma_f32_16x16x32_bf16 v[100:103], v[148:151], v[194:197], v[100:103]
	v_mfma_f32_16x16x32_bf16 v[96:99], v[172:175], v[194:197], v[96:99]
	v_mfma_f32_16x16x32_bf16 v[84:87], v[148:151], v[202:205], v[84:87]
	v_mfma_f32_16x16x32_bf16 v[80:83], v[172:175], v[202:205], v[80:83]
	v_mfma_f32_16x16x32_bf16 v[68:71], v[148:151], v[210:213], v[68:71]
	v_mfma_f32_16x16x32_bf16 v[64:67], v[172:175], v[210:213], v[64:67]
	s_setprio 0
	s_barrier
; #define PG8_STAGE(bufoff, gbase, voff) do { _Pragma("unroll") for (int _i = 0; _i < 2; ++_i) \
;         __builtin_amdgcn_global_load_lds((const unsigned*)((const char*)(gbase) + (voff)[_i]), (PG8_LAS unsigned*)(lds + (bufoff) + ldsw + _i * 8192), 16, 0, 0); } while (0)
; #define PG8_LDA(dst, b, h) do { _Pragma("unroll") for (int m = 0; m < 4; ++m) _Pragma("unroll") for (int k = 0; k < 2; ++k) dst[m][k] = *(const PG8_LAS bf16x8*)(lds + PG8_SA(b, h) + aoff + m * 2048 + k * 1024); } while (0)
; #define PG8_MMA(ai, bj, At, Bt) do { __builtin_amdgcn_s_setprio(1); _Pragma("unroll") for (int m = 0; m < 4; ++m) _Pragma("unroll") for (int n = 0; n < 2; ++n) _Pragma("unroll") for (int k = 0; k < 2; ++k) \
;         acc[ai][bj][m][n] = __builtin_amdgcn_mfma_f32_16x16x32_bf16(Bt[n][k], At[m][k], acc[ai][bj][m][n], 0, 0, 0); __builtin_amdgcn_s_setprio(0); } while (0)
; #define PG8_WAIT_V(n) asm volatile("s_waitcnt vmcnt(" #n ")" ::: "memory")
; #define PG8_WAIT_L(n) asm volatile("s_waitcnt lgkmcnt(" #n ")" ::: "memory")
; #define PG8_BAR __builtin_amdgcn_s_barrier()
; #define PG8_SCHED __builtin_amdgcn_sched_barrier(0)
; template <class Epi, class Sched, bool ALIGN_EPI = false, bool SP2 = false>
; __device__ __forceinline__ void gemm_phase(PG8_LAS unsigned char* lds, const Gemm g, const Sched& S, const Epi& E, const int wid) {
;     ...
;         for (int t = 0; t < nt; t += 2) {
;             const bool last = (t == nt - 2);
;             const char* a1 = cA + (size_t)(t + 1) * kstep;
;             const char* a2 = last ? nA : cA + (size_t)(t + 2) * kstep; const char* b2 = last ? nB : cB + (size_t)(t + 2) * kstep;
;     ...
;             PG8_LDA(At, 1, 1); PG8_STAGE(PG8_SB(1, 0), b3, voffB); PG8_STAGE(PG8_SB(1, 1), b3 + hstep, voffB); PG8_STAGE(PG8_SA(1, 0), a3, voffA);
;             PG8_WAIT_V(8); PG8_WAIT_L(0); PG8_BAR; PG8_MMA(1, 0, At, B0); PG8_MMA(1, 1, At, B1); PG8_BAR; PG8_SCHED;
;     ...
;         if constexpr (ALIGN_EPI) { if (wr == 0) PG8_BAR; }
	ds_read_b128 v[176:179], v183 offset:49152
	ds_read_b128 v[186:189], v183 offset:50176
	ds_read_b128 v[190:193], v183 offset:51200
	ds_read_b128 v[194:197], v183 offset:52224
	ds_read_b128 v[198:201], v183 offset:53248
	ds_read_b128 v[202:205], v183 offset:54272
	ds_read_b128 v[206:209], v183 offset:55296
	ds_read_b128 v[210:213], v183 offset:56320
	s_add_i32 s38, s58, s41
	v_lshl_add_u64 v[214:215], v[214:215], 0, s[20:21]
	s_mov_b32 m0, s38
	s_nop 0
	global_load_lds_dwordx4 v[214:215], off
	s_add_i32 m0, s38, 0x2000
	s_add_u32 s36, s36, 0x100080
	v_lshl_add_u64 v[214:215], v[216:217], 0, s[20:21]
	s_addc_u32 s37, s37, 0
	s_add_i32 s38, s59, s41
	global_load_lds_dwordx4 v[214:215], off
	v_lshl_add_u64 v[214:215], s[36:37], 0, v[154:155]
	s_mov_b32 m0, s38
	s_nop 0
	global_load_lds_dwordx4 v[214:215], off
	v_lshl_add_u64 v[214:215], s[36:37], 0, v[158:159]
	s_add_i32 m0, s38, 0x2000
	s_nop 0
	global_load_lds_dwordx4 v[214:215], off
	v_lshl_add_u64 v[214:215], v[218:219], 0, s[20:21]
	s_mov_b32 m0, s49
	s_nop 0
	global_load_lds_dwordx4 v[214:215], off
	v_lshl_add_u64 v[214:215], v[220:221], 0, s[20:21]
	s_mov_b32 m0, s50
	s_nop 0
	global_load_lds_dwordx4 v[214:215], off
	s_waitcnt vmcnt(8)
	s_waitcnt lgkmcnt(0)
	s_barrier
	s_setprio 1
	s_waitcnt lgkmcnt(0)
	v_mfma_f32_16x16x32_bf16 v[60:63], v[128:131], v[176:179], v[60:63]
	v_mfma_f32_16x16x32_bf16 v[56:59], v[136:139], v[176:179], v[56:59]
	v_mfma_f32_16x16x32_bf16 v[44:47], v[128:131], v[190:193], v[44:47]
	v_mfma_f32_16x16x32_bf16 v[40:43], v[136:139], v[190:193], v[40:43]
	v_mfma_f32_16x16x32_bf16 v[28:31], v[128:131], v[198:201], v[28:31]
	v_mfma_f32_16x16x32_bf16 v[24:27], v[136:139], v[198:201], v[24:27]
	v_mfma_f32_16x16x32_bf16 v[12:15], v[128:131], v[206:209], v[12:15]
	v_mfma_f32_16x16x32_bf16 v[8:11], v[136:139], v[206:209], v[8:11]
	v_mfma_f32_16x16x32_bf16 v[60:63], v[132:135], v[186:189], v[60:63]
	v_mfma_f32_16x16x32_bf16 v[56:59], v[140:143], v[186:189], v[56:59]
	v_mfma_f32_16x16x32_bf16 v[44:47], v[132:135], v[194:197], v[44:47]
	v_mfma_f32_16x16x32_bf16 v[40:43], v[140:143], v[194:197], v[40:43]
	v_mfma_f32_16x16x32_bf16 v[28:31], v[132:135], v[202:205], v[28:31]
	v_mfma_f32_16x16x32_bf16 v[24:27], v[140:143], v[202:205], v[24:27]
	v_mfma_f32_16x16x32_bf16 v[12:15], v[132:135], v[210:213], v[12:15]
	v_mfma_f32_16x16x32_bf16 v[8:11], v[140:143], v[210:213], v[8:11]
	s_setprio 0
	s_setprio 1
	v_mfma_f32_16x16x32_bf16 v[52:55], v[144:147], v[176:179], v[52:55]
	v_mfma_f32_16x16x32_bf16 v[48:51], v[168:171], v[176:179], v[48:51]
	v_mfma_f32_16x16x32_bf16 v[36:39], v[144:147], v[190:193], v[36:39]
	v_mfma_f32_16x16x32_bf16 v[32:35], v[168:171], v[190:193], v[32:35]
	s_add_i32 s57, s57, 2
	s_add_u32 s34, s34, 0x100
	s_addc_u32 s35, s35, 0
	s_add_u32 s55, s55, 0x100
	s_addc_u32 s56, s56, 0
	s_cmp_gt_u32 s57, 61
	v_mfma_f32_16x16x32_bf16 v[20:23], v[144:147], v[198:201], v[20:23]
	v_mfma_f32_16x16x32_bf16 v[16:19], v[168:171], v[198:201], v[16:19]
	v_mfma_f32_16x16x32_bf16 v[4:7], v[144:147], v[206:209], v[4:7]
	v_mfma_f32_16x16x32_bf16 v[0:3], v[168:171], v[206:209], v[0:3]
	v_mfma_f32_16x16x32_bf16 v[52:55], v[148:151], v[186:189], v[52:55]
	v_mfma_f32_16x16x32_bf16 v[48:51], v[172:175], v[186:189], v[48:51]
	v_mfma_f32_16x16x32_bf16 v[36:39], v[148:151], v[194:197], v[36:39]
	v_mfma_f32_16x16x32_bf16 v[32:35], v[172:175], v[194:197], v[32:35]
	v_mfma_f32_16x16x32_bf16 v[20:23], v[148:151], v[202:205], v[20:23]
	v_mfma_f32_16x16x32_bf16 v[16:19], v[172:175], v[202:205], v[16:19]
	v_mfma_f32_16x16x32_bf16 v[4:7], v[148:151], v[210:213], v[4:7]
	v_mfma_f32_16x16x32_bf16 v[0:3], v[172:175], v[210:213], v[0:3]
	s_setprio 0
	s_barrier
	s_cbranch_scc0 .LBB0_3030
	s_and_b64 vcc, exec, s[22:23]
	s_cbranch_vccz .LBB0_3033
	s_barrier
